# GEMM K-loops: removed the back-to-back s_setprio 0 / s_setprio 1 pair in the middle of every 32-MFMA phase (two issue slots per phase)
# speedup vs baseline: 1.0063x; 1.0063x over previous
.Lpws__106_0:
	s_waitcnt lgkmcnt(0)
	s_barrier
	s_setprio 1
	s_waitcnt lgkmcnt(0)
	v_mfma_f32_16x16x32_bf16 v[126:129], v[130:133], v[186:189], 0
	v_mfma_f32_16x16x32_bf16 v[62:65], v[150:153], v[186:189], 0
	v_mfma_f32_16x16x32_bf16 v[110:113], v[130:133], v[194:197], 0
	v_mfma_f32_16x16x32_bf16 v[46:49], v[150:153], v[194:197], 0
	v_mfma_f32_16x16x32_bf16 v[106:109], v[130:133], v[202:205], 0
	v_mfma_f32_16x16x32_bf16 v[42:45], v[150:153], v[202:205], 0
	v_mfma_f32_16x16x32_bf16 v[118:121], v[130:133], v[230:233], 0
	v_mfma_f32_16x16x32_bf16 v[54:57], v[150:153], v[230:233], 0
	v_mfma_f32_16x16x32_bf16 v[126:129], v[134:137], v[190:193], v[126:129]
	v_mfma_f32_16x16x32_bf16 v[62:65], v[154:157], v[190:193], v[62:65]
	v_mfma_f32_16x16x32_bf16 v[110:113], v[134:137], v[198:201], v[110:113]
	v_mfma_f32_16x16x32_bf16 v[46:49], v[154:157], v[198:201], v[46:49]
	v_mfma_f32_16x16x32_bf16 v[106:109], v[134:137], v[226:229], v[106:109]
	v_mfma_f32_16x16x32_bf16 v[42:45], v[154:157], v[226:229], v[42:45]
	v_mfma_f32_16x16x32_bf16 v[118:121], v[134:137], v[234:237], v[118:121]
	v_mfma_f32_16x16x32_bf16 v[54:57], v[154:157], v[234:237], v[54:57]
	v_mfma_f32_16x16x32_bf16 v[122:125], v[170:173], v[186:189], 0
	v_mfma_f32_16x16x32_bf16 v[58:61], v[178:181], v[186:189], 0
	v_mfma_f32_16x16x32_bf16 v[102:105], v[170:173], v[194:197], 0
	v_mfma_f32_16x16x32_bf16 v[38:41], v[178:181], v[194:197], 0
	v_mfma_f32_16x16x32_bf16 v[98:101], v[170:173], v[202:205], 0
	v_mfma_f32_16x16x32_bf16 v[34:37], v[178:181], v[202:205], 0
	v_mfma_f32_16x16x32_bf16 v[114:117], v[170:173], v[230:233], 0
	v_mfma_f32_16x16x32_bf16 v[50:53], v[178:181], v[230:233], 0
	v_mfma_f32_16x16x32_bf16 v[122:125], v[174:177], v[190:193], v[122:125]
	v_mfma_f32_16x16x32_bf16 v[58:61], v[182:185], v[190:193], v[58:61]
	v_mfma_f32_16x16x32_bf16 v[102:105], v[174:177], v[198:201], v[102:105]
	v_mfma_f32_16x16x32_bf16 v[38:41], v[182:185], v[198:201], v[38:41]
	v_mfma_f32_16x16x32_bf16 v[98:101], v[174:177], v[226:229], v[98:101]
	v_mfma_f32_16x16x32_bf16 v[34:37], v[182:185], v[226:229], v[34:37]
	v_mfma_f32_16x16x32_bf16 v[114:117], v[174:177], v[234:237], v[114:117]
	v_mfma_f32_16x16x32_bf16 v[50:53], v[182:185], v[234:237], v[50:53]
	s_setprio 0
	s_barrier
	s_add_i32 s46, s46, s12
	v_lshl_add_u64 v[158:159], s[0:1], 0, v[140:141]
	s_mov_b32 m0, s46
	ds_read_b128 v[186:189], v225 offset:16384
	ds_read_b128 v[190:193], v225 offset:17408
	ds_read_b128 v[194:197], v225 offset:18432
	ds_read_b128 v[198:201], v225 offset:19456
	ds_read_b128 v[202:205], v225 offset:20480
	ds_read_b128 v[226:229], v225 offset:21504
	ds_read_b128 v[230:233], v225 offset:22528
	ds_read_b128 v[234:237], v225 offset:23552
	global_load_lds_dwordx4 v[158:159], off
	s_add_i32 m0, s46, 0x2000
	s_add_u32 s46, s0, 0x40000
	v_lshl_add_u64 v[206:207], s[0:1], 0, v[144:145]
	s_addc_u32 s47, s1, 0
	s_add_i32 s50, s50, s12
	global_load_lds_dwordx4 v[206:207], off
	v_lshl_add_u64 v[238:239], s[46:47], 0, v[140:141]
	s_mov_b32 m0, s50
	v_lshl_add_u64 v[240:241], s[4:5], 0, v[142:143]
	global_load_lds_dwordx4 v[238:239], off
	v_lshl_add_u64 v[238:239], s[46:47], 0, v[144:145]
	s_add_i32 m0, s50, 0x2000
	s_nop 0
	global_load_lds_dwordx4 v[238:239], off
	v_lshl_add_u64 v[238:239], s[4:5], 0, v[138:139]
	s_mov_b32 m0, s13
	s_nop 0
	global_load_lds_dwordx4 v[238:239], off
	s_mov_b32 m0, s14
	s_nop 0
	global_load_lds_dwordx4 v[240:241], off
	s_cmp_lg_u32 s35, -2
	s_cbranch_scc1 .Lpwt__106_1
	s_cmp_lt_u32 s26, 2
	s_cbranch_scc0 .Lpws__106_1

.Lpws__106_1:
	s_waitcnt lgkmcnt(0)
	s_barrier
	s_setprio 1
	s_waitcnt lgkmcnt(0)
	v_mfma_f32_16x16x32_bf16 v[94:97], v[130:133], v[186:189], 0
	v_mfma_f32_16x16x32_bf16 v[30:33], v[150:153], v[186:189], 0
	v_mfma_f32_16x16x32_bf16 v[78:81], v[130:133], v[194:197], 0
	v_mfma_f32_16x16x32_bf16 v[18:21], v[150:153], v[194:197], 0
	v_mfma_f32_16x16x32_bf16 v[74:77], v[130:133], v[202:205], 0
	v_mfma_f32_16x16x32_bf16 v[10:13], v[150:153], v[202:205], 0
	v_mfma_f32_16x16x32_bf16 v[86:89], v[130:133], v[230:233], 0
	v_mfma_f32_16x16x32_bf16 v[22:25], v[150:153], v[230:233], 0
	v_mfma_f32_16x16x32_bf16 v[94:97], v[134:137], v[190:193], v[94:97]
	v_mfma_f32_16x16x32_bf16 v[30:33], v[154:157], v[190:193], v[30:33]
	v_mfma_f32_16x16x32_bf16 v[78:81], v[134:137], v[198:201], v[78:81]
	v_mfma_f32_16x16x32_bf16 v[18:21], v[154:157], v[198:201], v[18:21]
	v_mfma_f32_16x16x32_bf16 v[74:77], v[134:137], v[226:229], v[74:77]
	v_mfma_f32_16x16x32_bf16 v[10:13], v[154:157], v[226:229], v[10:13]
	v_mfma_f32_16x16x32_bf16 v[86:89], v[134:137], v[234:237], v[86:89]
	v_mfma_f32_16x16x32_bf16 v[22:25], v[154:157], v[234:237], v[22:25]
	v_mfma_f32_16x16x32_bf16 v[90:93], v[170:173], v[186:189], 0
	v_mfma_f32_16x16x32_bf16 v[26:29], v[178:181], v[186:189], 0
	v_mfma_f32_16x16x32_bf16 v[70:73], v[170:173], v[194:197], 0
	v_mfma_f32_16x16x32_bf16 v[6:9], v[178:181], v[194:197], 0
	v_mfma_f32_16x16x32_bf16 v[66:69], v[170:173], v[202:205], 0
	v_mfma_f32_16x16x32_bf16 v[2:5], v[178:181], v[202:205], 0
	v_mfma_f32_16x16x32_bf16 v[82:85], v[170:173], v[230:233], 0
	v_mfma_f32_16x16x32_bf16 v[14:17], v[178:181], v[230:233], 0
	v_mfma_f32_16x16x32_bf16 v[90:93], v[174:177], v[190:193], v[90:93]
	v_mfma_f32_16x16x32_bf16 v[26:29], v[182:185], v[190:193], v[26:29]
	v_mfma_f32_16x16x32_bf16 v[70:73], v[174:177], v[198:201], v[70:73]
	v_mfma_f32_16x16x32_bf16 v[6:9], v[182:185], v[198:201], v[6:9]
	v_mfma_f32_16x16x32_bf16 v[66:69], v[174:177], v[226:229], v[66:69]
	v_mfma_f32_16x16x32_bf16 v[2:5], v[182:185], v[226:229], v[2:5]
	v_mfma_f32_16x16x32_bf16 v[82:85], v[174:177], v[234:237], v[82:85]
	v_mfma_f32_16x16x32_bf16 v[14:17], v[182:185], v[234:237], v[14:17]
	s_setprio 0
	s_barrier
	s_add_i32 s46, 0, 0x18000
	v_add_u32_e32 v0, s46, v223
	s_add_i32 s47, 0, 0x1c000
	ds_read_b128 v[130:133], v0
	ds_read_b128 v[134:137], v0 offset:1024
	ds_read_b128 v[150:153], v0 offset:2048
	ds_read_b128 v[154:157], v0 offset:3072
	v_add_u32_e32 v0, s47, v223
	ds_read_b128 v[170:173], v0
	ds_read_b128 v[174:177], v0 offset:1024
	ds_read_b128 v[178:181], v0 offset:2048
	ds_read_b128 v[182:185], v0 offset:3072
	s_add_u32 s4, s4, 0x40000
	s_addc_u32 s5, s5, 0
	s_mov_b32 m0, s15
	v_lshl_add_u64 v[242:243], s[4:5], 0, v[138:139]
	ds_read_b128 v[186:189], v225 offset:32768
	ds_read_b128 v[190:193], v225 offset:33792
	ds_read_b128 v[194:197], v225 offset:34816
	ds_read_b128 v[198:201], v225 offset:35840
	ds_read_b128 v[202:205], v225 offset:36864
	ds_read_b128 v[226:229], v225 offset:37888
	ds_read_b128 v[230:233], v225 offset:38912
	ds_read_b128 v[234:237], v225 offset:39936
	global_load_lds_dwordx4 v[242:243], off
	v_lshl_add_u64 v[242:243], s[4:5], 0, v[142:143]
	s_mov_b32 m0, s16
	s_nop 0
	global_load_lds_dwordx4 v[242:243], off
	s_waitcnt vmcnt(8)
	s_waitcnt lgkmcnt(0)
	s_barrier
	s_setprio 1
	s_waitcnt lgkmcnt(0)
	v_mfma_f32_16x16x32_bf16 v[126:129], v[130:133], v[186:189], v[126:129]
	v_mfma_f32_16x16x32_bf16 v[62:65], v[150:153], v[186:189], v[62:65]
	v_mfma_f32_16x16x32_bf16 v[110:113], v[130:133], v[194:197], v[110:113]
	v_mfma_f32_16x16x32_bf16 v[46:49], v[150:153], v[194:197], v[46:49]
	v_mfma_f32_16x16x32_bf16 v[106:109], v[130:133], v[202:205], v[106:109]
	v_mfma_f32_16x16x32_bf16 v[42:45], v[150:153], v[202:205], v[42:45]
	v_mfma_f32_16x16x32_bf16 v[118:121], v[130:133], v[230:233], v[118:121]
	v_mfma_f32_16x16x32_bf16 v[54:57], v[150:153], v[230:233], v[54:57]
	v_mfma_f32_16x16x32_bf16 v[126:129], v[134:137], v[190:193], v[126:129]
	v_mfma_f32_16x16x32_bf16 v[62:65], v[154:157], v[190:193], v[62:65]
	v_mfma_f32_16x16x32_bf16 v[110:113], v[134:137], v[198:201], v[110:113]
	v_mfma_f32_16x16x32_bf16 v[46:49], v[154:157], v[198:201], v[46:49]
	v_mfma_f32_16x16x32_bf16 v[106:109], v[134:137], v[226:229], v[106:109]
	v_mfma_f32_16x16x32_bf16 v[42:45], v[154:157], v[226:229], v[42:45]
	v_mfma_f32_16x16x32_bf16 v[118:121], v[134:137], v[234:237], v[118:121]
	v_mfma_f32_16x16x32_bf16 v[54:57], v[154:157], v[234:237], v[54:57]
	v_mfma_f32_16x16x32_bf16 v[122:125], v[170:173], v[186:189], v[122:125]
	v_mfma_f32_16x16x32_bf16 v[58:61], v[178:181], v[186:189], v[58:61]
	v_mfma_f32_16x16x32_bf16 v[102:105], v[170:173], v[194:197], v[102:105]
	v_mfma_f32_16x16x32_bf16 v[38:41], v[178:181], v[194:197], v[38:41]
	v_mfma_f32_16x16x32_bf16 v[98:101], v[170:173], v[202:205], v[98:101]
	v_mfma_f32_16x16x32_bf16 v[34:37], v[178:181], v[202:205], v[34:37]
	v_mfma_f32_16x16x32_bf16 v[114:117], v[170:173], v[230:233], v[114:117]
	v_mfma_f32_16x16x32_bf16 v[50:53], v[178:181], v[230:233], v[50:53]
	v_mfma_f32_16x16x32_bf16 v[122:125], v[174:177], v[190:193], v[122:125]
	v_mfma_f32_16x16x32_bf16 v[58:61], v[182:185], v[190:193], v[58:61]
	v_mfma_f32_16x16x32_bf16 v[102:105], v[174:177], v[198:201], v[102:105]
	v_mfma_f32_16x16x32_bf16 v[38:41], v[182:185], v[198:201], v[38:41]
	v_mfma_f32_16x16x32_bf16 v[98:101], v[174:177], v[226:229], v[98:101]
	v_mfma_f32_16x16x32_bf16 v[34:37], v[182:185], v[226:229], v[34:37]
	v_mfma_f32_16x16x32_bf16 v[114:117], v[174:177], v[234:237], v[114:117]
	v_mfma_f32_16x16x32_bf16 v[50:53], v[182:185], v[234:237], v[50:53]
	s_setprio 0
	s_barrier
	s_add_i32 s4, s46, s12
	v_lshl_add_u64 v[158:159], v[158:159], 0, s[80:81]
	s_mov_b32 m0, s4
	ds_read_b128 v[186:189], v225 offset:49152
	ds_read_b128 v[190:193], v225 offset:50176
	ds_read_b128 v[194:197], v225 offset:51200
	ds_read_b128 v[198:201], v225 offset:52224
	ds_read_b128 v[202:205], v225 offset:53248
	ds_read_b128 v[226:229], v225 offset:54272
	ds_read_b128 v[230:233], v225 offset:55296
	ds_read_b128 v[234:237], v225 offset:56320
	global_load_lds_dwordx4 v[158:159], off
	s_add_i32 m0, s4, 0x2000
	s_add_u32 s0, s0, 0x40080
	v_lshl_add_u64 v[158:159], v[206:207], 0, s[80:81]
	s_addc_u32 s1, s1, 0
	s_add_i32 s4, s47, s12
	global_load_lds_dwordx4 v[158:159], off
	v_lshl_add_u64 v[158:159], s[0:1], 0, v[140:141]
	s_mov_b32 m0, s4
	s_nop 0
	global_load_lds_dwordx4 v[158:159], off
	v_lshl_add_u64 v[158:159], s[0:1], 0, v[144:145]
	s_add_i32 m0, s4, 0x2000
	s_nop 0
	global_load_lds_dwordx4 v[158:159], off
	v_lshl_add_u64 v[158:159], v[238:239], 0, s[80:81]
	s_mov_b32 m0, s22
	s_nop 0
	global_load_lds_dwordx4 v[158:159], off
	v_lshl_add_u64 v[158:159], v[240:241], 0, s[80:81]
	s_mov_b32 m0, s23
	s_nop 0
	global_load_lds_dwordx4 v[158:159], off
	s_waitcnt vmcnt(8)
	s_waitcnt lgkmcnt(0)
	s_barrier
	s_setprio 1
	s_waitcnt lgkmcnt(0)
	v_mfma_f32_16x16x32_bf16 v[94:97], v[130:133], v[186:189], v[94:97]
	v_mfma_f32_16x16x32_bf16 v[30:33], v[150:153], v[186:189], v[30:33]
	v_mfma_f32_16x16x32_bf16 v[78:81], v[130:133], v[194:197], v[78:81]
	v_mfma_f32_16x16x32_bf16 v[18:21], v[150:153], v[194:197], v[18:21]
	v_mfma_f32_16x16x32_bf16 v[74:77], v[130:133], v[202:205], v[74:77]
	v_mfma_f32_16x16x32_bf16 v[10:13], v[150:153], v[202:205], v[10:13]
	v_mfma_f32_16x16x32_bf16 v[86:89], v[130:133], v[230:233], v[86:89]
	v_mfma_f32_16x16x32_bf16 v[22:25], v[150:153], v[230:233], v[22:25]
	v_mfma_f32_16x16x32_bf16 v[94:97], v[134:137], v[190:193], v[94:97]
	v_mfma_f32_16x16x32_bf16 v[30:33], v[154:157], v[190:193], v[30:33]
	v_mfma_f32_16x16x32_bf16 v[78:81], v[134:137], v[198:201], v[78:81]
	v_mfma_f32_16x16x32_bf16 v[18:21], v[154:157], v[198:201], v[18:21]
	v_mfma_f32_16x16x32_bf16 v[74:77], v[134:137], v[226:229], v[74:77]
	v_mfma_f32_16x16x32_bf16 v[10:13], v[154:157], v[226:229], v[10:13]
	v_mfma_f32_16x16x32_bf16 v[86:89], v[134:137], v[234:237], v[86:89]
	v_mfma_f32_16x16x32_bf16 v[22:25], v[154:157], v[234:237], v[22:25]
	v_mfma_f32_16x16x32_bf16 v[90:93], v[170:173], v[186:189], v[90:93]
	v_mfma_f32_16x16x32_bf16 v[26:29], v[178:181], v[186:189], v[26:29]
	v_mfma_f32_16x16x32_bf16 v[70:73], v[170:173], v[194:197], v[70:73]
	v_mfma_f32_16x16x32_bf16 v[6:9], v[178:181], v[194:197], v[6:9]
	v_mfma_f32_16x16x32_bf16 v[66:69], v[170:173], v[202:205], v[66:69]
	v_mfma_f32_16x16x32_bf16 v[2:5], v[178:181], v[202:205], v[2:5]
	v_mfma_f32_16x16x32_bf16 v[82:85], v[170:173], v[230:233], v[82:85]
	v_mfma_f32_16x16x32_bf16 v[14:17], v[178:181], v[230:233], v[14:17]
	v_mfma_f32_16x16x32_bf16 v[90:93], v[174:177], v[190:193], v[90:93]
	v_mfma_f32_16x16x32_bf16 v[26:29], v[182:185], v[190:193], v[26:29]
	v_mfma_f32_16x16x32_bf16 v[70:73], v[174:177], v[198:201], v[70:73]
	v_mfma_f32_16x16x32_bf16 v[6:9], v[182:185], v[198:201], v[6:9]
	v_mfma_f32_16x16x32_bf16 v[66:69], v[174:177], v[226:229], v[66:69]
	v_mfma_f32_16x16x32_bf16 v[2:5], v[182:185], v[226:229], v[2:5]
	v_mfma_f32_16x16x32_bf16 v[82:85], v[174:177], v[234:237], v[82:85]
	v_mfma_f32_16x16x32_bf16 v[14:17], v[182:185], v[234:237], v[14:17]
	s_setprio 0
	s_barrier
	s_add_i32 s35, s35, 2
	s_add_u32 s42, s42, 0x100
	s_addc_u32 s43, s43, 0
	s_add_u32 s29, s29, 0x100
	s_addc_u32 s34, s34, 0
	s_cmp_gt_u32 s35, 13

.Lws__106_0:
	s_waitcnt lgkmcnt(0)
	s_barrier
	s_setprio 1
	s_waitcnt lgkmcnt(0)
	v_mfma_f32_16x16x32_bf16 v[126:129], v[130:133], v[186:189], v[126:129]
	v_mfma_f32_16x16x32_bf16 v[62:65], v[150:153], v[186:189], v[62:65]
	v_mfma_f32_16x16x32_bf16 v[110:113], v[130:133], v[194:197], v[110:113]
	v_mfma_f32_16x16x32_bf16 v[46:49], v[150:153], v[194:197], v[46:49]
	v_mfma_f32_16x16x32_bf16 v[106:109], v[130:133], v[202:205], v[106:109]
	v_mfma_f32_16x16x32_bf16 v[42:45], v[150:153], v[202:205], v[42:45]
	v_mfma_f32_16x16x32_bf16 v[118:121], v[130:133], v[230:233], v[118:121]
	v_mfma_f32_16x16x32_bf16 v[54:57], v[150:153], v[230:233], v[54:57]
	v_mfma_f32_16x16x32_bf16 v[126:129], v[134:137], v[190:193], v[126:129]
	v_mfma_f32_16x16x32_bf16 v[62:65], v[154:157], v[190:193], v[62:65]
	v_mfma_f32_16x16x32_bf16 v[110:113], v[134:137], v[198:201], v[110:113]
	v_mfma_f32_16x16x32_bf16 v[46:49], v[154:157], v[198:201], v[46:49]
	v_mfma_f32_16x16x32_bf16 v[106:109], v[134:137], v[226:229], v[106:109]
	v_mfma_f32_16x16x32_bf16 v[42:45], v[154:157], v[226:229], v[42:45]
	v_mfma_f32_16x16x32_bf16 v[118:121], v[134:137], v[234:237], v[118:121]
	v_mfma_f32_16x16x32_bf16 v[54:57], v[154:157], v[234:237], v[54:57]
	v_mfma_f32_16x16x32_bf16 v[122:125], v[170:173], v[186:189], v[122:125]
	v_mfma_f32_16x16x32_bf16 v[58:61], v[178:181], v[186:189], v[58:61]
	v_mfma_f32_16x16x32_bf16 v[102:105], v[170:173], v[194:197], v[102:105]
	v_mfma_f32_16x16x32_bf16 v[38:41], v[178:181], v[194:197], v[38:41]
	v_mfma_f32_16x16x32_bf16 v[98:101], v[170:173], v[202:205], v[98:101]
	v_mfma_f32_16x16x32_bf16 v[34:37], v[178:181], v[202:205], v[34:37]
	v_mfma_f32_16x16x32_bf16 v[114:117], v[170:173], v[230:233], v[114:117]
	v_mfma_f32_16x16x32_bf16 v[50:53], v[178:181], v[230:233], v[50:53]
	v_mfma_f32_16x16x32_bf16 v[122:125], v[174:177], v[190:193], v[122:125]
	v_mfma_f32_16x16x32_bf16 v[58:61], v[182:185], v[190:193], v[58:61]
	v_mfma_f32_16x16x32_bf16 v[102:105], v[174:177], v[198:201], v[102:105]
	v_mfma_f32_16x16x32_bf16 v[38:41], v[182:185], v[198:201], v[38:41]
	v_mfma_f32_16x16x32_bf16 v[98:101], v[174:177], v[226:229], v[98:101]
	v_mfma_f32_16x16x32_bf16 v[34:37], v[182:185], v[226:229], v[34:37]
	v_mfma_f32_16x16x32_bf16 v[114:117], v[174:177], v[234:237], v[114:117]
	v_mfma_f32_16x16x32_bf16 v[50:53], v[182:185], v[234:237], v[50:53]
	s_setprio 0
	s_barrier
	s_add_i32 s46, s46, s12
	v_lshl_add_u64 v[158:159], s[0:1], 0, v[140:141]
	s_mov_b32 m0, s46
	ds_read_b128 v[186:189], v225 offset:16384
	ds_read_b128 v[190:193], v225 offset:17408
	ds_read_b128 v[194:197], v225 offset:18432
	ds_read_b128 v[198:201], v225 offset:19456
	ds_read_b128 v[202:205], v225 offset:20480
	ds_read_b128 v[226:229], v225 offset:21504
	ds_read_b128 v[230:233], v225 offset:22528
	ds_read_b128 v[234:237], v225 offset:23552
	global_load_lds_dwordx4 v[158:159], off
	s_add_i32 m0, s46, 0x2000
	s_add_u32 s46, s0, 0x40000
	v_lshl_add_u64 v[206:207], s[0:1], 0, v[144:145]
	s_addc_u32 s47, s1, 0
	s_add_i32 s50, s50, s12
	global_load_lds_dwordx4 v[206:207], off
	v_lshl_add_u64 v[238:239], s[46:47], 0, v[140:141]
	s_mov_b32 m0, s50
	v_lshl_add_u64 v[240:241], s[4:5], 0, v[142:143]
	global_load_lds_dwordx4 v[238:239], off
	v_lshl_add_u64 v[238:239], s[46:47], 0, v[144:145]
	s_add_i32 m0, s50, 0x2000
	s_nop 0
	global_load_lds_dwordx4 v[238:239], off
	v_lshl_add_u64 v[238:239], s[4:5], 0, v[138:139]
	s_mov_b32 m0, s13
	s_nop 0
	global_load_lds_dwordx4 v[238:239], off
	s_mov_b32 m0, s14
	s_nop 0
	global_load_lds_dwordx4 v[240:241], off
	s_cmp_lg_u32 s35, -2
	s_cbranch_scc1 .Lwt__106_1
	s_cmp_lt_u32 s26, 2
	s_cbranch_scc0 .Lws__106_1

.Lws__106_1:
	s_waitcnt lgkmcnt(0)
	s_barrier
	s_setprio 1
	s_waitcnt lgkmcnt(0)
	v_mfma_f32_16x16x32_bf16 v[94:97], v[130:133], v[186:189], v[94:97]
	v_mfma_f32_16x16x32_bf16 v[30:33], v[150:153], v[186:189], v[30:33]
	v_mfma_f32_16x16x32_bf16 v[78:81], v[130:133], v[194:197], v[78:81]
	v_mfma_f32_16x16x32_bf16 v[18:21], v[150:153], v[194:197], v[18:21]
	v_mfma_f32_16x16x32_bf16 v[74:77], v[130:133], v[202:205], v[74:77]
	v_mfma_f32_16x16x32_bf16 v[10:13], v[150:153], v[202:205], v[10:13]
	v_mfma_f32_16x16x32_bf16 v[86:89], v[130:133], v[230:233], v[86:89]
	v_mfma_f32_16x16x32_bf16 v[22:25], v[150:153], v[230:233], v[22:25]
	v_mfma_f32_16x16x32_bf16 v[94:97], v[134:137], v[190:193], v[94:97]
	v_mfma_f32_16x16x32_bf16 v[30:33], v[154:157], v[190:193], v[30:33]
	v_mfma_f32_16x16x32_bf16 v[78:81], v[134:137], v[198:201], v[78:81]
	v_mfma_f32_16x16x32_bf16 v[18:21], v[154:157], v[198:201], v[18:21]
	v_mfma_f32_16x16x32_bf16 v[74:77], v[134:137], v[226:229], v[74:77]
	v_mfma_f32_16x16x32_bf16 v[10:13], v[154:157], v[226:229], v[10:13]
	v_mfma_f32_16x16x32_bf16 v[86:89], v[134:137], v[234:237], v[86:89]
	v_mfma_f32_16x16x32_bf16 v[22:25], v[154:157], v[234:237], v[22:25]
	v_mfma_f32_16x16x32_bf16 v[90:93], v[170:173], v[186:189], v[90:93]
	v_mfma_f32_16x16x32_bf16 v[26:29], v[178:181], v[186:189], v[26:29]
	v_mfma_f32_16x16x32_bf16 v[70:73], v[170:173], v[194:197], v[70:73]
	v_mfma_f32_16x16x32_bf16 v[6:9], v[178:181], v[194:197], v[6:9]
	v_mfma_f32_16x16x32_bf16 v[66:69], v[170:173], v[202:205], v[66:69]
	v_mfma_f32_16x16x32_bf16 v[2:5], v[178:181], v[202:205], v[2:5]
	v_mfma_f32_16x16x32_bf16 v[82:85], v[170:173], v[230:233], v[82:85]
	v_mfma_f32_16x16x32_bf16 v[14:17], v[178:181], v[230:233], v[14:17]
	v_mfma_f32_16x16x32_bf16 v[90:93], v[174:177], v[190:193], v[90:93]
	v_mfma_f32_16x16x32_bf16 v[26:29], v[182:185], v[190:193], v[26:29]
	v_mfma_f32_16x16x32_bf16 v[70:73], v[174:177], v[198:201], v[70:73]
	v_mfma_f32_16x16x32_bf16 v[6:9], v[182:185], v[198:201], v[6:9]
	v_mfma_f32_16x16x32_bf16 v[66:69], v[174:177], v[226:229], v[66:69]
	v_mfma_f32_16x16x32_bf16 v[2:5], v[182:185], v[226:229], v[2:5]
	v_mfma_f32_16x16x32_bf16 v[82:85], v[174:177], v[234:237], v[82:85]
	v_mfma_f32_16x16x32_bf16 v[14:17], v[182:185], v[234:237], v[14:17]
	s_setprio 0
	s_barrier
	s_add_i32 s46, 0, 0x18000
	v_add_u32_e32 v0, s46, v223
	s_add_i32 s47, 0, 0x1c000
	ds_read_b128 v[130:133], v0
	ds_read_b128 v[134:137], v0 offset:1024
	ds_read_b128 v[150:153], v0 offset:2048
	ds_read_b128 v[154:157], v0 offset:3072
	v_add_u32_e32 v0, s47, v223
	ds_read_b128 v[170:173], v0
	ds_read_b128 v[174:177], v0 offset:1024
	ds_read_b128 v[178:181], v0 offset:2048
	ds_read_b128 v[182:185], v0 offset:3072
	s_add_u32 s4, s4, 0x40000
	s_addc_u32 s5, s5, 0
	s_mov_b32 m0, s15
	v_lshl_add_u64 v[242:243], s[4:5], 0, v[138:139]
	ds_read_b128 v[186:189], v225 offset:32768
	ds_read_b128 v[190:193], v225 offset:33792
	ds_read_b128 v[194:197], v225 offset:34816
	ds_read_b128 v[198:201], v225 offset:35840
	ds_read_b128 v[202:205], v225 offset:36864
	ds_read_b128 v[226:229], v225 offset:37888
	ds_read_b128 v[230:233], v225 offset:38912
	ds_read_b128 v[234:237], v225 offset:39936
	global_load_lds_dwordx4 v[242:243], off
	v_lshl_add_u64 v[242:243], s[4:5], 0, v[142:143]
	s_mov_b32 m0, s16
	s_nop 0
	global_load_lds_dwordx4 v[242:243], off
	s_waitcnt vmcnt(8)
	s_waitcnt lgkmcnt(0)
	s_barrier
	s_setprio 1
	s_waitcnt lgkmcnt(0)
	v_mfma_f32_16x16x32_bf16 v[126:129], v[130:133], v[186:189], v[126:129]
	v_mfma_f32_16x16x32_bf16 v[62:65], v[150:153], v[186:189], v[62:65]
	v_mfma_f32_16x16x32_bf16 v[110:113], v[130:133], v[194:197], v[110:113]
	v_mfma_f32_16x16x32_bf16 v[46:49], v[150:153], v[194:197], v[46:49]
	v_mfma_f32_16x16x32_bf16 v[106:109], v[130:133], v[202:205], v[106:109]
	v_mfma_f32_16x16x32_bf16 v[42:45], v[150:153], v[202:205], v[42:45]
	v_mfma_f32_16x16x32_bf16 v[118:121], v[130:133], v[230:233], v[118:121]
	v_mfma_f32_16x16x32_bf16 v[54:57], v[150:153], v[230:233], v[54:57]
	v_mfma_f32_16x16x32_bf16 v[126:129], v[134:137], v[190:193], v[126:129]
	v_mfma_f32_16x16x32_bf16 v[62:65], v[154:157], v[190:193], v[62:65]
	v_mfma_f32_16x16x32_bf16 v[110:113], v[134:137], v[198:201], v[110:113]
	v_mfma_f32_16x16x32_bf16 v[46:49], v[154:157], v[198:201], v[46:49]
	v_mfma_f32_16x16x32_bf16 v[106:109], v[134:137], v[226:229], v[106:109]
	v_mfma_f32_16x16x32_bf16 v[42:45], v[154:157], v[226:229], v[42:45]
	v_mfma_f32_16x16x32_bf16 v[118:121], v[134:137], v[234:237], v[118:121]
	v_mfma_f32_16x16x32_bf16 v[54:57], v[154:157], v[234:237], v[54:57]
	v_mfma_f32_16x16x32_bf16 v[122:125], v[170:173], v[186:189], v[122:125]
	v_mfma_f32_16x16x32_bf16 v[58:61], v[178:181], v[186:189], v[58:61]
	v_mfma_f32_16x16x32_bf16 v[102:105], v[170:173], v[194:197], v[102:105]
	v_mfma_f32_16x16x32_bf16 v[38:41], v[178:181], v[194:197], v[38:41]
	v_mfma_f32_16x16x32_bf16 v[98:101], v[170:173], v[202:205], v[98:101]
	v_mfma_f32_16x16x32_bf16 v[34:37], v[178:181], v[202:205], v[34:37]
	v_mfma_f32_16x16x32_bf16 v[114:117], v[170:173], v[230:233], v[114:117]
	v_mfma_f32_16x16x32_bf16 v[50:53], v[178:181], v[230:233], v[50:53]
	v_mfma_f32_16x16x32_bf16 v[122:125], v[174:177], v[190:193], v[122:125]
	v_mfma_f32_16x16x32_bf16 v[58:61], v[182:185], v[190:193], v[58:61]
	v_mfma_f32_16x16x32_bf16 v[102:105], v[174:177], v[198:201], v[102:105]
	v_mfma_f32_16x16x32_bf16 v[38:41], v[182:185], v[198:201], v[38:41]
	v_mfma_f32_16x16x32_bf16 v[98:101], v[174:177], v[226:229], v[98:101]
	v_mfma_f32_16x16x32_bf16 v[34:37], v[182:185], v[226:229], v[34:37]
	v_mfma_f32_16x16x32_bf16 v[114:117], v[174:177], v[234:237], v[114:117]
	v_mfma_f32_16x16x32_bf16 v[50:53], v[182:185], v[234:237], v[50:53]
	s_setprio 0
	s_barrier
	s_add_i32 s4, s46, s12
	v_lshl_add_u64 v[158:159], v[158:159], 0, s[80:81]
	s_mov_b32 m0, s4
	ds_read_b128 v[186:189], v225 offset:49152
	ds_read_b128 v[190:193], v225 offset:50176
	ds_read_b128 v[194:197], v225 offset:51200
	ds_read_b128 v[198:201], v225 offset:52224
	ds_read_b128 v[202:205], v225 offset:53248
	ds_read_b128 v[226:229], v225 offset:54272
	ds_read_b128 v[230:233], v225 offset:55296
	ds_read_b128 v[234:237], v225 offset:56320
	global_load_lds_dwordx4 v[158:159], off
	s_add_i32 m0, s4, 0x2000
	s_add_u32 s0, s0, 0x40080
	v_lshl_add_u64 v[158:159], v[206:207], 0, s[80:81]
	s_addc_u32 s1, s1, 0
	s_add_i32 s4, s47, s12
	global_load_lds_dwordx4 v[158:159], off
	v_lshl_add_u64 v[158:159], s[0:1], 0, v[140:141]
	s_mov_b32 m0, s4
	s_nop 0
	global_load_lds_dwordx4 v[158:159], off
	v_lshl_add_u64 v[158:159], s[0:1], 0, v[144:145]
	s_add_i32 m0, s4, 0x2000
	s_nop 0
	global_load_lds_dwordx4 v[158:159], off
	v_lshl_add_u64 v[158:159], v[238:239], 0, s[80:81]
	s_mov_b32 m0, s22
	s_nop 0
	global_load_lds_dwordx4 v[158:159], off
	v_lshl_add_u64 v[158:159], v[240:241], 0, s[80:81]
	s_mov_b32 m0, s23
	s_nop 0
	global_load_lds_dwordx4 v[158:159], off
	s_waitcnt vmcnt(8)
	s_waitcnt lgkmcnt(0)
	s_barrier
	s_setprio 1
	s_waitcnt lgkmcnt(0)
	v_mfma_f32_16x16x32_bf16 v[94:97], v[130:133], v[186:189], v[94:97]
	v_mfma_f32_16x16x32_bf16 v[30:33], v[150:153], v[186:189], v[30:33]
	v_mfma_f32_16x16x32_bf16 v[78:81], v[130:133], v[194:197], v[78:81]
	v_mfma_f32_16x16x32_bf16 v[18:21], v[150:153], v[194:197], v[18:21]
	v_mfma_f32_16x16x32_bf16 v[74:77], v[130:133], v[202:205], v[74:77]
	v_mfma_f32_16x16x32_bf16 v[10:13], v[150:153], v[202:205], v[10:13]
	v_mfma_f32_16x16x32_bf16 v[86:89], v[130:133], v[230:233], v[86:89]
	v_mfma_f32_16x16x32_bf16 v[22:25], v[150:153], v[230:233], v[22:25]
	v_mfma_f32_16x16x32_bf16 v[94:97], v[134:137], v[190:193], v[94:97]
	v_mfma_f32_16x16x32_bf16 v[30:33], v[154:157], v[190:193], v[30:33]
	v_mfma_f32_16x16x32_bf16 v[78:81], v[134:137], v[198:201], v[78:81]
	v_mfma_f32_16x16x32_bf16 v[18:21], v[154:157], v[198:201], v[18:21]
	v_mfma_f32_16x16x32_bf16 v[74:77], v[134:137], v[226:229], v[74:77]
	v_mfma_f32_16x16x32_bf16 v[10:13], v[154:157], v[226:229], v[10:13]
	v_mfma_f32_16x16x32_bf16 v[86:89], v[134:137], v[234:237], v[86:89]
	v_mfma_f32_16x16x32_bf16 v[22:25], v[154:157], v[234:237], v[22:25]
	v_mfma_f32_16x16x32_bf16 v[90:93], v[170:173], v[186:189], v[90:93]
	v_mfma_f32_16x16x32_bf16 v[26:29], v[178:181], v[186:189], v[26:29]
	v_mfma_f32_16x16x32_bf16 v[70:73], v[170:173], v[194:197], v[70:73]
	v_mfma_f32_16x16x32_bf16 v[6:9], v[178:181], v[194:197], v[6:9]
	v_mfma_f32_16x16x32_bf16 v[66:69], v[170:173], v[202:205], v[66:69]
	v_mfma_f32_16x16x32_bf16 v[2:5], v[178:181], v[202:205], v[2:5]
	v_mfma_f32_16x16x32_bf16 v[82:85], v[170:173], v[230:233], v[82:85]
	v_mfma_f32_16x16x32_bf16 v[14:17], v[178:181], v[230:233], v[14:17]
	v_mfma_f32_16x16x32_bf16 v[90:93], v[174:177], v[190:193], v[90:93]
	v_mfma_f32_16x16x32_bf16 v[26:29], v[182:185], v[190:193], v[26:29]
	v_mfma_f32_16x16x32_bf16 v[70:73], v[174:177], v[198:201], v[70:73]
	v_mfma_f32_16x16x32_bf16 v[6:9], v[182:185], v[198:201], v[6:9]
	v_mfma_f32_16x16x32_bf16 v[66:69], v[174:177], v[226:229], v[66:69]
	v_mfma_f32_16x16x32_bf16 v[2:5], v[182:185], v[226:229], v[2:5]
	v_mfma_f32_16x16x32_bf16 v[82:85], v[174:177], v[234:237], v[82:85]
	v_mfma_f32_16x16x32_bf16 v[14:17], v[182:185], v[234:237], v[14:17]
	s_setprio 0
	s_barrier
	s_add_i32 s35, s35, 2
	s_add_u32 s42, s42, 0x100
	s_addc_u32 s43, s43, 0
	s_add_u32 s29, s29, 0x100
	s_addc_u32 s34, s34, 0
	s_cmp_gt_u32 s35, 13
	s_cbranch_scc0 .LBB0_106
	s_mov_b32 s98, 0xbfb8aa3b
	s_and_b64 vcc, exec, s[56:57]
	s_cbranch_vccz .LBB0_109
	s_barrier

.LBB0_162:
	s_add_u32 s0, s66, 0xfffc0080
	s_addc_u32 s1, s67, -1
	s_add_i32 s27, 0, 0x10000
	s_cmp_eq_u32 s26, 12
	s_cselect_b32 s3, s4, s1
	s_cselect_b32 s2, s5, s0
	s_cselect_b32 s1, s22, s25
	s_cselect_b32 s0, s23, s24
	s_add_i32 s34, 0, 0x14000
	v_add_u32_e32 v126, s27, v189
	v_add_u32_e32 v178, s34, v189
	ds_read_b128 v[114:117], v126
	ds_read_b128 v[118:121], v126 offset:1024
	ds_read_b128 v[122:125], v126 offset:2048
	ds_read_b128 v[126:129], v126 offset:3072
	ds_read_b128 v[130:133], v178
	ds_read_b128 v[134:137], v178 offset:1024
	ds_read_b128 v[174:177], v178 offset:2048
	ds_read_b128 v[178:181], v178 offset:3072
	v_lshl_add_u64 v[186:187], s[66:67], 0, v[170:171]
	s_add_i32 m0, s13, 0xc000
	ds_read_b128 v[182:185], v191
	ds_read_b128 v[192:195], v191 offset:1024
	ds_read_b128 v[196:199], v191 offset:2048
	ds_read_b128 v[200:203], v191 offset:3072
	ds_read_b128 v[204:207], v191 offset:4096
	ds_read_b128 v[224:227], v191 offset:5120
	ds_read_b128 v[228:231], v191 offset:6144
	ds_read_b128 v[232:235], v191 offset:7168
	global_load_lds_dwordx4 v[186:187], off
	v_lshl_add_u64 v[186:187], s[66:67], 0, v[172:173]
	s_add_i32 m0, s13, 0xe000
	s_nop 0
	global_load_lds_dwordx4 v[186:187], off
	s_waitcnt vmcnt(8)
	s_waitcnt lgkmcnt(0)
	s_barrier
	s_setprio 1
	s_waitcnt lgkmcnt(0)
	v_mfma_f32_16x16x32_bf16 v[150:153], v[114:117], v[182:185], v[150:153]
	v_mfma_f32_16x16x32_bf16 v[146:149], v[122:125], v[182:185], v[146:149]
	v_mfma_f32_16x16x32_bf16 v[110:113], v[114:117], v[196:199], v[110:113]
	v_mfma_f32_16x16x32_bf16 v[106:109], v[122:125], v[196:199], v[106:109]
	v_mfma_f32_16x16x32_bf16 v[94:97], v[114:117], v[204:207], v[94:97]
	v_mfma_f32_16x16x32_bf16 v[90:93], v[122:125], v[204:207], v[90:93]
	v_mfma_f32_16x16x32_bf16 v[78:81], v[114:117], v[228:231], v[78:81]
	v_mfma_f32_16x16x32_bf16 v[74:77], v[122:125], v[228:231], v[74:77]
	v_mfma_f32_16x16x32_bf16 v[150:153], v[118:121], v[192:195], v[150:153]
	v_mfma_f32_16x16x32_bf16 v[146:149], v[126:129], v[192:195], v[146:149]
	v_mfma_f32_16x16x32_bf16 v[110:113], v[118:121], v[200:203], v[110:113]
	v_mfma_f32_16x16x32_bf16 v[106:109], v[126:129], v[200:203], v[106:109]
	v_mfma_f32_16x16x32_bf16 v[94:97], v[118:121], v[224:227], v[94:97]
	v_mfma_f32_16x16x32_bf16 v[90:93], v[126:129], v[224:227], v[90:93]
	v_mfma_f32_16x16x32_bf16 v[78:81], v[118:121], v[232:235], v[78:81]
	v_mfma_f32_16x16x32_bf16 v[74:77], v[126:129], v[232:235], v[74:77]
	v_mfma_f32_16x16x32_bf16 v[142:145], v[130:133], v[182:185], v[142:145]
	v_mfma_f32_16x16x32_bf16 v[138:141], v[174:177], v[182:185], v[138:141]
	v_mfma_f32_16x16x32_bf16 v[102:105], v[130:133], v[196:199], v[102:105]
	v_mfma_f32_16x16x32_bf16 v[98:101], v[174:177], v[196:199], v[98:101]
	v_mfma_f32_16x16x32_bf16 v[86:89], v[130:133], v[204:207], v[86:89]
	v_mfma_f32_16x16x32_bf16 v[82:85], v[174:177], v[204:207], v[82:85]
	v_mfma_f32_16x16x32_bf16 v[70:73], v[130:133], v[228:231], v[70:73]
	v_mfma_f32_16x16x32_bf16 v[66:69], v[174:177], v[228:231], v[66:69]
	v_mfma_f32_16x16x32_bf16 v[142:145], v[134:137], v[192:195], v[142:145]
	v_mfma_f32_16x16x32_bf16 v[138:141], v[178:181], v[192:195], v[138:141]
	v_mfma_f32_16x16x32_bf16 v[102:105], v[134:137], v[200:203], v[102:105]
	v_mfma_f32_16x16x32_bf16 v[98:101], v[178:181], v[200:203], v[98:101]
	v_mfma_f32_16x16x32_bf16 v[86:89], v[134:137], v[224:227], v[86:89]
	v_mfma_f32_16x16x32_bf16 v[82:85], v[178:181], v[224:227], v[82:85]
	v_mfma_f32_16x16x32_bf16 v[70:73], v[134:137], v[232:235], v[70:73]
	v_mfma_f32_16x16x32_bf16 v[66:69], v[178:181], v[232:235], v[66:69]
	s_setprio 0
	s_barrier
	s_add_i32 s27, s27, s12
	v_lshl_add_u64 v[186:187], s[0:1], 0, v[0:1]
	s_mov_b32 m0, s27
	ds_read_b128 v[182:185], v191 offset:16384
	ds_read_b128 v[192:195], v191 offset:17408
	ds_read_b128 v[196:199], v191 offset:18432
	ds_read_b128 v[200:203], v191 offset:19456
	ds_read_b128 v[204:207], v191 offset:20480
	ds_read_b128 v[224:227], v191 offset:21504
	ds_read_b128 v[228:231], v191 offset:22528
	ds_read_b128 v[232:235], v191 offset:23552
	global_load_lds_dwordx4 v[186:187], off
	s_add_i32 m0, s27, 0x2000
	s_add_u32 s28, s0, 0x40000
	v_lshl_add_u64 v[236:237], s[0:1], 0, v[158:159]
	s_addc_u32 s29, s1, 0
	s_add_i32 s27, s34, s12
	global_load_lds_dwordx4 v[236:237], off
	v_lshl_add_u64 v[238:239], s[28:29], 0, v[0:1]
	s_mov_b32 m0, s27
	v_lshl_add_u64 v[240:241], s[2:3], 0, v[156:157]
	global_load_lds_dwordx4 v[238:239], off
	v_lshl_add_u64 v[238:239], s[28:29], 0, v[158:159]
	s_add_i32 m0, s27, 0x2000
	s_nop 0
	global_load_lds_dwordx4 v[238:239], off
	v_lshl_add_u64 v[238:239], s[2:3], 0, v[154:155]
	s_mov_b32 m0, s13
	s_nop 0
	global_load_lds_dwordx4 v[238:239], off
	s_mov_b32 m0, s14
	s_nop 0
	global_load_lds_dwordx4 v[240:241], off
	s_waitcnt vmcnt(8)
	s_waitcnt lgkmcnt(0)
	s_barrier
	s_setprio 1
	s_waitcnt lgkmcnt(0)
	v_mfma_f32_16x16x32_bf16 v[62:65], v[114:117], v[182:185], v[62:65]
	v_mfma_f32_16x16x32_bf16 v[58:61], v[122:125], v[182:185], v[58:61]
	v_mfma_f32_16x16x32_bf16 v[46:49], v[114:117], v[196:199], v[46:49]
	v_mfma_f32_16x16x32_bf16 v[42:45], v[122:125], v[196:199], v[42:45]
	v_mfma_f32_16x16x32_bf16 v[30:33], v[114:117], v[204:207], v[30:33]
	v_mfma_f32_16x16x32_bf16 v[26:29], v[122:125], v[204:207], v[26:29]
	v_mfma_f32_16x16x32_bf16 v[14:17], v[114:117], v[228:231], v[14:17]
	v_mfma_f32_16x16x32_bf16 v[10:13], v[122:125], v[228:231], v[10:13]
	v_mfma_f32_16x16x32_bf16 v[62:65], v[118:121], v[192:195], v[62:65]
	v_mfma_f32_16x16x32_bf16 v[58:61], v[126:129], v[192:195], v[58:61]
	v_mfma_f32_16x16x32_bf16 v[46:49], v[118:121], v[200:203], v[46:49]
	v_mfma_f32_16x16x32_bf16 v[42:45], v[126:129], v[200:203], v[42:45]
	v_mfma_f32_16x16x32_bf16 v[30:33], v[118:121], v[224:227], v[30:33]
	v_mfma_f32_16x16x32_bf16 v[26:29], v[126:129], v[224:227], v[26:29]
	v_mfma_f32_16x16x32_bf16 v[14:17], v[118:121], v[232:235], v[14:17]
	v_mfma_f32_16x16x32_bf16 v[10:13], v[126:129], v[232:235], v[10:13]
	v_mfma_f32_16x16x32_bf16 v[54:57], v[130:133], v[182:185], v[54:57]
	v_mfma_f32_16x16x32_bf16 v[50:53], v[174:177], v[182:185], v[50:53]
	v_mfma_f32_16x16x32_bf16 v[38:41], v[130:133], v[196:199], v[38:41]
	v_mfma_f32_16x16x32_bf16 v[34:37], v[174:177], v[196:199], v[34:37]
	v_mfma_f32_16x16x32_bf16 v[22:25], v[130:133], v[204:207], v[22:25]
	v_mfma_f32_16x16x32_bf16 v[18:21], v[174:177], v[204:207], v[18:21]
	v_mfma_f32_16x16x32_bf16 v[6:9], v[130:133], v[228:231], v[6:9]
	v_mfma_f32_16x16x32_bf16 v[2:5], v[174:177], v[228:231], v[2:5]
	v_mfma_f32_16x16x32_bf16 v[54:57], v[134:137], v[192:195], v[54:57]
	v_mfma_f32_16x16x32_bf16 v[50:53], v[178:181], v[192:195], v[50:53]
	v_mfma_f32_16x16x32_bf16 v[38:41], v[134:137], v[200:203], v[38:41]
	v_mfma_f32_16x16x32_bf16 v[34:37], v[178:181], v[200:203], v[34:37]
	v_mfma_f32_16x16x32_bf16 v[22:25], v[134:137], v[224:227], v[22:25]
	v_mfma_f32_16x16x32_bf16 v[18:21], v[178:181], v[224:227], v[18:21]
	v_mfma_f32_16x16x32_bf16 v[6:9], v[134:137], v[232:235], v[6:9]
	v_mfma_f32_16x16x32_bf16 v[2:5], v[178:181], v[232:235], v[2:5]
	s_setprio 0
	s_barrier
	s_add_i32 s27, 0, 0x18000
	s_add_i32 s28, 0, 0x1c000
	v_add_u32_e32 v126, s27, v189
	v_add_u32_e32 v178, s28, v189
	ds_read_b128 v[114:117], v126
	ds_read_b128 v[118:121], v126 offset:1024
	ds_read_b128 v[122:125], v126 offset:2048
	ds_read_b128 v[126:129], v126 offset:3072
	ds_read_b128 v[130:133], v178
	ds_read_b128 v[134:137], v178 offset:1024
	ds_read_b128 v[174:177], v178 offset:2048
	ds_read_b128 v[178:181], v178 offset:3072
	s_add_u32 s2, s2, 0x40000
	s_addc_u32 s3, s3, 0
	s_mov_b32 m0, s15
	v_lshl_add_u64 v[242:243], s[2:3], 0, v[154:155]
	ds_read_b128 v[182:185], v191 offset:32768
	ds_read_b128 v[192:195], v191 offset:33792
	ds_read_b128 v[196:199], v191 offset:34816
	ds_read_b128 v[200:203], v191 offset:35840
	ds_read_b128 v[204:207], v191 offset:36864
	ds_read_b128 v[224:227], v191 offset:37888
	ds_read_b128 v[228:231], v191 offset:38912
	ds_read_b128 v[232:235], v191 offset:39936
	global_load_lds_dwordx4 v[242:243], off
	v_lshl_add_u64 v[242:243], s[2:3], 0, v[156:157]
	s_mov_b32 m0, s16
	s_nop 0
	global_load_lds_dwordx4 v[242:243], off
	s_waitcnt vmcnt(8)
	s_waitcnt lgkmcnt(0)
	s_barrier
	s_setprio 1
	s_waitcnt lgkmcnt(0)
	v_mfma_f32_16x16x32_bf16 v[150:153], v[114:117], v[182:185], v[150:153]
	v_mfma_f32_16x16x32_bf16 v[146:149], v[122:125], v[182:185], v[146:149]
	v_mfma_f32_16x16x32_bf16 v[110:113], v[114:117], v[196:199], v[110:113]
	v_mfma_f32_16x16x32_bf16 v[106:109], v[122:125], v[196:199], v[106:109]
	v_mfma_f32_16x16x32_bf16 v[94:97], v[114:117], v[204:207], v[94:97]
	v_mfma_f32_16x16x32_bf16 v[90:93], v[122:125], v[204:207], v[90:93]
	v_mfma_f32_16x16x32_bf16 v[78:81], v[114:117], v[228:231], v[78:81]
	v_mfma_f32_16x16x32_bf16 v[74:77], v[122:125], v[228:231], v[74:77]
	v_mfma_f32_16x16x32_bf16 v[150:153], v[118:121], v[192:195], v[150:153]
	v_mfma_f32_16x16x32_bf16 v[146:149], v[126:129], v[192:195], v[146:149]
	v_mfma_f32_16x16x32_bf16 v[110:113], v[118:121], v[200:203], v[110:113]
	v_mfma_f32_16x16x32_bf16 v[106:109], v[126:129], v[200:203], v[106:109]
	v_mfma_f32_16x16x32_bf16 v[94:97], v[118:121], v[224:227], v[94:97]
	v_mfma_f32_16x16x32_bf16 v[90:93], v[126:129], v[224:227], v[90:93]
	v_mfma_f32_16x16x32_bf16 v[78:81], v[118:121], v[232:235], v[78:81]
	v_mfma_f32_16x16x32_bf16 v[74:77], v[126:129], v[232:235], v[74:77]
	v_mfma_f32_16x16x32_bf16 v[142:145], v[130:133], v[182:185], v[142:145]
	v_mfma_f32_16x16x32_bf16 v[138:141], v[174:177], v[182:185], v[138:141]
	v_mfma_f32_16x16x32_bf16 v[102:105], v[130:133], v[196:199], v[102:105]
	v_mfma_f32_16x16x32_bf16 v[98:101], v[174:177], v[196:199], v[98:101]
	v_mfma_f32_16x16x32_bf16 v[86:89], v[130:133], v[204:207], v[86:89]
	v_mfma_f32_16x16x32_bf16 v[82:85], v[174:177], v[204:207], v[82:85]
	v_mfma_f32_16x16x32_bf16 v[70:73], v[130:133], v[228:231], v[70:73]
	v_mfma_f32_16x16x32_bf16 v[66:69], v[174:177], v[228:231], v[66:69]
	v_mfma_f32_16x16x32_bf16 v[142:145], v[134:137], v[192:195], v[142:145]
	v_mfma_f32_16x16x32_bf16 v[138:141], v[178:181], v[192:195], v[138:141]
	v_mfma_f32_16x16x32_bf16 v[102:105], v[134:137], v[200:203], v[102:105]
	v_mfma_f32_16x16x32_bf16 v[98:101], v[178:181], v[200:203], v[98:101]
	v_mfma_f32_16x16x32_bf16 v[86:89], v[134:137], v[224:227], v[86:89]
	v_mfma_f32_16x16x32_bf16 v[82:85], v[178:181], v[224:227], v[82:85]
	v_mfma_f32_16x16x32_bf16 v[70:73], v[134:137], v[232:235], v[70:73]
	v_mfma_f32_16x16x32_bf16 v[66:69], v[178:181], v[232:235], v[66:69]
	s_setprio 0
	s_barrier
	s_add_i32 s2, s27, s12
	v_lshl_add_u64 v[186:187], v[186:187], 0, s[78:79]
	s_mov_b32 m0, s2
	ds_read_b128 v[182:185], v191 offset:49152
	ds_read_b128 v[192:195], v191 offset:50176
	ds_read_b128 v[196:199], v191 offset:51200
	ds_read_b128 v[200:203], v191 offset:52224
	ds_read_b128 v[204:207], v191 offset:53248
	ds_read_b128 v[224:227], v191 offset:54272
	ds_read_b128 v[228:231], v191 offset:55296
	ds_read_b128 v[232:235], v191 offset:56320
	global_load_lds_dwordx4 v[186:187], off
	s_add_i32 m0, s2, 0x2000
	s_add_u32 s0, s0, 0x40080
	v_lshl_add_u64 v[186:187], v[236:237], 0, s[78:79]
	s_addc_u32 s1, s1, 0
	s_add_i32 s2, s28, s12
	global_load_lds_dwordx4 v[186:187], off
	v_lshl_add_u64 v[186:187], s[0:1], 0, v[0:1]
	s_mov_b32 m0, s2
	s_nop 0
	global_load_lds_dwordx4 v[186:187], off
	v_lshl_add_u64 v[186:187], s[0:1], 0, v[158:159]
	s_add_i32 m0, s2, 0x2000
	s_nop 0
	global_load_lds_dwordx4 v[186:187], off
	v_lshl_add_u64 v[186:187], v[238:239], 0, s[78:79]
	s_mov_b32 m0, s17
	s_nop 0
	global_load_lds_dwordx4 v[186:187], off
	v_lshl_add_u64 v[186:187], v[240:241], 0, s[78:79]
	s_mov_b32 m0, s18
	s_nop 0
	global_load_lds_dwordx4 v[186:187], off
	s_waitcnt vmcnt(8)
	s_waitcnt lgkmcnt(0)
	s_barrier
	s_setprio 1
	s_waitcnt lgkmcnt(0)
	v_mfma_f32_16x16x32_bf16 v[62:65], v[114:117], v[182:185], v[62:65]
	v_mfma_f32_16x16x32_bf16 v[58:61], v[122:125], v[182:185], v[58:61]
	v_mfma_f32_16x16x32_bf16 v[46:49], v[114:117], v[196:199], v[46:49]
	v_mfma_f32_16x16x32_bf16 v[42:45], v[122:125], v[196:199], v[42:45]
	v_mfma_f32_16x16x32_bf16 v[30:33], v[114:117], v[204:207], v[30:33]
	v_mfma_f32_16x16x32_bf16 v[26:29], v[122:125], v[204:207], v[26:29]
	v_mfma_f32_16x16x32_bf16 v[14:17], v[114:117], v[228:231], v[14:17]
	v_mfma_f32_16x16x32_bf16 v[10:13], v[122:125], v[228:231], v[10:13]
	v_mfma_f32_16x16x32_bf16 v[62:65], v[118:121], v[192:195], v[62:65]
	v_mfma_f32_16x16x32_bf16 v[58:61], v[126:129], v[192:195], v[58:61]
	v_mfma_f32_16x16x32_bf16 v[46:49], v[118:121], v[200:203], v[46:49]
	v_mfma_f32_16x16x32_bf16 v[42:45], v[126:129], v[200:203], v[42:45]
	v_mfma_f32_16x16x32_bf16 v[30:33], v[118:121], v[224:227], v[30:33]
	v_mfma_f32_16x16x32_bf16 v[26:29], v[126:129], v[224:227], v[26:29]
	v_mfma_f32_16x16x32_bf16 v[14:17], v[118:121], v[232:235], v[14:17]
	v_mfma_f32_16x16x32_bf16 v[10:13], v[126:129], v[232:235], v[10:13]
	v_mfma_f32_16x16x32_bf16 v[54:57], v[130:133], v[182:185], v[54:57]
	v_mfma_f32_16x16x32_bf16 v[50:53], v[174:177], v[182:185], v[50:53]
	v_mfma_f32_16x16x32_bf16 v[38:41], v[130:133], v[196:199], v[38:41]
	v_mfma_f32_16x16x32_bf16 v[34:37], v[174:177], v[196:199], v[34:37]
	v_mfma_f32_16x16x32_bf16 v[22:25], v[130:133], v[204:207], v[22:25]
	v_mfma_f32_16x16x32_bf16 v[18:21], v[174:177], v[204:207], v[18:21]
	v_mfma_f32_16x16x32_bf16 v[6:9], v[130:133], v[228:231], v[6:9]
	v_mfma_f32_16x16x32_bf16 v[2:5], v[174:177], v[228:231], v[2:5]
	v_mfma_f32_16x16x32_bf16 v[54:57], v[134:137], v[192:195], v[54:57]
	v_mfma_f32_16x16x32_bf16 v[50:53], v[178:181], v[192:195], v[50:53]
	v_mfma_f32_16x16x32_bf16 v[38:41], v[134:137], v[200:203], v[38:41]
	v_mfma_f32_16x16x32_bf16 v[34:37], v[178:181], v[200:203], v[34:37]
	v_mfma_f32_16x16x32_bf16 v[22:25], v[134:137], v[224:227], v[22:25]
	v_mfma_f32_16x16x32_bf16 v[18:21], v[178:181], v[224:227], v[18:21]
	v_mfma_f32_16x16x32_bf16 v[6:9], v[134:137], v[232:235], v[6:9]
	v_mfma_f32_16x16x32_bf16 v[2:5], v[178:181], v[232:235], v[2:5]
	s_setprio 0
	s_barrier
	s_add_i32 s26, s26, 2
	s_add_u32 s66, s66, 0x100
	s_addc_u32 s67, s67, 0
	s_add_u32 s24, s24, 0x100
	s_addc_u32 s25, s25, 0
	s_cmp_gt_u32 s26, 13
	s_cbranch_scc0 .LBB0_162
	s_and_b64 vcc, exec, s[38:39]
	s_cbranch_vccz .LBB0_165
	s_barrier

.LBB0_198:
	s_add_u32 s0, s44, 0xfffe0080
	s_addc_u32 s1, s45, -1
	s_add_i32 s9, 0, 0x10000
	s_cmp_eq_u32 s8, 4
	s_cselect_b32 s3, s61, s1
	s_cselect_b32 s2, s60, s0
	v_add_u32_e32 v0, s9, v203
	s_cselect_b32 s1, s24, s5
	s_cselect_b32 s0, s25, s4
	s_add_i32 s28, 0, 0x14000
	ds_read_b128 v[142:145], v0
	ds_read_b128 v[146:149], v0 offset:1024
	ds_read_b128 v[150:153], v0 offset:2048
	ds_read_b128 v[154:157], v0 offset:3072
	v_add_u32_e32 v0, s28, v203
	ds_read_b128 v[170:173], v0
	ds_read_b128 v[174:177], v0 offset:1024
	ds_read_b128 v[178:181], v0 offset:2048
	ds_read_b128 v[182:185], v0 offset:3072
	v_lshl_add_u64 v[158:159], s[44:45], 0, v[138:139]
	s_add_i32 m0, s14, 0xc000
	ds_read_b128 v[186:189], v205
	ds_read_b128 v[190:193], v205 offset:1024
	ds_read_b128 v[194:197], v205 offset:2048
	ds_read_b128 v[198:201], v205 offset:3072
	ds_read_b128 v[224:227], v205 offset:4096
	ds_read_b128 v[228:231], v205 offset:5120
	ds_read_b128 v[232:235], v205 offset:6144
	ds_read_b128 v[236:239], v205 offset:7168
	global_load_lds_dwordx4 v[158:159], off
	v_lshl_add_u64 v[158:159], s[44:45], 0, v[140:141]
	s_add_i32 m0, s14, 0xe000
	s_nop 0
	global_load_lds_dwordx4 v[158:159], off
	s_waitcnt vmcnt(8)
	s_waitcnt lgkmcnt(0)
	s_barrier
	s_setprio 1
	s_waitcnt lgkmcnt(0)
	v_mfma_f32_16x16x32_bf16 v[122:125], v[142:145], v[186:189], v[122:125]
	v_mfma_f32_16x16x32_bf16 v[126:129], v[150:153], v[186:189], v[126:129]
	v_mfma_f32_16x16x32_bf16 v[114:117], v[142:145], v[194:197], v[114:117]
	v_mfma_f32_16x16x32_bf16 v[118:121], v[150:153], v[194:197], v[118:121]
	v_mfma_f32_16x16x32_bf16 v[106:109], v[142:145], v[224:227], v[106:109]
	v_mfma_f32_16x16x32_bf16 v[110:113], v[150:153], v[224:227], v[110:113]
	v_mfma_f32_16x16x32_bf16 v[98:101], v[142:145], v[232:235], v[98:101]
	v_mfma_f32_16x16x32_bf16 v[102:105], v[150:153], v[232:235], v[102:105]
	v_mfma_f32_16x16x32_bf16 v[122:125], v[146:149], v[190:193], v[122:125]
	v_mfma_f32_16x16x32_bf16 v[126:129], v[154:157], v[190:193], v[126:129]
	v_mfma_f32_16x16x32_bf16 v[114:117], v[146:149], v[198:201], v[114:117]
	v_mfma_f32_16x16x32_bf16 v[118:121], v[154:157], v[198:201], v[118:121]
	v_mfma_f32_16x16x32_bf16 v[106:109], v[146:149], v[228:231], v[106:109]
	v_mfma_f32_16x16x32_bf16 v[110:113], v[154:157], v[228:231], v[110:113]
	v_mfma_f32_16x16x32_bf16 v[98:101], v[146:149], v[236:239], v[98:101]
	v_mfma_f32_16x16x32_bf16 v[102:105], v[154:157], v[236:239], v[102:105]
	v_mfma_f32_16x16x32_bf16 v[90:93], v[170:173], v[186:189], v[90:93]
	v_mfma_f32_16x16x32_bf16 v[94:97], v[178:181], v[186:189], v[94:97]
	v_mfma_f32_16x16x32_bf16 v[82:85], v[170:173], v[194:197], v[82:85]
	v_mfma_f32_16x16x32_bf16 v[86:89], v[178:181], v[194:197], v[86:89]
	v_mfma_f32_16x16x32_bf16 v[74:77], v[170:173], v[224:227], v[74:77]
	v_mfma_f32_16x16x32_bf16 v[78:81], v[178:181], v[224:227], v[78:81]
	v_mfma_f32_16x16x32_bf16 v[66:69], v[170:173], v[232:235], v[66:69]
	v_mfma_f32_16x16x32_bf16 v[70:73], v[178:181], v[232:235], v[70:73]
	v_mfma_f32_16x16x32_bf16 v[90:93], v[174:177], v[190:193], v[90:93]
	v_mfma_f32_16x16x32_bf16 v[94:97], v[182:185], v[190:193], v[94:97]
	v_mfma_f32_16x16x32_bf16 v[82:85], v[174:177], v[198:201], v[82:85]
	v_mfma_f32_16x16x32_bf16 v[86:89], v[182:185], v[198:201], v[86:89]
	v_mfma_f32_16x16x32_bf16 v[74:77], v[174:177], v[228:231], v[74:77]
	v_mfma_f32_16x16x32_bf16 v[78:81], v[182:185], v[228:231], v[78:81]
	v_mfma_f32_16x16x32_bf16 v[66:69], v[174:177], v[236:239], v[66:69]
	v_mfma_f32_16x16x32_bf16 v[70:73], v[182:185], v[236:239], v[70:73]
	s_setprio 0
	s_barrier
	s_add_i32 s9, s9, s13
	v_lshl_add_u64 v[158:159], s[0:1], 0, v[134:135]
	s_mov_b32 m0, s9
	ds_read_b128 v[186:189], v205 offset:16384
	ds_read_b128 v[190:193], v205 offset:17408
	ds_read_b128 v[194:197], v205 offset:18432
	ds_read_b128 v[198:201], v205 offset:19456
	ds_read_b128 v[224:227], v205 offset:20480
	ds_read_b128 v[228:231], v205 offset:21504
	ds_read_b128 v[232:235], v205 offset:22528
	ds_read_b128 v[236:239], v205 offset:23552
	global_load_lds_dwordx4 v[158:159], off
	s_add_i32 m0, s9, 0x2000
	s_add_u32 s26, s0, 0x20000
	v_lshl_add_u64 v[206:207], s[0:1], 0, v[130:131]
	s_addc_u32 s27, s1, 0
	s_add_i32 s9, s28, s13
	global_load_lds_dwordx4 v[206:207], off
	v_lshl_add_u64 v[240:241], s[26:27], 0, v[134:135]
	s_mov_b32 m0, s9
	v_lshl_add_u64 v[242:243], s[2:3], 0, v[132:133]
	global_load_lds_dwordx4 v[240:241], off
	v_lshl_add_u64 v[240:241], s[26:27], 0, v[130:131]
	s_add_i32 m0, s9, 0x2000
	s_nop 0
	global_load_lds_dwordx4 v[240:241], off
	v_lshl_add_u64 v[240:241], s[2:3], 0, v[136:137]
	s_mov_b32 m0, s14
	s_nop 0
	global_load_lds_dwordx4 v[240:241], off
	s_mov_b32 m0, s15
	s_nop 0
	global_load_lds_dwordx4 v[242:243], off
	s_waitcnt vmcnt(8)
	s_waitcnt lgkmcnt(0)
	s_barrier
	s_setprio 1
	s_waitcnt lgkmcnt(0)
	v_mfma_f32_16x16x32_bf16 v[62:65], v[142:145], v[186:189], v[62:65]
	v_mfma_f32_16x16x32_bf16 v[58:61], v[150:153], v[186:189], v[58:61]
	v_mfma_f32_16x16x32_bf16 v[54:57], v[142:145], v[194:197], v[54:57]
	v_mfma_f32_16x16x32_bf16 v[50:53], v[150:153], v[194:197], v[50:53]
	v_mfma_f32_16x16x32_bf16 v[46:49], v[142:145], v[224:227], v[46:49]
	v_mfma_f32_16x16x32_bf16 v[42:45], v[150:153], v[224:227], v[42:45]
	v_mfma_f32_16x16x32_bf16 v[38:41], v[142:145], v[232:235], v[38:41]
	v_mfma_f32_16x16x32_bf16 v[34:37], v[150:153], v[232:235], v[34:37]
	v_mfma_f32_16x16x32_bf16 v[62:65], v[146:149], v[190:193], v[62:65]
	v_mfma_f32_16x16x32_bf16 v[58:61], v[154:157], v[190:193], v[58:61]
	v_mfma_f32_16x16x32_bf16 v[54:57], v[146:149], v[198:201], v[54:57]
	v_mfma_f32_16x16x32_bf16 v[50:53], v[154:157], v[198:201], v[50:53]
	v_mfma_f32_16x16x32_bf16 v[46:49], v[146:149], v[228:231], v[46:49]
	v_mfma_f32_16x16x32_bf16 v[42:45], v[154:157], v[228:231], v[42:45]
	v_mfma_f32_16x16x32_bf16 v[38:41], v[146:149], v[236:239], v[38:41]
	v_mfma_f32_16x16x32_bf16 v[34:37], v[154:157], v[236:239], v[34:37]
	v_mfma_f32_16x16x32_bf16 v[30:33], v[170:173], v[186:189], v[30:33]
	v_mfma_f32_16x16x32_bf16 v[26:29], v[178:181], v[186:189], v[26:29]
	v_mfma_f32_16x16x32_bf16 v[22:25], v[170:173], v[194:197], v[22:25]
	v_mfma_f32_16x16x32_bf16 v[18:21], v[178:181], v[194:197], v[18:21]
	v_mfma_f32_16x16x32_bf16 v[14:17], v[170:173], v[224:227], v[14:17]
	v_mfma_f32_16x16x32_bf16 v[10:13], v[178:181], v[224:227], v[10:13]
	v_mfma_f32_16x16x32_bf16 v[6:9], v[170:173], v[232:235], v[6:9]
	v_mfma_f32_16x16x32_bf16 v[2:5], v[178:181], v[232:235], v[2:5]
	v_mfma_f32_16x16x32_bf16 v[30:33], v[174:177], v[190:193], v[30:33]
	v_mfma_f32_16x16x32_bf16 v[26:29], v[182:185], v[190:193], v[26:29]
	v_mfma_f32_16x16x32_bf16 v[22:25], v[174:177], v[198:201], v[22:25]
	v_mfma_f32_16x16x32_bf16 v[18:21], v[182:185], v[198:201], v[18:21]
	v_mfma_f32_16x16x32_bf16 v[14:17], v[174:177], v[228:231], v[14:17]
	v_mfma_f32_16x16x32_bf16 v[10:13], v[182:185], v[228:231], v[10:13]
	v_mfma_f32_16x16x32_bf16 v[6:9], v[174:177], v[236:239], v[6:9]
	v_mfma_f32_16x16x32_bf16 v[2:5], v[182:185], v[236:239], v[2:5]
	s_setprio 0
	s_barrier
	s_add_i32 s9, 0, 0x18000
	v_add_u32_e32 v0, s9, v203
	s_add_i32 s26, 0, 0x1c000
	ds_read_b128 v[142:145], v0
	ds_read_b128 v[146:149], v0 offset:1024
	ds_read_b128 v[150:153], v0 offset:2048
	ds_read_b128 v[154:157], v0 offset:3072
	v_add_u32_e32 v0, s26, v203
	ds_read_b128 v[170:173], v0
	ds_read_b128 v[174:177], v0 offset:1024
	ds_read_b128 v[178:181], v0 offset:2048
	ds_read_b128 v[182:185], v0 offset:3072
	s_add_u32 s2, s2, 0x20000
	s_addc_u32 s3, s3, 0
	s_mov_b32 m0, s16
	v_lshl_add_u64 v[244:245], s[2:3], 0, v[136:137]
	ds_read_b128 v[186:189], v205 offset:32768
	ds_read_b128 v[190:193], v205 offset:33792
	ds_read_b128 v[194:197], v205 offset:34816
	ds_read_b128 v[198:201], v205 offset:35840
	ds_read_b128 v[224:227], v205 offset:36864
	ds_read_b128 v[228:231], v205 offset:37888
	ds_read_b128 v[232:235], v205 offset:38912
	ds_read_b128 v[236:239], v205 offset:39936
	global_load_lds_dwordx4 v[244:245], off
	v_lshl_add_u64 v[244:245], s[2:3], 0, v[132:133]
	s_mov_b32 m0, s17
	s_nop 0
	global_load_lds_dwordx4 v[244:245], off
	s_waitcnt vmcnt(8)
	s_waitcnt lgkmcnt(0)
	s_barrier
	s_setprio 1
	s_waitcnt lgkmcnt(0)
	v_mfma_f32_16x16x32_bf16 v[122:125], v[142:145], v[186:189], v[122:125]
	v_mfma_f32_16x16x32_bf16 v[126:129], v[150:153], v[186:189], v[126:129]
	v_mfma_f32_16x16x32_bf16 v[114:117], v[142:145], v[194:197], v[114:117]
	v_mfma_f32_16x16x32_bf16 v[118:121], v[150:153], v[194:197], v[118:121]
	v_mfma_f32_16x16x32_bf16 v[106:109], v[142:145], v[224:227], v[106:109]
	v_mfma_f32_16x16x32_bf16 v[110:113], v[150:153], v[224:227], v[110:113]
	v_mfma_f32_16x16x32_bf16 v[98:101], v[142:145], v[232:235], v[98:101]
	v_mfma_f32_16x16x32_bf16 v[102:105], v[150:153], v[232:235], v[102:105]
	v_mfma_f32_16x16x32_bf16 v[122:125], v[146:149], v[190:193], v[122:125]
	v_mfma_f32_16x16x32_bf16 v[126:129], v[154:157], v[190:193], v[126:129]
	v_mfma_f32_16x16x32_bf16 v[114:117], v[146:149], v[198:201], v[114:117]
	v_mfma_f32_16x16x32_bf16 v[118:121], v[154:157], v[198:201], v[118:121]
	v_mfma_f32_16x16x32_bf16 v[106:109], v[146:149], v[228:231], v[106:109]
	v_mfma_f32_16x16x32_bf16 v[110:113], v[154:157], v[228:231], v[110:113]
	v_mfma_f32_16x16x32_bf16 v[98:101], v[146:149], v[236:239], v[98:101]
	v_mfma_f32_16x16x32_bf16 v[102:105], v[154:157], v[236:239], v[102:105]
	v_mfma_f32_16x16x32_bf16 v[90:93], v[170:173], v[186:189], v[90:93]
	v_mfma_f32_16x16x32_bf16 v[94:97], v[178:181], v[186:189], v[94:97]
	v_mfma_f32_16x16x32_bf16 v[82:85], v[170:173], v[194:197], v[82:85]
	v_mfma_f32_16x16x32_bf16 v[86:89], v[178:181], v[194:197], v[86:89]
	v_mfma_f32_16x16x32_bf16 v[74:77], v[170:173], v[224:227], v[74:77]
	v_mfma_f32_16x16x32_bf16 v[78:81], v[178:181], v[224:227], v[78:81]
	v_mfma_f32_16x16x32_bf16 v[66:69], v[170:173], v[232:235], v[66:69]
	v_mfma_f32_16x16x32_bf16 v[70:73], v[178:181], v[232:235], v[70:73]
	v_mfma_f32_16x16x32_bf16 v[90:93], v[174:177], v[190:193], v[90:93]
	v_mfma_f32_16x16x32_bf16 v[94:97], v[182:185], v[190:193], v[94:97]
	v_mfma_f32_16x16x32_bf16 v[82:85], v[174:177], v[198:201], v[82:85]
	v_mfma_f32_16x16x32_bf16 v[86:89], v[182:185], v[198:201], v[86:89]
	v_mfma_f32_16x16x32_bf16 v[74:77], v[174:177], v[228:231], v[74:77]
	v_mfma_f32_16x16x32_bf16 v[78:81], v[182:185], v[228:231], v[78:81]
	v_mfma_f32_16x16x32_bf16 v[66:69], v[174:177], v[236:239], v[66:69]
	v_mfma_f32_16x16x32_bf16 v[70:73], v[182:185], v[236:239], v[70:73]
	s_setprio 0
	s_barrier
	s_add_i32 s2, s9, s13
	v_lshl_add_u64 v[158:159], v[158:159], 0, s[64:65]
	s_mov_b32 m0, s2
	ds_read_b128 v[186:189], v205 offset:49152
	ds_read_b128 v[190:193], v205 offset:50176
	ds_read_b128 v[194:197], v205 offset:51200
	ds_read_b128 v[198:201], v205 offset:52224
	ds_read_b128 v[224:227], v205 offset:53248
	ds_read_b128 v[228:231], v205 offset:54272
	ds_read_b128 v[232:235], v205 offset:55296
	ds_read_b128 v[236:239], v205 offset:56320
	global_load_lds_dwordx4 v[158:159], off
	s_add_i32 m0, s2, 0x2000
	s_add_u32 s0, s0, 0x20080
	v_lshl_add_u64 v[158:159], v[206:207], 0, s[64:65]
	s_addc_u32 s1, s1, 0
	s_add_i32 s2, s26, s13
	global_load_lds_dwordx4 v[158:159], off
	v_lshl_add_u64 v[158:159], s[0:1], 0, v[134:135]
	s_mov_b32 m0, s2
	s_nop 0
	global_load_lds_dwordx4 v[158:159], off
	v_lshl_add_u64 v[158:159], s[0:1], 0, v[130:131]
	s_add_i32 m0, s2, 0x2000
	s_nop 0
	global_load_lds_dwordx4 v[158:159], off
	v_lshl_add_u64 v[158:159], v[240:241], 0, s[64:65]
	s_mov_b32 m0, s20
	s_nop 0
	global_load_lds_dwordx4 v[158:159], off
	v_lshl_add_u64 v[158:159], v[242:243], 0, s[64:65]
	s_mov_b32 m0, s21
	s_nop 0
	global_load_lds_dwordx4 v[158:159], off
	s_waitcnt vmcnt(8)
	s_waitcnt lgkmcnt(0)
	s_barrier
	s_setprio 1
	s_waitcnt lgkmcnt(0)
	v_mfma_f32_16x16x32_bf16 v[62:65], v[142:145], v[186:189], v[62:65]
	v_mfma_f32_16x16x32_bf16 v[58:61], v[150:153], v[186:189], v[58:61]
	v_mfma_f32_16x16x32_bf16 v[54:57], v[142:145], v[194:197], v[54:57]
	v_mfma_f32_16x16x32_bf16 v[50:53], v[150:153], v[194:197], v[50:53]
	v_mfma_f32_16x16x32_bf16 v[46:49], v[142:145], v[224:227], v[46:49]
	v_mfma_f32_16x16x32_bf16 v[42:45], v[150:153], v[224:227], v[42:45]
	v_mfma_f32_16x16x32_bf16 v[38:41], v[142:145], v[232:235], v[38:41]
	v_mfma_f32_16x16x32_bf16 v[34:37], v[150:153], v[232:235], v[34:37]
	v_mfma_f32_16x16x32_bf16 v[62:65], v[146:149], v[190:193], v[62:65]
	v_mfma_f32_16x16x32_bf16 v[58:61], v[154:157], v[190:193], v[58:61]
	v_mfma_f32_16x16x32_bf16 v[54:57], v[146:149], v[198:201], v[54:57]
	v_mfma_f32_16x16x32_bf16 v[50:53], v[154:157], v[198:201], v[50:53]
	v_mfma_f32_16x16x32_bf16 v[46:49], v[146:149], v[228:231], v[46:49]
	v_mfma_f32_16x16x32_bf16 v[42:45], v[154:157], v[228:231], v[42:45]
	v_mfma_f32_16x16x32_bf16 v[38:41], v[146:149], v[236:239], v[38:41]
	v_mfma_f32_16x16x32_bf16 v[34:37], v[154:157], v[236:239], v[34:37]
	v_mfma_f32_16x16x32_bf16 v[30:33], v[170:173], v[186:189], v[30:33]
	v_mfma_f32_16x16x32_bf16 v[26:29], v[178:181], v[186:189], v[26:29]
	v_mfma_f32_16x16x32_bf16 v[22:25], v[170:173], v[194:197], v[22:25]
	v_mfma_f32_16x16x32_bf16 v[18:21], v[178:181], v[194:197], v[18:21]
	v_mfma_f32_16x16x32_bf16 v[14:17], v[170:173], v[224:227], v[14:17]
	v_mfma_f32_16x16x32_bf16 v[10:13], v[178:181], v[224:227], v[10:13]
	v_mfma_f32_16x16x32_bf16 v[6:9], v[170:173], v[232:235], v[6:9]
	v_mfma_f32_16x16x32_bf16 v[2:5], v[178:181], v[232:235], v[2:5]
	v_mfma_f32_16x16x32_bf16 v[30:33], v[174:177], v[190:193], v[30:33]
	v_mfma_f32_16x16x32_bf16 v[26:29], v[182:185], v[190:193], v[26:29]
	v_mfma_f32_16x16x32_bf16 v[22:25], v[174:177], v[198:201], v[22:25]
	v_mfma_f32_16x16x32_bf16 v[18:21], v[182:185], v[198:201], v[18:21]
	v_mfma_f32_16x16x32_bf16 v[14:17], v[174:177], v[228:231], v[14:17]
	v_mfma_f32_16x16x32_bf16 v[10:13], v[182:185], v[228:231], v[10:13]
	v_mfma_f32_16x16x32_bf16 v[6:9], v[174:177], v[236:239], v[6:9]
	v_mfma_f32_16x16x32_bf16 v[2:5], v[182:185], v[236:239], v[2:5]
	s_setprio 0
	s_barrier
	s_add_i32 s8, s8, 2
	s_add_u32 s44, s44, 0x100
	s_addc_u32 s45, s45, 0
	s_add_u32 s4, s4, 0x100
	s_addc_u32 s5, s5, 0
	s_cmp_gt_u32 s8, 5
	s_cbranch_scc0 .LBB0_198
	s_and_b64 vcc, exec, s[38:39]
	s_cbranch_vccz .LBB0_201
	s_barrier

.Lpws__662_0:
	s_waitcnt lgkmcnt(0)
	s_barrier
	s_setprio 1
	s_waitcnt lgkmcnt(0)
	v_mfma_f32_16x16x32_bf16 v[150:153], v[114:117], v[182:185], 0
	v_mfma_f32_16x16x32_bf16 v[146:149], v[122:125], v[182:185], 0
	v_mfma_f32_16x16x32_bf16 v[110:113], v[114:117], v[196:199], 0
	v_mfma_f32_16x16x32_bf16 v[106:109], v[122:125], v[196:199], 0
	v_mfma_f32_16x16x32_bf16 v[94:97], v[114:117], v[204:207], 0
	v_mfma_f32_16x16x32_bf16 v[90:93], v[122:125], v[204:207], 0
	v_mfma_f32_16x16x32_bf16 v[78:81], v[114:117], v[228:231], 0
	v_mfma_f32_16x16x32_bf16 v[74:77], v[122:125], v[228:231], 0
	v_mfma_f32_16x16x32_bf16 v[150:153], v[118:121], v[192:195], v[150:153]
	v_mfma_f32_16x16x32_bf16 v[146:149], v[126:129], v[192:195], v[146:149]
	v_mfma_f32_16x16x32_bf16 v[110:113], v[118:121], v[200:203], v[110:113]
	v_mfma_f32_16x16x32_bf16 v[106:109], v[126:129], v[200:203], v[106:109]
	v_mfma_f32_16x16x32_bf16 v[94:97], v[118:121], v[224:227], v[94:97]
	v_mfma_f32_16x16x32_bf16 v[90:93], v[126:129], v[224:227], v[90:93]
	v_mfma_f32_16x16x32_bf16 v[78:81], v[118:121], v[232:235], v[78:81]
	v_mfma_f32_16x16x32_bf16 v[74:77], v[126:129], v[232:235], v[74:77]
	v_mfma_f32_16x16x32_bf16 v[142:145], v[130:133], v[182:185], 0
	v_mfma_f32_16x16x32_bf16 v[138:141], v[174:177], v[182:185], 0
	v_mfma_f32_16x16x32_bf16 v[102:105], v[130:133], v[196:199], 0
	v_mfma_f32_16x16x32_bf16 v[98:101], v[174:177], v[196:199], 0
	v_mfma_f32_16x16x32_bf16 v[86:89], v[130:133], v[204:207], 0
	v_mfma_f32_16x16x32_bf16 v[82:85], v[174:177], v[204:207], 0
	v_mfma_f32_16x16x32_bf16 v[70:73], v[130:133], v[228:231], 0
	v_mfma_f32_16x16x32_bf16 v[66:69], v[174:177], v[228:231], 0
	v_mfma_f32_16x16x32_bf16 v[142:145], v[134:137], v[192:195], v[142:145]
	v_mfma_f32_16x16x32_bf16 v[138:141], v[178:181], v[192:195], v[138:141]
	v_mfma_f32_16x16x32_bf16 v[102:105], v[134:137], v[200:203], v[102:105]
	v_mfma_f32_16x16x32_bf16 v[98:101], v[178:181], v[200:203], v[98:101]
	v_mfma_f32_16x16x32_bf16 v[86:89], v[134:137], v[224:227], v[86:89]
	v_mfma_f32_16x16x32_bf16 v[82:85], v[178:181], v[224:227], v[82:85]
	v_mfma_f32_16x16x32_bf16 v[70:73], v[134:137], v[232:235], v[70:73]
	v_mfma_f32_16x16x32_bf16 v[66:69], v[178:181], v[232:235], v[66:69]
	s_setprio 0
	s_barrier
	s_add_i32 s28, s28, s13
	v_lshl_add_u64 v[186:187], s[2:3], 0, v[0:1]
	s_mov_b32 m0, s28
	ds_read_b128 v[182:185], v191 offset:16384
	ds_read_b128 v[192:195], v191 offset:17408
	ds_read_b128 v[196:199], v191 offset:18432
	ds_read_b128 v[200:203], v191 offset:19456
	ds_read_b128 v[204:207], v191 offset:20480
	ds_read_b128 v[224:227], v191 offset:21504
	ds_read_b128 v[228:231], v191 offset:22528
	ds_read_b128 v[232:235], v191 offset:23552
	global_load_lds_dwordx4 v[186:187], off
	s_add_i32 m0, s28, 0x2000
	s_add_u32 s28, s2, 0xb0000
	v_lshl_add_u64 v[236:237], s[2:3], 0, v[158:159]
	s_addc_u32 s29, s3, 0
	s_add_i32 s34, s34, s13
	global_load_lds_dwordx4 v[236:237], off
	v_lshl_add_u64 v[238:239], s[28:29], 0, v[0:1]
	s_mov_b32 m0, s34
	v_lshl_add_u64 v[240:241], s[4:5], 0, v[156:157]
	global_load_lds_dwordx4 v[238:239], off
	v_lshl_add_u64 v[238:239], s[28:29], 0, v[158:159]
	s_add_i32 m0, s34, 0x2000
	s_nop 0
	global_load_lds_dwordx4 v[238:239], off
	v_lshl_add_u64 v[238:239], s[4:5], 0, v[154:155]
	s_mov_b32 m0, s14
	s_nop 0
	global_load_lds_dwordx4 v[238:239], off
	s_mov_b32 m0, s15
	s_nop 0
	global_load_lds_dwordx4 v[240:241], off
	s_cmp_lg_u32 s27, -2
	s_cbranch_scc1 .Lpwt__662_1
	s_cmp_lt_u32 s20, 2
	s_cbranch_scc0 .Lpws__662_1

.Lpws__662_1:
	s_waitcnt lgkmcnt(0)
	s_barrier
	s_setprio 1
	s_waitcnt lgkmcnt(0)
	v_mfma_f32_16x16x32_bf16 v[62:65], v[114:117], v[182:185], 0
	v_mfma_f32_16x16x32_bf16 v[58:61], v[122:125], v[182:185], 0
	v_mfma_f32_16x16x32_bf16 v[46:49], v[114:117], v[196:199], 0
	v_mfma_f32_16x16x32_bf16 v[42:45], v[122:125], v[196:199], 0
	v_mfma_f32_16x16x32_bf16 v[30:33], v[114:117], v[204:207], 0
	v_mfma_f32_16x16x32_bf16 v[26:29], v[122:125], v[204:207], 0
	v_mfma_f32_16x16x32_bf16 v[14:17], v[114:117], v[228:231], 0
	v_mfma_f32_16x16x32_bf16 v[10:13], v[122:125], v[228:231], 0
	v_mfma_f32_16x16x32_bf16 v[62:65], v[118:121], v[192:195], v[62:65]
	v_mfma_f32_16x16x32_bf16 v[58:61], v[126:129], v[192:195], v[58:61]
	v_mfma_f32_16x16x32_bf16 v[46:49], v[118:121], v[200:203], v[46:49]
	v_mfma_f32_16x16x32_bf16 v[42:45], v[126:129], v[200:203], v[42:45]
	v_mfma_f32_16x16x32_bf16 v[30:33], v[118:121], v[224:227], v[30:33]
	v_mfma_f32_16x16x32_bf16 v[26:29], v[126:129], v[224:227], v[26:29]
	v_mfma_f32_16x16x32_bf16 v[14:17], v[118:121], v[232:235], v[14:17]
	v_mfma_f32_16x16x32_bf16 v[10:13], v[126:129], v[232:235], v[10:13]
	v_mfma_f32_16x16x32_bf16 v[54:57], v[130:133], v[182:185], 0
	v_mfma_f32_16x16x32_bf16 v[50:53], v[174:177], v[182:185], 0
	v_mfma_f32_16x16x32_bf16 v[38:41], v[130:133], v[196:199], 0
	v_mfma_f32_16x16x32_bf16 v[34:37], v[174:177], v[196:199], 0
	v_mfma_f32_16x16x32_bf16 v[22:25], v[130:133], v[204:207], 0
	v_mfma_f32_16x16x32_bf16 v[18:21], v[174:177], v[204:207], 0
	v_mfma_f32_16x16x32_bf16 v[6:9], v[130:133], v[228:231], 0
	v_mfma_f32_16x16x32_bf16 v[2:5], v[174:177], v[228:231], 0
	v_mfma_f32_16x16x32_bf16 v[54:57], v[134:137], v[192:195], v[54:57]
	v_mfma_f32_16x16x32_bf16 v[50:53], v[178:181], v[192:195], v[50:53]
	v_mfma_f32_16x16x32_bf16 v[38:41], v[134:137], v[200:203], v[38:41]
	v_mfma_f32_16x16x32_bf16 v[34:37], v[178:181], v[200:203], v[34:37]
	v_mfma_f32_16x16x32_bf16 v[22:25], v[134:137], v[224:227], v[22:25]
	v_mfma_f32_16x16x32_bf16 v[18:21], v[178:181], v[224:227], v[18:21]
	v_mfma_f32_16x16x32_bf16 v[6:9], v[134:137], v[232:235], v[6:9]
	v_mfma_f32_16x16x32_bf16 v[2:5], v[178:181], v[232:235], v[2:5]
	s_setprio 0
	s_barrier
	s_add_i32 s28, 0, 0x18000
	s_add_i32 s29, 0, 0x1c000
	v_add_u32_e32 v126, s28, v189
	v_add_u32_e32 v178, s29, v189
	ds_read_b128 v[114:117], v126
	ds_read_b128 v[118:121], v126 offset:1024
	ds_read_b128 v[122:125], v126 offset:2048
	ds_read_b128 v[126:129], v126 offset:3072
	ds_read_b128 v[130:133], v178
	ds_read_b128 v[134:137], v178 offset:1024
	ds_read_b128 v[174:177], v178 offset:2048
	ds_read_b128 v[178:181], v178 offset:3072
	s_add_u32 s4, s4, 0xb0000
	s_addc_u32 s5, s5, 0
	s_mov_b32 m0, s16
	v_lshl_add_u64 v[242:243], s[4:5], 0, v[154:155]
	ds_read_b128 v[182:185], v191 offset:32768
	ds_read_b128 v[192:195], v191 offset:33792
	ds_read_b128 v[196:199], v191 offset:34816
	ds_read_b128 v[200:203], v191 offset:35840
	ds_read_b128 v[204:207], v191 offset:36864
	ds_read_b128 v[224:227], v191 offset:37888
	ds_read_b128 v[228:231], v191 offset:38912
	ds_read_b128 v[232:235], v191 offset:39936
	global_load_lds_dwordx4 v[242:243], off
	v_lshl_add_u64 v[242:243], s[4:5], 0, v[156:157]
	s_mov_b32 m0, s17
	s_nop 0
	global_load_lds_dwordx4 v[242:243], off
	s_waitcnt vmcnt(8)
	s_waitcnt lgkmcnt(0)
	s_barrier
	s_setprio 1
	s_waitcnt lgkmcnt(0)
	v_mfma_f32_16x16x32_bf16 v[150:153], v[114:117], v[182:185], v[150:153]
	v_mfma_f32_16x16x32_bf16 v[146:149], v[122:125], v[182:185], v[146:149]
	v_mfma_f32_16x16x32_bf16 v[110:113], v[114:117], v[196:199], v[110:113]
	v_mfma_f32_16x16x32_bf16 v[106:109], v[122:125], v[196:199], v[106:109]
	v_mfma_f32_16x16x32_bf16 v[94:97], v[114:117], v[204:207], v[94:97]
	v_mfma_f32_16x16x32_bf16 v[90:93], v[122:125], v[204:207], v[90:93]
	v_mfma_f32_16x16x32_bf16 v[78:81], v[114:117], v[228:231], v[78:81]
	v_mfma_f32_16x16x32_bf16 v[74:77], v[122:125], v[228:231], v[74:77]
	v_mfma_f32_16x16x32_bf16 v[150:153], v[118:121], v[192:195], v[150:153]
	v_mfma_f32_16x16x32_bf16 v[146:149], v[126:129], v[192:195], v[146:149]
	v_mfma_f32_16x16x32_bf16 v[110:113], v[118:121], v[200:203], v[110:113]
	v_mfma_f32_16x16x32_bf16 v[106:109], v[126:129], v[200:203], v[106:109]
	v_mfma_f32_16x16x32_bf16 v[94:97], v[118:121], v[224:227], v[94:97]
	v_mfma_f32_16x16x32_bf16 v[90:93], v[126:129], v[224:227], v[90:93]
	v_mfma_f32_16x16x32_bf16 v[78:81], v[118:121], v[232:235], v[78:81]
	v_mfma_f32_16x16x32_bf16 v[74:77], v[126:129], v[232:235], v[74:77]
	v_mfma_f32_16x16x32_bf16 v[142:145], v[130:133], v[182:185], v[142:145]
	v_mfma_f32_16x16x32_bf16 v[138:141], v[174:177], v[182:185], v[138:141]
	v_mfma_f32_16x16x32_bf16 v[102:105], v[130:133], v[196:199], v[102:105]
	v_mfma_f32_16x16x32_bf16 v[98:101], v[174:177], v[196:199], v[98:101]
	v_mfma_f32_16x16x32_bf16 v[86:89], v[130:133], v[204:207], v[86:89]
	v_mfma_f32_16x16x32_bf16 v[82:85], v[174:177], v[204:207], v[82:85]
	v_mfma_f32_16x16x32_bf16 v[70:73], v[130:133], v[228:231], v[70:73]
	v_mfma_f32_16x16x32_bf16 v[66:69], v[174:177], v[228:231], v[66:69]
	v_mfma_f32_16x16x32_bf16 v[142:145], v[134:137], v[192:195], v[142:145]
	v_mfma_f32_16x16x32_bf16 v[138:141], v[178:181], v[192:195], v[138:141]
	v_mfma_f32_16x16x32_bf16 v[102:105], v[134:137], v[200:203], v[102:105]
	v_mfma_f32_16x16x32_bf16 v[98:101], v[178:181], v[200:203], v[98:101]
	v_mfma_f32_16x16x32_bf16 v[86:89], v[134:137], v[224:227], v[86:89]
	v_mfma_f32_16x16x32_bf16 v[82:85], v[178:181], v[224:227], v[82:85]
	v_mfma_f32_16x16x32_bf16 v[70:73], v[134:137], v[232:235], v[70:73]
	v_mfma_f32_16x16x32_bf16 v[66:69], v[178:181], v[232:235], v[66:69]
	s_setprio 0
	s_barrier
	s_add_i32 s4, s28, s13
	v_lshl_add_u64 v[186:187], v[186:187], 0, s[60:61]
	s_mov_b32 m0, s4
	ds_read_b128 v[182:185], v191 offset:49152
	ds_read_b128 v[192:195], v191 offset:50176
	ds_read_b128 v[196:199], v191 offset:51200
	ds_read_b128 v[200:203], v191 offset:52224
	ds_read_b128 v[204:207], v191 offset:53248
	ds_read_b128 v[224:227], v191 offset:54272
	ds_read_b128 v[228:231], v191 offset:55296
	ds_read_b128 v[232:235], v191 offset:56320
	global_load_lds_dwordx4 v[186:187], off
	s_add_i32 m0, s4, 0x2000
	s_add_u32 s2, s2, 0xb0080
	v_lshl_add_u64 v[186:187], v[236:237], 0, s[60:61]
	s_addc_u32 s3, s3, 0
	s_add_i32 s4, s29, s13
	global_load_lds_dwordx4 v[186:187], off
	v_lshl_add_u64 v[186:187], s[2:3], 0, v[0:1]
	s_mov_b32 m0, s4
	s_nop 0
	global_load_lds_dwordx4 v[186:187], off
	v_lshl_add_u64 v[186:187], s[2:3], 0, v[158:159]
	s_add_i32 m0, s4, 0x2000
	s_nop 0
	global_load_lds_dwordx4 v[186:187], off
	v_lshl_add_u64 v[186:187], v[238:239], 0, s[60:61]
	s_mov_b32 m0, s18
	s_nop 0
	global_load_lds_dwordx4 v[186:187], off
	v_lshl_add_u64 v[186:187], v[240:241], 0, s[60:61]
	s_mov_b32 m0, s19
	s_nop 0
	global_load_lds_dwordx4 v[186:187], off
	s_waitcnt vmcnt(8)
	s_waitcnt lgkmcnt(0)
	s_barrier
	s_setprio 1
	s_waitcnt lgkmcnt(0)
	v_mfma_f32_16x16x32_bf16 v[62:65], v[114:117], v[182:185], v[62:65]
	v_mfma_f32_16x16x32_bf16 v[58:61], v[122:125], v[182:185], v[58:61]
	v_mfma_f32_16x16x32_bf16 v[46:49], v[114:117], v[196:199], v[46:49]
	v_mfma_f32_16x16x32_bf16 v[42:45], v[122:125], v[196:199], v[42:45]
	v_mfma_f32_16x16x32_bf16 v[30:33], v[114:117], v[204:207], v[30:33]
	v_mfma_f32_16x16x32_bf16 v[26:29], v[122:125], v[204:207], v[26:29]
	v_mfma_f32_16x16x32_bf16 v[14:17], v[114:117], v[228:231], v[14:17]
	v_mfma_f32_16x16x32_bf16 v[10:13], v[122:125], v[228:231], v[10:13]
	v_mfma_f32_16x16x32_bf16 v[62:65], v[118:121], v[192:195], v[62:65]
	v_mfma_f32_16x16x32_bf16 v[58:61], v[126:129], v[192:195], v[58:61]
	v_mfma_f32_16x16x32_bf16 v[46:49], v[118:121], v[200:203], v[46:49]
	v_mfma_f32_16x16x32_bf16 v[42:45], v[126:129], v[200:203], v[42:45]
	v_mfma_f32_16x16x32_bf16 v[30:33], v[118:121], v[224:227], v[30:33]
	v_mfma_f32_16x16x32_bf16 v[26:29], v[126:129], v[224:227], v[26:29]
	v_mfma_f32_16x16x32_bf16 v[14:17], v[118:121], v[232:235], v[14:17]
	v_mfma_f32_16x16x32_bf16 v[10:13], v[126:129], v[232:235], v[10:13]
	v_mfma_f32_16x16x32_bf16 v[54:57], v[130:133], v[182:185], v[54:57]
	v_mfma_f32_16x16x32_bf16 v[50:53], v[174:177], v[182:185], v[50:53]
	v_mfma_f32_16x16x32_bf16 v[38:41], v[130:133], v[196:199], v[38:41]
	v_mfma_f32_16x16x32_bf16 v[34:37], v[174:177], v[196:199], v[34:37]
	v_mfma_f32_16x16x32_bf16 v[22:25], v[130:133], v[204:207], v[22:25]
	v_mfma_f32_16x16x32_bf16 v[18:21], v[174:177], v[204:207], v[18:21]
	v_mfma_f32_16x16x32_bf16 v[6:9], v[130:133], v[228:231], v[6:9]
	v_mfma_f32_16x16x32_bf16 v[2:5], v[174:177], v[228:231], v[2:5]
	v_mfma_f32_16x16x32_bf16 v[54:57], v[134:137], v[192:195], v[54:57]
	v_mfma_f32_16x16x32_bf16 v[50:53], v[178:181], v[192:195], v[50:53]
	v_mfma_f32_16x16x32_bf16 v[38:41], v[134:137], v[200:203], v[38:41]
	v_mfma_f32_16x16x32_bf16 v[34:37], v[178:181], v[200:203], v[34:37]
	v_mfma_f32_16x16x32_bf16 v[22:25], v[134:137], v[224:227], v[22:25]
	v_mfma_f32_16x16x32_bf16 v[18:21], v[178:181], v[224:227], v[18:21]
	v_mfma_f32_16x16x32_bf16 v[6:9], v[134:137], v[232:235], v[6:9]
	v_mfma_f32_16x16x32_bf16 v[2:5], v[178:181], v[232:235], v[2:5]
	s_setprio 0
	s_barrier
	s_add_i32 s27, s27, 2
	s_add_u32 s25, s25, 0x100
	s_addc_u32 s26, s26, 0
	s_cmp_gt_u32 s27, 41
	s_mov_b64 s[56:57], s[0:1]

.Lws__662_0:
	s_waitcnt lgkmcnt(0)
	s_barrier
	s_setprio 1
	s_waitcnt lgkmcnt(0)
	v_mfma_f32_16x16x32_bf16 v[150:153], v[114:117], v[182:185], v[150:153]
	v_mfma_f32_16x16x32_bf16 v[146:149], v[122:125], v[182:185], v[146:149]
	v_mfma_f32_16x16x32_bf16 v[110:113], v[114:117], v[196:199], v[110:113]
	v_mfma_f32_16x16x32_bf16 v[106:109], v[122:125], v[196:199], v[106:109]
	v_mfma_f32_16x16x32_bf16 v[94:97], v[114:117], v[204:207], v[94:97]
	v_mfma_f32_16x16x32_bf16 v[90:93], v[122:125], v[204:207], v[90:93]
	v_mfma_f32_16x16x32_bf16 v[78:81], v[114:117], v[228:231], v[78:81]
	v_mfma_f32_16x16x32_bf16 v[74:77], v[122:125], v[228:231], v[74:77]
	v_mfma_f32_16x16x32_bf16 v[150:153], v[118:121], v[192:195], v[150:153]
	v_mfma_f32_16x16x32_bf16 v[146:149], v[126:129], v[192:195], v[146:149]
	v_mfma_f32_16x16x32_bf16 v[110:113], v[118:121], v[200:203], v[110:113]
	v_mfma_f32_16x16x32_bf16 v[106:109], v[126:129], v[200:203], v[106:109]
	v_mfma_f32_16x16x32_bf16 v[94:97], v[118:121], v[224:227], v[94:97]
	v_mfma_f32_16x16x32_bf16 v[90:93], v[126:129], v[224:227], v[90:93]
	v_mfma_f32_16x16x32_bf16 v[78:81], v[118:121], v[232:235], v[78:81]
	v_mfma_f32_16x16x32_bf16 v[74:77], v[126:129], v[232:235], v[74:77]
	v_mfma_f32_16x16x32_bf16 v[142:145], v[130:133], v[182:185], v[142:145]
	v_mfma_f32_16x16x32_bf16 v[138:141], v[174:177], v[182:185], v[138:141]
	v_mfma_f32_16x16x32_bf16 v[102:105], v[130:133], v[196:199], v[102:105]
	v_mfma_f32_16x16x32_bf16 v[98:101], v[174:177], v[196:199], v[98:101]
	v_mfma_f32_16x16x32_bf16 v[86:89], v[130:133], v[204:207], v[86:89]
	v_mfma_f32_16x16x32_bf16 v[82:85], v[174:177], v[204:207], v[82:85]
	v_mfma_f32_16x16x32_bf16 v[70:73], v[130:133], v[228:231], v[70:73]
	v_mfma_f32_16x16x32_bf16 v[66:69], v[174:177], v[228:231], v[66:69]
	v_mfma_f32_16x16x32_bf16 v[142:145], v[134:137], v[192:195], v[142:145]
	v_mfma_f32_16x16x32_bf16 v[138:141], v[178:181], v[192:195], v[138:141]
	v_mfma_f32_16x16x32_bf16 v[102:105], v[134:137], v[200:203], v[102:105]
	v_mfma_f32_16x16x32_bf16 v[98:101], v[178:181], v[200:203], v[98:101]
	v_mfma_f32_16x16x32_bf16 v[86:89], v[134:137], v[224:227], v[86:89]
	v_mfma_f32_16x16x32_bf16 v[82:85], v[178:181], v[224:227], v[82:85]
	v_mfma_f32_16x16x32_bf16 v[70:73], v[134:137], v[232:235], v[70:73]
	v_mfma_f32_16x16x32_bf16 v[66:69], v[178:181], v[232:235], v[66:69]
	s_setprio 0
	s_barrier
	s_add_i32 s28, s28, s13
	v_lshl_add_u64 v[186:187], s[2:3], 0, v[0:1]
	s_mov_b32 m0, s28
	ds_read_b128 v[182:185], v191 offset:16384
	ds_read_b128 v[192:195], v191 offset:17408
	ds_read_b128 v[196:199], v191 offset:18432
	ds_read_b128 v[200:203], v191 offset:19456
	ds_read_b128 v[204:207], v191 offset:20480
	ds_read_b128 v[224:227], v191 offset:21504
	ds_read_b128 v[228:231], v191 offset:22528
	ds_read_b128 v[232:235], v191 offset:23552
	global_load_lds_dwordx4 v[186:187], off
	s_add_i32 m0, s28, 0x2000
	s_add_u32 s28, s2, 0xb0000
	v_lshl_add_u64 v[236:237], s[2:3], 0, v[158:159]
	s_addc_u32 s29, s3, 0
	s_add_i32 s34, s34, s13
	global_load_lds_dwordx4 v[236:237], off
	v_lshl_add_u64 v[238:239], s[28:29], 0, v[0:1]
	s_mov_b32 m0, s34
	v_lshl_add_u64 v[240:241], s[4:5], 0, v[156:157]
	global_load_lds_dwordx4 v[238:239], off
	v_lshl_add_u64 v[238:239], s[28:29], 0, v[158:159]
	s_add_i32 m0, s34, 0x2000
	s_nop 0
	global_load_lds_dwordx4 v[238:239], off
	v_lshl_add_u64 v[238:239], s[4:5], 0, v[154:155]
	s_mov_b32 m0, s14
	s_nop 0
	global_load_lds_dwordx4 v[238:239], off
	s_mov_b32 m0, s15
	s_nop 0
	global_load_lds_dwordx4 v[240:241], off
	s_cmp_lg_u32 s27, -2
	s_cbranch_scc1 .Lwt__662_1
	s_cmp_lt_u32 s20, 2
	s_cbranch_scc0 .Lws__662_1

.Lws__662_1:
	s_waitcnt lgkmcnt(0)
	s_barrier
	s_setprio 1
	s_waitcnt lgkmcnt(0)
	v_mfma_f32_16x16x32_bf16 v[62:65], v[114:117], v[182:185], v[62:65]
	v_mfma_f32_16x16x32_bf16 v[58:61], v[122:125], v[182:185], v[58:61]
	v_mfma_f32_16x16x32_bf16 v[46:49], v[114:117], v[196:199], v[46:49]
	v_mfma_f32_16x16x32_bf16 v[42:45], v[122:125], v[196:199], v[42:45]
	v_mfma_f32_16x16x32_bf16 v[30:33], v[114:117], v[204:207], v[30:33]
	v_mfma_f32_16x16x32_bf16 v[26:29], v[122:125], v[204:207], v[26:29]
	v_mfma_f32_16x16x32_bf16 v[14:17], v[114:117], v[228:231], v[14:17]
	v_mfma_f32_16x16x32_bf16 v[10:13], v[122:125], v[228:231], v[10:13]
	v_mfma_f32_16x16x32_bf16 v[62:65], v[118:121], v[192:195], v[62:65]
	v_mfma_f32_16x16x32_bf16 v[58:61], v[126:129], v[192:195], v[58:61]
	v_mfma_f32_16x16x32_bf16 v[46:49], v[118:121], v[200:203], v[46:49]
	v_mfma_f32_16x16x32_bf16 v[42:45], v[126:129], v[200:203], v[42:45]
	v_mfma_f32_16x16x32_bf16 v[30:33], v[118:121], v[224:227], v[30:33]
	v_mfma_f32_16x16x32_bf16 v[26:29], v[126:129], v[224:227], v[26:29]
	v_mfma_f32_16x16x32_bf16 v[14:17], v[118:121], v[232:235], v[14:17]
	v_mfma_f32_16x16x32_bf16 v[10:13], v[126:129], v[232:235], v[10:13]
	v_mfma_f32_16x16x32_bf16 v[54:57], v[130:133], v[182:185], v[54:57]
	v_mfma_f32_16x16x32_bf16 v[50:53], v[174:177], v[182:185], v[50:53]
	v_mfma_f32_16x16x32_bf16 v[38:41], v[130:133], v[196:199], v[38:41]
	v_mfma_f32_16x16x32_bf16 v[34:37], v[174:177], v[196:199], v[34:37]
	v_mfma_f32_16x16x32_bf16 v[22:25], v[130:133], v[204:207], v[22:25]
	v_mfma_f32_16x16x32_bf16 v[18:21], v[174:177], v[204:207], v[18:21]
	v_mfma_f32_16x16x32_bf16 v[6:9], v[130:133], v[228:231], v[6:9]
	v_mfma_f32_16x16x32_bf16 v[2:5], v[174:177], v[228:231], v[2:5]
	v_mfma_f32_16x16x32_bf16 v[54:57], v[134:137], v[192:195], v[54:57]
	v_mfma_f32_16x16x32_bf16 v[50:53], v[178:181], v[192:195], v[50:53]
	v_mfma_f32_16x16x32_bf16 v[38:41], v[134:137], v[200:203], v[38:41]
	v_mfma_f32_16x16x32_bf16 v[34:37], v[178:181], v[200:203], v[34:37]
	v_mfma_f32_16x16x32_bf16 v[22:25], v[134:137], v[224:227], v[22:25]
	v_mfma_f32_16x16x32_bf16 v[18:21], v[178:181], v[224:227], v[18:21]
	v_mfma_f32_16x16x32_bf16 v[6:9], v[134:137], v[232:235], v[6:9]
	v_mfma_f32_16x16x32_bf16 v[2:5], v[178:181], v[232:235], v[2:5]
	s_setprio 0
	s_barrier
	s_add_i32 s28, 0, 0x18000
	s_add_i32 s29, 0, 0x1c000
	v_add_u32_e32 v126, s28, v189
	v_add_u32_e32 v178, s29, v189
	ds_read_b128 v[114:117], v126
	ds_read_b128 v[118:121], v126 offset:1024
	ds_read_b128 v[122:125], v126 offset:2048
	ds_read_b128 v[126:129], v126 offset:3072
	ds_read_b128 v[130:133], v178
	ds_read_b128 v[134:137], v178 offset:1024
	ds_read_b128 v[174:177], v178 offset:2048
	ds_read_b128 v[178:181], v178 offset:3072
	s_add_u32 s4, s4, 0xb0000
	s_addc_u32 s5, s5, 0
	s_mov_b32 m0, s16
	v_lshl_add_u64 v[242:243], s[4:5], 0, v[154:155]
	ds_read_b128 v[182:185], v191 offset:32768
	ds_read_b128 v[192:195], v191 offset:33792
	ds_read_b128 v[196:199], v191 offset:34816
	ds_read_b128 v[200:203], v191 offset:35840
	ds_read_b128 v[204:207], v191 offset:36864
	ds_read_b128 v[224:227], v191 offset:37888
	ds_read_b128 v[228:231], v191 offset:38912
	ds_read_b128 v[232:235], v191 offset:39936
	global_load_lds_dwordx4 v[242:243], off
	v_lshl_add_u64 v[242:243], s[4:5], 0, v[156:157]
	s_mov_b32 m0, s17
	s_nop 0
	global_load_lds_dwordx4 v[242:243], off
	s_waitcnt vmcnt(8)
	s_waitcnt lgkmcnt(0)
	s_barrier
	s_setprio 1
	s_waitcnt lgkmcnt(0)
	v_mfma_f32_16x16x32_bf16 v[150:153], v[114:117], v[182:185], v[150:153]
	v_mfma_f32_16x16x32_bf16 v[146:149], v[122:125], v[182:185], v[146:149]
	v_mfma_f32_16x16x32_bf16 v[110:113], v[114:117], v[196:199], v[110:113]
	v_mfma_f32_16x16x32_bf16 v[106:109], v[122:125], v[196:199], v[106:109]
	v_mfma_f32_16x16x32_bf16 v[94:97], v[114:117], v[204:207], v[94:97]
	v_mfma_f32_16x16x32_bf16 v[90:93], v[122:125], v[204:207], v[90:93]
	v_mfma_f32_16x16x32_bf16 v[78:81], v[114:117], v[228:231], v[78:81]
	v_mfma_f32_16x16x32_bf16 v[74:77], v[122:125], v[228:231], v[74:77]
	v_mfma_f32_16x16x32_bf16 v[150:153], v[118:121], v[192:195], v[150:153]
	v_mfma_f32_16x16x32_bf16 v[146:149], v[126:129], v[192:195], v[146:149]
	v_mfma_f32_16x16x32_bf16 v[110:113], v[118:121], v[200:203], v[110:113]
	v_mfma_f32_16x16x32_bf16 v[106:109], v[126:129], v[200:203], v[106:109]
	v_mfma_f32_16x16x32_bf16 v[94:97], v[118:121], v[224:227], v[94:97]
	v_mfma_f32_16x16x32_bf16 v[90:93], v[126:129], v[224:227], v[90:93]
	v_mfma_f32_16x16x32_bf16 v[78:81], v[118:121], v[232:235], v[78:81]
	v_mfma_f32_16x16x32_bf16 v[74:77], v[126:129], v[232:235], v[74:77]
	v_mfma_f32_16x16x32_bf16 v[142:145], v[130:133], v[182:185], v[142:145]
	v_mfma_f32_16x16x32_bf16 v[138:141], v[174:177], v[182:185], v[138:141]
	v_mfma_f32_16x16x32_bf16 v[102:105], v[130:133], v[196:199], v[102:105]
	v_mfma_f32_16x16x32_bf16 v[98:101], v[174:177], v[196:199], v[98:101]
	v_mfma_f32_16x16x32_bf16 v[86:89], v[130:133], v[204:207], v[86:89]
	v_mfma_f32_16x16x32_bf16 v[82:85], v[174:177], v[204:207], v[82:85]
	v_mfma_f32_16x16x32_bf16 v[70:73], v[130:133], v[228:231], v[70:73]
	v_mfma_f32_16x16x32_bf16 v[66:69], v[174:177], v[228:231], v[66:69]
	v_mfma_f32_16x16x32_bf16 v[142:145], v[134:137], v[192:195], v[142:145]
	v_mfma_f32_16x16x32_bf16 v[138:141], v[178:181], v[192:195], v[138:141]
	v_mfma_f32_16x16x32_bf16 v[102:105], v[134:137], v[200:203], v[102:105]
	v_mfma_f32_16x16x32_bf16 v[98:101], v[178:181], v[200:203], v[98:101]
	v_mfma_f32_16x16x32_bf16 v[86:89], v[134:137], v[224:227], v[86:89]
	v_mfma_f32_16x16x32_bf16 v[82:85], v[178:181], v[224:227], v[82:85]
	v_mfma_f32_16x16x32_bf16 v[70:73], v[134:137], v[232:235], v[70:73]
	v_mfma_f32_16x16x32_bf16 v[66:69], v[178:181], v[232:235], v[66:69]
	s_setprio 0
	s_barrier
	s_add_i32 s4, s28, s13
	v_lshl_add_u64 v[186:187], v[186:187], 0, s[60:61]
	s_mov_b32 m0, s4
	ds_read_b128 v[182:185], v191 offset:49152
	ds_read_b128 v[192:195], v191 offset:50176
	ds_read_b128 v[196:199], v191 offset:51200
	ds_read_b128 v[200:203], v191 offset:52224
	ds_read_b128 v[204:207], v191 offset:53248
	ds_read_b128 v[224:227], v191 offset:54272
	ds_read_b128 v[228:231], v191 offset:55296
	ds_read_b128 v[232:235], v191 offset:56320
	global_load_lds_dwordx4 v[186:187], off
	s_add_i32 m0, s4, 0x2000
	s_add_u32 s2, s2, 0xb0080
	v_lshl_add_u64 v[186:187], v[236:237], 0, s[60:61]
	s_addc_u32 s3, s3, 0
	s_add_i32 s4, s29, s13
	global_load_lds_dwordx4 v[186:187], off
	v_lshl_add_u64 v[186:187], s[2:3], 0, v[0:1]
	s_mov_b32 m0, s4
	s_nop 0
	global_load_lds_dwordx4 v[186:187], off
	v_lshl_add_u64 v[186:187], s[2:3], 0, v[158:159]
	s_add_i32 m0, s4, 0x2000
	s_nop 0
	global_load_lds_dwordx4 v[186:187], off
	v_lshl_add_u64 v[186:187], v[238:239], 0, s[60:61]
	s_mov_b32 m0, s18
	s_nop 0
	global_load_lds_dwordx4 v[186:187], off
	v_lshl_add_u64 v[186:187], v[240:241], 0, s[60:61]
	s_mov_b32 m0, s19
	s_nop 0
	global_load_lds_dwordx4 v[186:187], off
	s_waitcnt vmcnt(8)
	s_waitcnt lgkmcnt(0)
	s_barrier
	s_setprio 1
	s_waitcnt lgkmcnt(0)
	v_mfma_f32_16x16x32_bf16 v[62:65], v[114:117], v[182:185], v[62:65]
	v_mfma_f32_16x16x32_bf16 v[58:61], v[122:125], v[182:185], v[58:61]
	v_mfma_f32_16x16x32_bf16 v[46:49], v[114:117], v[196:199], v[46:49]
	v_mfma_f32_16x16x32_bf16 v[42:45], v[122:125], v[196:199], v[42:45]
	v_mfma_f32_16x16x32_bf16 v[30:33], v[114:117], v[204:207], v[30:33]
	v_mfma_f32_16x16x32_bf16 v[26:29], v[122:125], v[204:207], v[26:29]
	v_mfma_f32_16x16x32_bf16 v[14:17], v[114:117], v[228:231], v[14:17]
	v_mfma_f32_16x16x32_bf16 v[10:13], v[122:125], v[228:231], v[10:13]
	v_mfma_f32_16x16x32_bf16 v[62:65], v[118:121], v[192:195], v[62:65]
	v_mfma_f32_16x16x32_bf16 v[58:61], v[126:129], v[192:195], v[58:61]
	v_mfma_f32_16x16x32_bf16 v[46:49], v[118:121], v[200:203], v[46:49]
	v_mfma_f32_16x16x32_bf16 v[42:45], v[126:129], v[200:203], v[42:45]
	v_mfma_f32_16x16x32_bf16 v[30:33], v[118:121], v[224:227], v[30:33]
	v_mfma_f32_16x16x32_bf16 v[26:29], v[126:129], v[224:227], v[26:29]
	v_mfma_f32_16x16x32_bf16 v[14:17], v[118:121], v[232:235], v[14:17]
	v_mfma_f32_16x16x32_bf16 v[10:13], v[126:129], v[232:235], v[10:13]
	v_mfma_f32_16x16x32_bf16 v[54:57], v[130:133], v[182:185], v[54:57]
	v_mfma_f32_16x16x32_bf16 v[50:53], v[174:177], v[182:185], v[50:53]
	v_mfma_f32_16x16x32_bf16 v[38:41], v[130:133], v[196:199], v[38:41]
	v_mfma_f32_16x16x32_bf16 v[34:37], v[174:177], v[196:199], v[34:37]
	v_mfma_f32_16x16x32_bf16 v[22:25], v[130:133], v[204:207], v[22:25]
	v_mfma_f32_16x16x32_bf16 v[18:21], v[174:177], v[204:207], v[18:21]
	v_mfma_f32_16x16x32_bf16 v[6:9], v[130:133], v[228:231], v[6:9]
	v_mfma_f32_16x16x32_bf16 v[2:5], v[174:177], v[228:231], v[2:5]
	v_mfma_f32_16x16x32_bf16 v[54:57], v[134:137], v[192:195], v[54:57]
	v_mfma_f32_16x16x32_bf16 v[50:53], v[178:181], v[192:195], v[50:53]
	v_mfma_f32_16x16x32_bf16 v[38:41], v[134:137], v[200:203], v[38:41]
	v_mfma_f32_16x16x32_bf16 v[34:37], v[178:181], v[200:203], v[34:37]
	v_mfma_f32_16x16x32_bf16 v[22:25], v[134:137], v[224:227], v[22:25]
	v_mfma_f32_16x16x32_bf16 v[18:21], v[178:181], v[224:227], v[18:21]
	v_mfma_f32_16x16x32_bf16 v[6:9], v[134:137], v[232:235], v[6:9]
	v_mfma_f32_16x16x32_bf16 v[2:5], v[178:181], v[232:235], v[2:5]
	s_setprio 0
	s_barrier
	s_add_i32 s27, s27, 2
	s_add_u32 s25, s25, 0x100
	s_addc_u32 s26, s26, 0
	s_cmp_gt_u32 s27, 41
	s_mov_b64 s[56:57], s[0:1]
	s_cbranch_scc0 .LBB0_662
	s_and_b64 vcc, exec, s[48:49]
	s_cbranch_vccz .LBB0_665
	s_barrier

.Lpws__698_0:
	s_waitcnt lgkmcnt(0)
	s_barrier
	s_setprio 1
	s_waitcnt lgkmcnt(0)
	v_mfma_f32_16x16x32_bf16 v[126:129], v[140:143], v[186:189], 0
	v_mfma_f32_16x16x32_bf16 v[122:125], v[148:151], v[186:189], 0
	v_mfma_f32_16x16x32_bf16 v[110:113], v[140:143], v[194:197], 0
	v_mfma_f32_16x16x32_bf16 v[106:109], v[148:151], v[194:197], 0
	v_mfma_f32_16x16x32_bf16 v[94:97], v[140:143], v[202:205], 0
	v_mfma_f32_16x16x32_bf16 v[90:93], v[148:151], v[202:205], 0
	v_mfma_f32_16x16x32_bf16 v[78:81], v[140:143], v[228:231], 0
	v_mfma_f32_16x16x32_bf16 v[74:77], v[148:151], v[228:231], 0
	v_mfma_f32_16x16x32_bf16 v[126:129], v[144:147], v[190:193], v[126:129]
	v_mfma_f32_16x16x32_bf16 v[122:125], v[152:155], v[190:193], v[122:125]
	v_mfma_f32_16x16x32_bf16 v[110:113], v[144:147], v[198:201], v[110:113]
	v_mfma_f32_16x16x32_bf16 v[106:109], v[152:155], v[198:201], v[106:109]
	v_mfma_f32_16x16x32_bf16 v[94:97], v[144:147], v[224:227], v[94:97]
	v_mfma_f32_16x16x32_bf16 v[90:93], v[152:155], v[224:227], v[90:93]
	v_mfma_f32_16x16x32_bf16 v[78:81], v[144:147], v[232:235], v[78:81]
	v_mfma_f32_16x16x32_bf16 v[74:77], v[152:155], v[232:235], v[74:77]
	v_mfma_f32_16x16x32_bf16 v[118:121], v[156:159], v[186:189], 0
	v_mfma_f32_16x16x32_bf16 v[114:117], v[178:181], v[186:189], 0
	v_mfma_f32_16x16x32_bf16 v[102:105], v[156:159], v[194:197], 0
	v_mfma_f32_16x16x32_bf16 v[98:101], v[178:181], v[194:197], 0
	v_mfma_f32_16x16x32_bf16 v[86:89], v[156:159], v[202:205], 0
	v_mfma_f32_16x16x32_bf16 v[82:85], v[178:181], v[202:205], 0
	v_mfma_f32_16x16x32_bf16 v[70:73], v[156:159], v[228:231], 0
	v_mfma_f32_16x16x32_bf16 v[66:69], v[178:181], v[228:231], 0
	v_mfma_f32_16x16x32_bf16 v[118:121], v[170:173], v[190:193], v[118:121]
	v_mfma_f32_16x16x32_bf16 v[114:117], v[182:185], v[190:193], v[114:117]
	v_mfma_f32_16x16x32_bf16 v[102:105], v[170:173], v[198:201], v[102:105]
	v_mfma_f32_16x16x32_bf16 v[98:101], v[182:185], v[198:201], v[98:101]
	v_mfma_f32_16x16x32_bf16 v[86:89], v[170:173], v[224:227], v[86:89]
	v_mfma_f32_16x16x32_bf16 v[82:85], v[182:185], v[224:227], v[82:85]
	v_mfma_f32_16x16x32_bf16 v[70:73], v[170:173], v[232:235], v[70:73]
	v_mfma_f32_16x16x32_bf16 v[66:69], v[182:185], v[232:235], v[66:69]
	s_setprio 0
	s_barrier
	s_add_i32 s43, s43, s10
	v_lshl_add_u64 v[206:207], s[0:1], 0, v[0:1]
	s_mov_b32 m0, s43
	ds_read_b128 v[186:189], v177 offset:16384
	ds_read_b128 v[190:193], v177 offset:17408
	ds_read_b128 v[194:197], v177 offset:18432
	ds_read_b128 v[198:201], v177 offset:19456
	ds_read_b128 v[202:205], v177 offset:20480
	ds_read_b128 v[224:227], v177 offset:21504
	ds_read_b128 v[228:231], v177 offset:22528
	ds_read_b128 v[232:235], v177 offset:23552
	global_load_lds_dwordx4 v[206:207], off
	s_add_i32 m0, s43, 0x2000
	s_add_u32 s46, s0, 0x40000
	v_lshl_add_u64 v[236:237], s[0:1], 0, v[134:135]
	s_addc_u32 s47, s1, 0
	s_add_i32 s43, s45, s10
	global_load_lds_dwordx4 v[236:237], off
	v_lshl_add_u64 v[238:239], s[46:47], 0, v[0:1]
	s_mov_b32 m0, s43
	v_lshl_add_u64 v[240:241], s[6:7], 0, v[132:133]
	global_load_lds_dwordx4 v[238:239], off
	v_lshl_add_u64 v[238:239], s[46:47], 0, v[134:135]
	s_add_i32 m0, s43, 0x2000
	s_nop 0
	global_load_lds_dwordx4 v[238:239], off
	v_lshl_add_u64 v[238:239], s[6:7], 0, v[130:131]
	s_mov_b32 m0, s13
	s_nop 0
	global_load_lds_dwordx4 v[238:239], off
	s_mov_b32 m0, s14
	s_nop 0
	global_load_lds_dwordx4 v[240:241], off
	s_cmp_lg_u32 s39, -2
	s_cbranch_scc1 .Lpwt__698_1
	s_cmp_lt_u32 s23, 2
	s_cbranch_scc0 .Lpws__698_1

.Lpws__698_1:
	s_waitcnt lgkmcnt(0)
	s_barrier
	s_setprio 1
	s_waitcnt lgkmcnt(0)
	v_mfma_f32_16x16x32_bf16 v[62:65], v[140:143], v[186:189], 0
	v_mfma_f32_16x16x32_bf16 v[58:61], v[148:151], v[186:189], 0
	v_mfma_f32_16x16x32_bf16 v[46:49], v[140:143], v[194:197], 0
	v_mfma_f32_16x16x32_bf16 v[42:45], v[148:151], v[194:197], 0
	v_mfma_f32_16x16x32_bf16 v[30:33], v[140:143], v[202:205], 0
	v_mfma_f32_16x16x32_bf16 v[26:29], v[148:151], v[202:205], 0
	v_mfma_f32_16x16x32_bf16 v[14:17], v[140:143], v[228:231], 0
	v_mfma_f32_16x16x32_bf16 v[10:13], v[148:151], v[228:231], 0
	v_mfma_f32_16x16x32_bf16 v[62:65], v[144:147], v[190:193], v[62:65]
	v_mfma_f32_16x16x32_bf16 v[58:61], v[152:155], v[190:193], v[58:61]
	v_mfma_f32_16x16x32_bf16 v[46:49], v[144:147], v[198:201], v[46:49]
	v_mfma_f32_16x16x32_bf16 v[42:45], v[152:155], v[198:201], v[42:45]
	v_mfma_f32_16x16x32_bf16 v[30:33], v[144:147], v[224:227], v[30:33]
	v_mfma_f32_16x16x32_bf16 v[26:29], v[152:155], v[224:227], v[26:29]
	v_mfma_f32_16x16x32_bf16 v[14:17], v[144:147], v[232:235], v[14:17]
	v_mfma_f32_16x16x32_bf16 v[10:13], v[152:155], v[232:235], v[10:13]
	v_mfma_f32_16x16x32_bf16 v[54:57], v[156:159], v[186:189], 0
	v_mfma_f32_16x16x32_bf16 v[50:53], v[178:181], v[186:189], 0
	v_mfma_f32_16x16x32_bf16 v[38:41], v[156:159], v[194:197], 0
	v_mfma_f32_16x16x32_bf16 v[34:37], v[178:181], v[194:197], 0
	v_mfma_f32_16x16x32_bf16 v[22:25], v[156:159], v[202:205], 0
	v_mfma_f32_16x16x32_bf16 v[18:21], v[178:181], v[202:205], 0
	v_mfma_f32_16x16x32_bf16 v[6:9], v[156:159], v[228:231], 0
	v_mfma_f32_16x16x32_bf16 v[2:5], v[178:181], v[228:231], 0
	v_mfma_f32_16x16x32_bf16 v[54:57], v[170:173], v[190:193], v[54:57]
	v_mfma_f32_16x16x32_bf16 v[50:53], v[182:185], v[190:193], v[50:53]
	v_mfma_f32_16x16x32_bf16 v[38:41], v[170:173], v[198:201], v[38:41]
	v_mfma_f32_16x16x32_bf16 v[34:37], v[182:185], v[198:201], v[34:37]
	v_mfma_f32_16x16x32_bf16 v[22:25], v[170:173], v[224:227], v[22:25]
	v_mfma_f32_16x16x32_bf16 v[18:21], v[182:185], v[224:227], v[18:21]
	v_mfma_f32_16x16x32_bf16 v[6:9], v[170:173], v[232:235], v[6:9]
	v_mfma_f32_16x16x32_bf16 v[2:5], v[182:185], v[232:235], v[2:5]
	s_setprio 0
	s_barrier
	s_add_i32 s43, 0, 0x18000
	s_add_i32 s45, 0, 0x1c000
	v_add_u32_e32 v152, s43, v175
	v_add_u32_e32 v182, s45, v175
	ds_read_b128 v[140:143], v152
	ds_read_b128 v[144:147], v152 offset:1024
	ds_read_b128 v[148:151], v152 offset:2048
	ds_read_b128 v[152:155], v152 offset:3072
	ds_read_b128 v[156:159], v182
	ds_read_b128 v[170:173], v182 offset:1024
	ds_read_b128 v[178:181], v182 offset:2048
	ds_read_b128 v[182:185], v182 offset:3072
	s_add_u32 s6, s6, 0x40000
	s_addc_u32 s7, s7, 0
	s_mov_b32 m0, s15
	v_lshl_add_u64 v[242:243], s[6:7], 0, v[130:131]
	ds_read_b128 v[186:189], v177 offset:32768
	ds_read_b128 v[190:193], v177 offset:33792
	ds_read_b128 v[194:197], v177 offset:34816
	ds_read_b128 v[198:201], v177 offset:35840
	ds_read_b128 v[202:205], v177 offset:36864
	ds_read_b128 v[224:227], v177 offset:37888
	ds_read_b128 v[228:231], v177 offset:38912
	ds_read_b128 v[232:235], v177 offset:39936
	global_load_lds_dwordx4 v[242:243], off
	v_lshl_add_u64 v[242:243], s[6:7], 0, v[132:133]
	s_mov_b32 m0, s16
	s_nop 0
	global_load_lds_dwordx4 v[242:243], off
	s_waitcnt vmcnt(8)
	s_waitcnt lgkmcnt(0)
	s_barrier
	s_setprio 1
	s_waitcnt lgkmcnt(0)
	v_mfma_f32_16x16x32_bf16 v[126:129], v[140:143], v[186:189], v[126:129]
	v_mfma_f32_16x16x32_bf16 v[122:125], v[148:151], v[186:189], v[122:125]
	v_mfma_f32_16x16x32_bf16 v[110:113], v[140:143], v[194:197], v[110:113]
	v_mfma_f32_16x16x32_bf16 v[106:109], v[148:151], v[194:197], v[106:109]
	v_mfma_f32_16x16x32_bf16 v[94:97], v[140:143], v[202:205], v[94:97]
	v_mfma_f32_16x16x32_bf16 v[90:93], v[148:151], v[202:205], v[90:93]
	v_mfma_f32_16x16x32_bf16 v[78:81], v[140:143], v[228:231], v[78:81]
	v_mfma_f32_16x16x32_bf16 v[74:77], v[148:151], v[228:231], v[74:77]
	v_mfma_f32_16x16x32_bf16 v[126:129], v[144:147], v[190:193], v[126:129]
	v_mfma_f32_16x16x32_bf16 v[122:125], v[152:155], v[190:193], v[122:125]
	v_mfma_f32_16x16x32_bf16 v[110:113], v[144:147], v[198:201], v[110:113]
	v_mfma_f32_16x16x32_bf16 v[106:109], v[152:155], v[198:201], v[106:109]
	v_mfma_f32_16x16x32_bf16 v[94:97], v[144:147], v[224:227], v[94:97]
	v_mfma_f32_16x16x32_bf16 v[90:93], v[152:155], v[224:227], v[90:93]
	v_mfma_f32_16x16x32_bf16 v[78:81], v[144:147], v[232:235], v[78:81]
	v_mfma_f32_16x16x32_bf16 v[74:77], v[152:155], v[232:235], v[74:77]
	v_mfma_f32_16x16x32_bf16 v[118:121], v[156:159], v[186:189], v[118:121]
	v_mfma_f32_16x16x32_bf16 v[114:117], v[178:181], v[186:189], v[114:117]
	v_mfma_f32_16x16x32_bf16 v[102:105], v[156:159], v[194:197], v[102:105]
	v_mfma_f32_16x16x32_bf16 v[98:101], v[178:181], v[194:197], v[98:101]
	v_mfma_f32_16x16x32_bf16 v[86:89], v[156:159], v[202:205], v[86:89]
	v_mfma_f32_16x16x32_bf16 v[82:85], v[178:181], v[202:205], v[82:85]
	v_mfma_f32_16x16x32_bf16 v[70:73], v[156:159], v[228:231], v[70:73]
	v_mfma_f32_16x16x32_bf16 v[66:69], v[178:181], v[228:231], v[66:69]
	v_mfma_f32_16x16x32_bf16 v[118:121], v[170:173], v[190:193], v[118:121]
	v_mfma_f32_16x16x32_bf16 v[114:117], v[182:185], v[190:193], v[114:117]
	v_mfma_f32_16x16x32_bf16 v[102:105], v[170:173], v[198:201], v[102:105]
	v_mfma_f32_16x16x32_bf16 v[98:101], v[182:185], v[198:201], v[98:101]
	v_mfma_f32_16x16x32_bf16 v[86:89], v[170:173], v[224:227], v[86:89]
	v_mfma_f32_16x16x32_bf16 v[82:85], v[182:185], v[224:227], v[82:85]
	v_mfma_f32_16x16x32_bf16 v[70:73], v[170:173], v[232:235], v[70:73]
	v_mfma_f32_16x16x32_bf16 v[66:69], v[182:185], v[232:235], v[66:69]
	s_setprio 0
	s_barrier
	s_add_i32 s6, s43, s10
	v_lshl_add_u64 v[206:207], v[206:207], 0, s[60:61]
	s_mov_b32 m0, s6
	ds_read_b128 v[186:189], v177 offset:49152
	ds_read_b128 v[190:193], v177 offset:50176
	ds_read_b128 v[194:197], v177 offset:51200
	ds_read_b128 v[198:201], v177 offset:52224
	ds_read_b128 v[202:205], v177 offset:53248
	ds_read_b128 v[224:227], v177 offset:54272
	ds_read_b128 v[228:231], v177 offset:55296
	ds_read_b128 v[232:235], v177 offset:56320
	global_load_lds_dwordx4 v[206:207], off
	s_add_i32 m0, s6, 0x2000
	s_add_u32 s0, s0, 0x40080
	v_lshl_add_u64 v[206:207], v[236:237], 0, s[60:61]
	s_addc_u32 s1, s1, 0
	s_add_i32 s6, s45, s10
	global_load_lds_dwordx4 v[206:207], off
	v_lshl_add_u64 v[206:207], s[0:1], 0, v[0:1]
	s_mov_b32 m0, s6
	s_nop 0
	global_load_lds_dwordx4 v[206:207], off
	v_lshl_add_u64 v[206:207], s[0:1], 0, v[134:135]
	s_add_i32 m0, s6, 0x2000
	s_nop 0
	global_load_lds_dwordx4 v[206:207], off
	v_lshl_add_u64 v[206:207], v[238:239], 0, s[60:61]
	s_mov_b32 m0, s19
	s_nop 0
	global_load_lds_dwordx4 v[206:207], off
	v_lshl_add_u64 v[206:207], v[240:241], 0, s[60:61]
	s_mov_b32 m0, s20
	s_nop 0
	global_load_lds_dwordx4 v[206:207], off
	s_waitcnt vmcnt(8)
	s_waitcnt lgkmcnt(0)
	s_barrier
	s_setprio 1
	s_waitcnt lgkmcnt(0)
	v_mfma_f32_16x16x32_bf16 v[62:65], v[140:143], v[186:189], v[62:65]
	v_mfma_f32_16x16x32_bf16 v[58:61], v[148:151], v[186:189], v[58:61]
	v_mfma_f32_16x16x32_bf16 v[46:49], v[140:143], v[194:197], v[46:49]
	v_mfma_f32_16x16x32_bf16 v[42:45], v[148:151], v[194:197], v[42:45]
	v_mfma_f32_16x16x32_bf16 v[30:33], v[140:143], v[202:205], v[30:33]
	v_mfma_f32_16x16x32_bf16 v[26:29], v[148:151], v[202:205], v[26:29]
	v_mfma_f32_16x16x32_bf16 v[14:17], v[140:143], v[228:231], v[14:17]
	v_mfma_f32_16x16x32_bf16 v[10:13], v[148:151], v[228:231], v[10:13]
	v_mfma_f32_16x16x32_bf16 v[62:65], v[144:147], v[190:193], v[62:65]
	v_mfma_f32_16x16x32_bf16 v[58:61], v[152:155], v[190:193], v[58:61]
	v_mfma_f32_16x16x32_bf16 v[46:49], v[144:147], v[198:201], v[46:49]
	v_mfma_f32_16x16x32_bf16 v[42:45], v[152:155], v[198:201], v[42:45]
	v_mfma_f32_16x16x32_bf16 v[30:33], v[144:147], v[224:227], v[30:33]
	v_mfma_f32_16x16x32_bf16 v[26:29], v[152:155], v[224:227], v[26:29]
	v_mfma_f32_16x16x32_bf16 v[14:17], v[144:147], v[232:235], v[14:17]
	v_mfma_f32_16x16x32_bf16 v[10:13], v[152:155], v[232:235], v[10:13]
	v_mfma_f32_16x16x32_bf16 v[54:57], v[156:159], v[186:189], v[54:57]
	v_mfma_f32_16x16x32_bf16 v[50:53], v[178:181], v[186:189], v[50:53]
	v_mfma_f32_16x16x32_bf16 v[38:41], v[156:159], v[194:197], v[38:41]
	v_mfma_f32_16x16x32_bf16 v[34:37], v[178:181], v[194:197], v[34:37]
	v_mfma_f32_16x16x32_bf16 v[22:25], v[156:159], v[202:205], v[22:25]
	v_mfma_f32_16x16x32_bf16 v[18:21], v[178:181], v[202:205], v[18:21]
	v_mfma_f32_16x16x32_bf16 v[6:9], v[156:159], v[228:231], v[6:9]
	v_mfma_f32_16x16x32_bf16 v[2:5], v[178:181], v[228:231], v[2:5]
	v_mfma_f32_16x16x32_bf16 v[54:57], v[170:173], v[190:193], v[54:57]
	v_mfma_f32_16x16x32_bf16 v[50:53], v[182:185], v[190:193], v[50:53]
	v_mfma_f32_16x16x32_bf16 v[38:41], v[170:173], v[198:201], v[38:41]
	v_mfma_f32_16x16x32_bf16 v[34:37], v[182:185], v[198:201], v[34:37]
	v_mfma_f32_16x16x32_bf16 v[22:25], v[170:173], v[224:227], v[22:25]
	v_mfma_f32_16x16x32_bf16 v[18:21], v[182:185], v[224:227], v[18:21]
	v_mfma_f32_16x16x32_bf16 v[6:9], v[170:173], v[232:235], v[6:9]
	v_mfma_f32_16x16x32_bf16 v[2:5], v[182:185], v[232:235], v[2:5]
	s_setprio 0
	s_barrier
	s_add_i32 s39, s39, 2
	s_add_u32 s56, s56, 0x100
	s_addc_u32 s57, s57, 0
	s_add_u32 s34, s34, 0x100
	s_addc_u32 s35, s35, 0
	s_cmp_gt_u32 s39, 13

.Lws__698_0:
	s_waitcnt lgkmcnt(0)
	s_barrier
	s_setprio 1
	s_waitcnt lgkmcnt(0)
	v_mfma_f32_16x16x32_bf16 v[126:129], v[140:143], v[186:189], v[126:129]
	v_mfma_f32_16x16x32_bf16 v[122:125], v[148:151], v[186:189], v[122:125]
	v_mfma_f32_16x16x32_bf16 v[110:113], v[140:143], v[194:197], v[110:113]
	v_mfma_f32_16x16x32_bf16 v[106:109], v[148:151], v[194:197], v[106:109]
	v_mfma_f32_16x16x32_bf16 v[94:97], v[140:143], v[202:205], v[94:97]
	v_mfma_f32_16x16x32_bf16 v[90:93], v[148:151], v[202:205], v[90:93]
	v_mfma_f32_16x16x32_bf16 v[78:81], v[140:143], v[228:231], v[78:81]
	v_mfma_f32_16x16x32_bf16 v[74:77], v[148:151], v[228:231], v[74:77]
	v_mfma_f32_16x16x32_bf16 v[126:129], v[144:147], v[190:193], v[126:129]
	v_mfma_f32_16x16x32_bf16 v[122:125], v[152:155], v[190:193], v[122:125]
	v_mfma_f32_16x16x32_bf16 v[110:113], v[144:147], v[198:201], v[110:113]
	v_mfma_f32_16x16x32_bf16 v[106:109], v[152:155], v[198:201], v[106:109]
	v_mfma_f32_16x16x32_bf16 v[94:97], v[144:147], v[224:227], v[94:97]
	v_mfma_f32_16x16x32_bf16 v[90:93], v[152:155], v[224:227], v[90:93]
	v_mfma_f32_16x16x32_bf16 v[78:81], v[144:147], v[232:235], v[78:81]
	v_mfma_f32_16x16x32_bf16 v[74:77], v[152:155], v[232:235], v[74:77]
	v_mfma_f32_16x16x32_bf16 v[118:121], v[156:159], v[186:189], v[118:121]
	v_mfma_f32_16x16x32_bf16 v[114:117], v[178:181], v[186:189], v[114:117]
	v_mfma_f32_16x16x32_bf16 v[102:105], v[156:159], v[194:197], v[102:105]
	v_mfma_f32_16x16x32_bf16 v[98:101], v[178:181], v[194:197], v[98:101]
	v_mfma_f32_16x16x32_bf16 v[86:89], v[156:159], v[202:205], v[86:89]
	v_mfma_f32_16x16x32_bf16 v[82:85], v[178:181], v[202:205], v[82:85]
	v_mfma_f32_16x16x32_bf16 v[70:73], v[156:159], v[228:231], v[70:73]
	v_mfma_f32_16x16x32_bf16 v[66:69], v[178:181], v[228:231], v[66:69]
	v_mfma_f32_16x16x32_bf16 v[118:121], v[170:173], v[190:193], v[118:121]
	v_mfma_f32_16x16x32_bf16 v[114:117], v[182:185], v[190:193], v[114:117]
	v_mfma_f32_16x16x32_bf16 v[102:105], v[170:173], v[198:201], v[102:105]
	v_mfma_f32_16x16x32_bf16 v[98:101], v[182:185], v[198:201], v[98:101]
	v_mfma_f32_16x16x32_bf16 v[86:89], v[170:173], v[224:227], v[86:89]
	v_mfma_f32_16x16x32_bf16 v[82:85], v[182:185], v[224:227], v[82:85]
	v_mfma_f32_16x16x32_bf16 v[70:73], v[170:173], v[232:235], v[70:73]
	v_mfma_f32_16x16x32_bf16 v[66:69], v[182:185], v[232:235], v[66:69]
	s_setprio 0
	s_barrier
	s_add_i32 s43, s43, s10
	v_lshl_add_u64 v[206:207], s[0:1], 0, v[0:1]
	s_mov_b32 m0, s43
	ds_read_b128 v[186:189], v177 offset:16384
	ds_read_b128 v[190:193], v177 offset:17408
	ds_read_b128 v[194:197], v177 offset:18432
	ds_read_b128 v[198:201], v177 offset:19456
	ds_read_b128 v[202:205], v177 offset:20480
	ds_read_b128 v[224:227], v177 offset:21504
	ds_read_b128 v[228:231], v177 offset:22528
	ds_read_b128 v[232:235], v177 offset:23552
	global_load_lds_dwordx4 v[206:207], off
	s_add_i32 m0, s43, 0x2000
	s_add_u32 s46, s0, 0x40000
	v_lshl_add_u64 v[236:237], s[0:1], 0, v[134:135]
	s_addc_u32 s47, s1, 0
	s_add_i32 s43, s45, s10
	global_load_lds_dwordx4 v[236:237], off
	v_lshl_add_u64 v[238:239], s[46:47], 0, v[0:1]
	s_mov_b32 m0, s43
	v_lshl_add_u64 v[240:241], s[6:7], 0, v[132:133]
	global_load_lds_dwordx4 v[238:239], off
	v_lshl_add_u64 v[238:239], s[46:47], 0, v[134:135]
	s_add_i32 m0, s43, 0x2000
	s_nop 0
	global_load_lds_dwordx4 v[238:239], off
	v_lshl_add_u64 v[238:239], s[6:7], 0, v[130:131]
	s_mov_b32 m0, s13
	s_nop 0
	global_load_lds_dwordx4 v[238:239], off
	s_mov_b32 m0, s14
	s_nop 0
	global_load_lds_dwordx4 v[240:241], off
	s_cmp_lg_u32 s39, -2
	s_cbranch_scc1 .Lwt__698_1
	s_cmp_lt_u32 s23, 2
	s_cbranch_scc0 .Lws__698_1

.Lws__698_1:
	s_waitcnt lgkmcnt(0)
	s_barrier
	s_setprio 1
	s_waitcnt lgkmcnt(0)
	v_mfma_f32_16x16x32_bf16 v[62:65], v[140:143], v[186:189], v[62:65]
	v_mfma_f32_16x16x32_bf16 v[58:61], v[148:151], v[186:189], v[58:61]
	v_mfma_f32_16x16x32_bf16 v[46:49], v[140:143], v[194:197], v[46:49]
	v_mfma_f32_16x16x32_bf16 v[42:45], v[148:151], v[194:197], v[42:45]
	v_mfma_f32_16x16x32_bf16 v[30:33], v[140:143], v[202:205], v[30:33]
	v_mfma_f32_16x16x32_bf16 v[26:29], v[148:151], v[202:205], v[26:29]
	v_mfma_f32_16x16x32_bf16 v[14:17], v[140:143], v[228:231], v[14:17]
	v_mfma_f32_16x16x32_bf16 v[10:13], v[148:151], v[228:231], v[10:13]
	v_mfma_f32_16x16x32_bf16 v[62:65], v[144:147], v[190:193], v[62:65]
	v_mfma_f32_16x16x32_bf16 v[58:61], v[152:155], v[190:193], v[58:61]
	v_mfma_f32_16x16x32_bf16 v[46:49], v[144:147], v[198:201], v[46:49]
	v_mfma_f32_16x16x32_bf16 v[42:45], v[152:155], v[198:201], v[42:45]
	v_mfma_f32_16x16x32_bf16 v[30:33], v[144:147], v[224:227], v[30:33]
	v_mfma_f32_16x16x32_bf16 v[26:29], v[152:155], v[224:227], v[26:29]
	v_mfma_f32_16x16x32_bf16 v[14:17], v[144:147], v[232:235], v[14:17]
	v_mfma_f32_16x16x32_bf16 v[10:13], v[152:155], v[232:235], v[10:13]
	v_mfma_f32_16x16x32_bf16 v[54:57], v[156:159], v[186:189], v[54:57]
	v_mfma_f32_16x16x32_bf16 v[50:53], v[178:181], v[186:189], v[50:53]
	v_mfma_f32_16x16x32_bf16 v[38:41], v[156:159], v[194:197], v[38:41]
	v_mfma_f32_16x16x32_bf16 v[34:37], v[178:181], v[194:197], v[34:37]
	v_mfma_f32_16x16x32_bf16 v[22:25], v[156:159], v[202:205], v[22:25]
	v_mfma_f32_16x16x32_bf16 v[18:21], v[178:181], v[202:205], v[18:21]
	v_mfma_f32_16x16x32_bf16 v[6:9], v[156:159], v[228:231], v[6:9]
	v_mfma_f32_16x16x32_bf16 v[2:5], v[178:181], v[228:231], v[2:5]
	v_mfma_f32_16x16x32_bf16 v[54:57], v[170:173], v[190:193], v[54:57]
	v_mfma_f32_16x16x32_bf16 v[50:53], v[182:185], v[190:193], v[50:53]
	v_mfma_f32_16x16x32_bf16 v[38:41], v[170:173], v[198:201], v[38:41]
	v_mfma_f32_16x16x32_bf16 v[34:37], v[182:185], v[198:201], v[34:37]
	v_mfma_f32_16x16x32_bf16 v[22:25], v[170:173], v[224:227], v[22:25]
	v_mfma_f32_16x16x32_bf16 v[18:21], v[182:185], v[224:227], v[18:21]
	v_mfma_f32_16x16x32_bf16 v[6:9], v[170:173], v[232:235], v[6:9]
	v_mfma_f32_16x16x32_bf16 v[2:5], v[182:185], v[232:235], v[2:5]
	s_setprio 0
	s_barrier
	s_add_i32 s43, 0, 0x18000
	s_add_i32 s45, 0, 0x1c000
	v_add_u32_e32 v152, s43, v175
	v_add_u32_e32 v182, s45, v175
	ds_read_b128 v[140:143], v152
	ds_read_b128 v[144:147], v152 offset:1024
	ds_read_b128 v[148:151], v152 offset:2048
	ds_read_b128 v[152:155], v152 offset:3072
	ds_read_b128 v[156:159], v182
	ds_read_b128 v[170:173], v182 offset:1024
	ds_read_b128 v[178:181], v182 offset:2048
	ds_read_b128 v[182:185], v182 offset:3072
	s_add_u32 s6, s6, 0x40000
	s_addc_u32 s7, s7, 0
	s_mov_b32 m0, s15
	v_lshl_add_u64 v[242:243], s[6:7], 0, v[130:131]
	ds_read_b128 v[186:189], v177 offset:32768
	ds_read_b128 v[190:193], v177 offset:33792
	ds_read_b128 v[194:197], v177 offset:34816
	ds_read_b128 v[198:201], v177 offset:35840
	ds_read_b128 v[202:205], v177 offset:36864
	ds_read_b128 v[224:227], v177 offset:37888
	ds_read_b128 v[228:231], v177 offset:38912
	ds_read_b128 v[232:235], v177 offset:39936
	global_load_lds_dwordx4 v[242:243], off
	v_lshl_add_u64 v[242:243], s[6:7], 0, v[132:133]
	s_mov_b32 m0, s16
	s_nop 0
	global_load_lds_dwordx4 v[242:243], off
	s_waitcnt vmcnt(8)
	s_waitcnt lgkmcnt(0)
	s_barrier
	s_setprio 1
	s_waitcnt lgkmcnt(0)
	v_mfma_f32_16x16x32_bf16 v[126:129], v[140:143], v[186:189], v[126:129]
	v_mfma_f32_16x16x32_bf16 v[122:125], v[148:151], v[186:189], v[122:125]
	v_mfma_f32_16x16x32_bf16 v[110:113], v[140:143], v[194:197], v[110:113]
	v_mfma_f32_16x16x32_bf16 v[106:109], v[148:151], v[194:197], v[106:109]
	v_mfma_f32_16x16x32_bf16 v[94:97], v[140:143], v[202:205], v[94:97]
	v_mfma_f32_16x16x32_bf16 v[90:93], v[148:151], v[202:205], v[90:93]
	v_mfma_f32_16x16x32_bf16 v[78:81], v[140:143], v[228:231], v[78:81]
	v_mfma_f32_16x16x32_bf16 v[74:77], v[148:151], v[228:231], v[74:77]
	v_mfma_f32_16x16x32_bf16 v[126:129], v[144:147], v[190:193], v[126:129]
	v_mfma_f32_16x16x32_bf16 v[122:125], v[152:155], v[190:193], v[122:125]
	v_mfma_f32_16x16x32_bf16 v[110:113], v[144:147], v[198:201], v[110:113]
	v_mfma_f32_16x16x32_bf16 v[106:109], v[152:155], v[198:201], v[106:109]
	v_mfma_f32_16x16x32_bf16 v[94:97], v[144:147], v[224:227], v[94:97]
	v_mfma_f32_16x16x32_bf16 v[90:93], v[152:155], v[224:227], v[90:93]
	v_mfma_f32_16x16x32_bf16 v[78:81], v[144:147], v[232:235], v[78:81]
	v_mfma_f32_16x16x32_bf16 v[74:77], v[152:155], v[232:235], v[74:77]
	v_mfma_f32_16x16x32_bf16 v[118:121], v[156:159], v[186:189], v[118:121]
	v_mfma_f32_16x16x32_bf16 v[114:117], v[178:181], v[186:189], v[114:117]
	v_mfma_f32_16x16x32_bf16 v[102:105], v[156:159], v[194:197], v[102:105]
	v_mfma_f32_16x16x32_bf16 v[98:101], v[178:181], v[194:197], v[98:101]
	v_mfma_f32_16x16x32_bf16 v[86:89], v[156:159], v[202:205], v[86:89]
	v_mfma_f32_16x16x32_bf16 v[82:85], v[178:181], v[202:205], v[82:85]
	v_mfma_f32_16x16x32_bf16 v[70:73], v[156:159], v[228:231], v[70:73]
	v_mfma_f32_16x16x32_bf16 v[66:69], v[178:181], v[228:231], v[66:69]
	v_mfma_f32_16x16x32_bf16 v[118:121], v[170:173], v[190:193], v[118:121]
	v_mfma_f32_16x16x32_bf16 v[114:117], v[182:185], v[190:193], v[114:117]
	v_mfma_f32_16x16x32_bf16 v[102:105], v[170:173], v[198:201], v[102:105]
	v_mfma_f32_16x16x32_bf16 v[98:101], v[182:185], v[198:201], v[98:101]
	v_mfma_f32_16x16x32_bf16 v[86:89], v[170:173], v[224:227], v[86:89]
	v_mfma_f32_16x16x32_bf16 v[82:85], v[182:185], v[224:227], v[82:85]
	v_mfma_f32_16x16x32_bf16 v[70:73], v[170:173], v[232:235], v[70:73]
	v_mfma_f32_16x16x32_bf16 v[66:69], v[182:185], v[232:235], v[66:69]
	s_setprio 0
	s_barrier
	s_add_i32 s6, s43, s10
	v_lshl_add_u64 v[206:207], v[206:207], 0, s[60:61]
	s_mov_b32 m0, s6
	ds_read_b128 v[186:189], v177 offset:49152
	ds_read_b128 v[190:193], v177 offset:50176
	ds_read_b128 v[194:197], v177 offset:51200
	ds_read_b128 v[198:201], v177 offset:52224
	ds_read_b128 v[202:205], v177 offset:53248
	ds_read_b128 v[224:227], v177 offset:54272
	ds_read_b128 v[228:231], v177 offset:55296
	ds_read_b128 v[232:235], v177 offset:56320
	global_load_lds_dwordx4 v[206:207], off
	s_add_i32 m0, s6, 0x2000
	s_add_u32 s0, s0, 0x40080
	v_lshl_add_u64 v[206:207], v[236:237], 0, s[60:61]
	s_addc_u32 s1, s1, 0
	s_add_i32 s6, s45, s10
	global_load_lds_dwordx4 v[206:207], off
	v_lshl_add_u64 v[206:207], s[0:1], 0, v[0:1]
	s_mov_b32 m0, s6
	s_nop 0
	global_load_lds_dwordx4 v[206:207], off
	v_lshl_add_u64 v[206:207], s[0:1], 0, v[134:135]
	s_add_i32 m0, s6, 0x2000
	s_nop 0
	global_load_lds_dwordx4 v[206:207], off
	v_lshl_add_u64 v[206:207], v[238:239], 0, s[60:61]
	s_mov_b32 m0, s19
	s_nop 0
	global_load_lds_dwordx4 v[206:207], off
	v_lshl_add_u64 v[206:207], v[240:241], 0, s[60:61]
	s_mov_b32 m0, s20
	s_nop 0
	global_load_lds_dwordx4 v[206:207], off
	s_waitcnt vmcnt(8)
	s_waitcnt lgkmcnt(0)
	s_barrier
	s_setprio 1
	s_waitcnt lgkmcnt(0)
	v_mfma_f32_16x16x32_bf16 v[62:65], v[140:143], v[186:189], v[62:65]
	v_mfma_f32_16x16x32_bf16 v[58:61], v[148:151], v[186:189], v[58:61]
	v_mfma_f32_16x16x32_bf16 v[46:49], v[140:143], v[194:197], v[46:49]
	v_mfma_f32_16x16x32_bf16 v[42:45], v[148:151], v[194:197], v[42:45]
	v_mfma_f32_16x16x32_bf16 v[30:33], v[140:143], v[202:205], v[30:33]
	v_mfma_f32_16x16x32_bf16 v[26:29], v[148:151], v[202:205], v[26:29]
	v_mfma_f32_16x16x32_bf16 v[14:17], v[140:143], v[228:231], v[14:17]
	v_mfma_f32_16x16x32_bf16 v[10:13], v[148:151], v[228:231], v[10:13]
	v_mfma_f32_16x16x32_bf16 v[62:65], v[144:147], v[190:193], v[62:65]
	v_mfma_f32_16x16x32_bf16 v[58:61], v[152:155], v[190:193], v[58:61]
	v_mfma_f32_16x16x32_bf16 v[46:49], v[144:147], v[198:201], v[46:49]
	v_mfma_f32_16x16x32_bf16 v[42:45], v[152:155], v[198:201], v[42:45]
	v_mfma_f32_16x16x32_bf16 v[30:33], v[144:147], v[224:227], v[30:33]
	v_mfma_f32_16x16x32_bf16 v[26:29], v[152:155], v[224:227], v[26:29]
	v_mfma_f32_16x16x32_bf16 v[14:17], v[144:147], v[232:235], v[14:17]
	v_mfma_f32_16x16x32_bf16 v[10:13], v[152:155], v[232:235], v[10:13]
	v_mfma_f32_16x16x32_bf16 v[54:57], v[156:159], v[186:189], v[54:57]
	v_mfma_f32_16x16x32_bf16 v[50:53], v[178:181], v[186:189], v[50:53]
	v_mfma_f32_16x16x32_bf16 v[38:41], v[156:159], v[194:197], v[38:41]
	v_mfma_f32_16x16x32_bf16 v[34:37], v[178:181], v[194:197], v[34:37]
	v_mfma_f32_16x16x32_bf16 v[22:25], v[156:159], v[202:205], v[22:25]
	v_mfma_f32_16x16x32_bf16 v[18:21], v[178:181], v[202:205], v[18:21]
	v_mfma_f32_16x16x32_bf16 v[6:9], v[156:159], v[228:231], v[6:9]
	v_mfma_f32_16x16x32_bf16 v[2:5], v[178:181], v[228:231], v[2:5]
	v_mfma_f32_16x16x32_bf16 v[54:57], v[170:173], v[190:193], v[54:57]
	v_mfma_f32_16x16x32_bf16 v[50:53], v[182:185], v[190:193], v[50:53]
	v_mfma_f32_16x16x32_bf16 v[38:41], v[170:173], v[198:201], v[38:41]
	v_mfma_f32_16x16x32_bf16 v[34:37], v[182:185], v[198:201], v[34:37]
	v_mfma_f32_16x16x32_bf16 v[22:25], v[170:173], v[224:227], v[22:25]
	v_mfma_f32_16x16x32_bf16 v[18:21], v[182:185], v[224:227], v[18:21]
	v_mfma_f32_16x16x32_bf16 v[6:9], v[170:173], v[232:235], v[6:9]
	v_mfma_f32_16x16x32_bf16 v[2:5], v[182:185], v[232:235], v[2:5]
	s_setprio 0
	s_barrier
	s_add_i32 s39, s39, 2
	s_add_u32 s56, s56, 0x100
	s_addc_u32 s57, s57, 0
	s_add_u32 s34, s34, 0x100
	s_addc_u32 s35, s35, 0
	s_cmp_gt_u32 s39, 13
	s_cbranch_scc0 .LBB0_698
	s_and_b64 vcc, exec, s[36:37]
	s_cbranch_vccz .LBB0_701
	s_barrier

.Lpws__778_0:
	s_waitcnt lgkmcnt(0)
	s_barrier
	s_setprio 1
	s_waitcnt lgkmcnt(0)
	v_mfma_f32_16x16x32_bf16 v[126:129], v[130:133], v[186:189], 0
	v_mfma_f32_16x16x32_bf16 v[122:125], v[138:141], v[186:189], 0
	v_mfma_f32_16x16x32_bf16 v[114:117], v[130:133], v[194:197], 0
	v_mfma_f32_16x16x32_bf16 v[106:109], v[138:141], v[194:197], 0
	v_mfma_f32_16x16x32_bf16 v[98:101], v[130:133], v[202:205], 0
	v_mfma_f32_16x16x32_bf16 v[90:93], v[138:141], v[202:205], 0
	v_mfma_f32_16x16x32_bf16 v[82:85], v[130:133], v[228:231], 0
	v_mfma_f32_16x16x32_bf16 v[74:77], v[138:141], v[228:231], 0
	v_mfma_f32_16x16x32_bf16 v[126:129], v[134:137], v[190:193], v[126:129]
	v_mfma_f32_16x16x32_bf16 v[122:125], v[142:145], v[190:193], v[122:125]
	v_mfma_f32_16x16x32_bf16 v[114:117], v[134:137], v[198:201], v[114:117]
	v_mfma_f32_16x16x32_bf16 v[106:109], v[142:145], v[198:201], v[106:109]
	v_mfma_f32_16x16x32_bf16 v[98:101], v[134:137], v[224:227], v[98:101]
	v_mfma_f32_16x16x32_bf16 v[90:93], v[142:145], v[224:227], v[90:93]
	v_mfma_f32_16x16x32_bf16 v[82:85], v[134:137], v[232:235], v[82:85]
	v_mfma_f32_16x16x32_bf16 v[74:77], v[142:145], v[232:235], v[74:77]
	v_mfma_f32_16x16x32_bf16 v[118:121], v[156:159], v[186:189], 0
	v_mfma_f32_16x16x32_bf16 v[110:113], v[174:177], v[186:189], 0
	v_mfma_f32_16x16x32_bf16 v[102:105], v[156:159], v[194:197], 0
	v_mfma_f32_16x16x32_bf16 v[94:97], v[174:177], v[194:197], 0
	v_mfma_f32_16x16x32_bf16 v[86:89], v[156:159], v[202:205], 0
	v_mfma_f32_16x16x32_bf16 v[78:81], v[174:177], v[202:205], 0
	v_mfma_f32_16x16x32_bf16 v[70:73], v[156:159], v[228:231], 0
	v_mfma_f32_16x16x32_bf16 v[66:69], v[174:177], v[228:231], 0
	v_mfma_f32_16x16x32_bf16 v[118:121], v[170:173], v[190:193], v[118:121]
	v_mfma_f32_16x16x32_bf16 v[110:113], v[182:185], v[190:193], v[110:113]
	v_mfma_f32_16x16x32_bf16 v[102:105], v[170:173], v[198:201], v[102:105]
	v_mfma_f32_16x16x32_bf16 v[94:97], v[182:185], v[198:201], v[94:97]
	v_mfma_f32_16x16x32_bf16 v[86:89], v[170:173], v[224:227], v[86:89]
	v_mfma_f32_16x16x32_bf16 v[78:81], v[182:185], v[224:227], v[78:81]
	v_mfma_f32_16x16x32_bf16 v[70:73], v[170:173], v[232:235], v[70:73]
	v_mfma_f32_16x16x32_bf16 v[66:69], v[182:185], v[232:235], v[66:69]
	s_setprio 0
	s_barrier
	s_add_i32 s39, s39, s12
	v_lshl_add_u64 v[206:207], s[0:1], 0, v[0:1]
	s_mov_b32 m0, s39
	ds_read_b128 v[186:189], v181 offset:16384
	ds_read_b128 v[190:193], v181 offset:17408
	ds_read_b128 v[194:197], v181 offset:18432
	ds_read_b128 v[198:201], v181 offset:19456
	ds_read_b128 v[202:205], v181 offset:20480
	ds_read_b128 v[224:227], v181 offset:21504
	ds_read_b128 v[228:231], v181 offset:22528
	ds_read_b128 v[232:235], v181 offset:23552
	global_load_lds_dwordx4 v[206:207], off
	s_add_i32 m0, s39, 0x2000
	s_add_u32 s46, s0, 0x40000
	v_lshl_add_u64 v[236:237], s[0:1], 0, v[146:147]
	s_addc_u32 s47, s1, 0
	s_add_i32 s39, s45, s12
	global_load_lds_dwordx4 v[236:237], off
	v_lshl_add_u64 v[238:239], s[46:47], 0, v[0:1]
	s_mov_b32 m0, s39
	v_lshl_add_u64 v[240:241], s[6:7], 0, v[148:149]
	global_load_lds_dwordx4 v[238:239], off
	v_lshl_add_u64 v[238:239], s[46:47], 0, v[146:147]
	s_add_i32 m0, s39, 0x2000
	s_nop 0
	global_load_lds_dwordx4 v[238:239], off
	v_lshl_add_u64 v[238:239], s[6:7], 0, v[150:151]
	s_mov_b32 m0, s14
	s_nop 0
	global_load_lds_dwordx4 v[238:239], off
	s_mov_b32 m0, s15
	s_nop 0
	global_load_lds_dwordx4 v[240:241], off
	s_cmp_lg_u32 s35, -2
	s_cbranch_scc1 .Lpwt__778_1
	s_cmp_lt_u32 s21, 2
	s_cbranch_scc0 .Lpws__778_1

.Lpws__778_1:
	s_waitcnt lgkmcnt(0)
	s_barrier
	s_setprio 1
	s_waitcnt lgkmcnt(0)
	v_mfma_f32_16x16x32_bf16 v[62:65], v[130:133], v[186:189], 0
	v_mfma_f32_16x16x32_bf16 v[58:61], v[138:141], v[186:189], 0
	v_mfma_f32_16x16x32_bf16 v[50:53], v[130:133], v[194:197], 0
	v_mfma_f32_16x16x32_bf16 v[42:45], v[138:141], v[194:197], 0
	v_mfma_f32_16x16x32_bf16 v[34:37], v[130:133], v[202:205], 0
	v_mfma_f32_16x16x32_bf16 v[26:29], v[138:141], v[202:205], 0
	v_mfma_f32_16x16x32_bf16 v[18:21], v[130:133], v[228:231], 0
	v_mfma_f32_16x16x32_bf16 v[10:13], v[138:141], v[228:231], 0
	v_mfma_f32_16x16x32_bf16 v[62:65], v[134:137], v[190:193], v[62:65]
	v_mfma_f32_16x16x32_bf16 v[58:61], v[142:145], v[190:193], v[58:61]
	v_mfma_f32_16x16x32_bf16 v[50:53], v[134:137], v[198:201], v[50:53]
	v_mfma_f32_16x16x32_bf16 v[42:45], v[142:145], v[198:201], v[42:45]
	v_mfma_f32_16x16x32_bf16 v[34:37], v[134:137], v[224:227], v[34:37]
	v_mfma_f32_16x16x32_bf16 v[26:29], v[142:145], v[224:227], v[26:29]
	v_mfma_f32_16x16x32_bf16 v[18:21], v[134:137], v[232:235], v[18:21]
	v_mfma_f32_16x16x32_bf16 v[10:13], v[142:145], v[232:235], v[10:13]
	v_mfma_f32_16x16x32_bf16 v[54:57], v[156:159], v[186:189], 0
	v_mfma_f32_16x16x32_bf16 v[46:49], v[174:177], v[186:189], 0
	v_mfma_f32_16x16x32_bf16 v[38:41], v[156:159], v[194:197], 0
	v_mfma_f32_16x16x32_bf16 v[30:33], v[174:177], v[194:197], 0
	v_mfma_f32_16x16x32_bf16 v[22:25], v[156:159], v[202:205], 0
	v_mfma_f32_16x16x32_bf16 v[14:17], v[174:177], v[202:205], 0
	v_mfma_f32_16x16x32_bf16 v[6:9], v[156:159], v[228:231], 0
	v_mfma_f32_16x16x32_bf16 v[2:5], v[174:177], v[228:231], 0
	v_mfma_f32_16x16x32_bf16 v[54:57], v[170:173], v[190:193], v[54:57]
	v_mfma_f32_16x16x32_bf16 v[46:49], v[182:185], v[190:193], v[46:49]
	v_mfma_f32_16x16x32_bf16 v[38:41], v[170:173], v[198:201], v[38:41]
	v_mfma_f32_16x16x32_bf16 v[30:33], v[182:185], v[198:201], v[30:33]
	v_mfma_f32_16x16x32_bf16 v[22:25], v[170:173], v[224:227], v[22:25]
	v_mfma_f32_16x16x32_bf16 v[14:17], v[182:185], v[224:227], v[14:17]
	v_mfma_f32_16x16x32_bf16 v[6:9], v[170:173], v[232:235], v[6:9]
	v_mfma_f32_16x16x32_bf16 v[2:5], v[182:185], v[232:235], v[2:5]
	s_setprio 0
	s_barrier
	s_add_i32 s39, 0, 0x18000
	s_add_i32 s45, 0, 0x1c000
	v_add_u32_e32 v142, s39, v179
	v_add_u32_e32 v182, s45, v179
	ds_read_b128 v[130:133], v142
	ds_read_b128 v[134:137], v142 offset:1024
	ds_read_b128 v[138:141], v142 offset:2048
	ds_read_b128 v[142:145], v142 offset:3072
	ds_read_b128 v[156:159], v182
	ds_read_b128 v[170:173], v182 offset:1024
	ds_read_b128 v[174:177], v182 offset:2048
	ds_read_b128 v[182:185], v182 offset:3072
	s_add_u32 s6, s6, 0x40000
	s_addc_u32 s7, s7, 0
	s_mov_b32 m0, s16
	v_lshl_add_u64 v[242:243], s[6:7], 0, v[150:151]
	ds_read_b128 v[186:189], v181 offset:32768
	ds_read_b128 v[190:193], v181 offset:33792
	ds_read_b128 v[194:197], v181 offset:34816
	ds_read_b128 v[198:201], v181 offset:35840
	ds_read_b128 v[202:205], v181 offset:36864
	ds_read_b128 v[224:227], v181 offset:37888
	ds_read_b128 v[228:231], v181 offset:38912
	ds_read_b128 v[232:235], v181 offset:39936
	global_load_lds_dwordx4 v[242:243], off
	v_lshl_add_u64 v[242:243], s[6:7], 0, v[148:149]
	s_mov_b32 m0, s17
	s_nop 0
	global_load_lds_dwordx4 v[242:243], off
	s_waitcnt vmcnt(8)
	s_waitcnt lgkmcnt(0)
	s_barrier
	s_setprio 1
	s_waitcnt lgkmcnt(0)
	v_mfma_f32_16x16x32_bf16 v[126:129], v[130:133], v[186:189], v[126:129]
	v_mfma_f32_16x16x32_bf16 v[122:125], v[138:141], v[186:189], v[122:125]
	v_mfma_f32_16x16x32_bf16 v[114:117], v[130:133], v[194:197], v[114:117]
	v_mfma_f32_16x16x32_bf16 v[106:109], v[138:141], v[194:197], v[106:109]
	v_mfma_f32_16x16x32_bf16 v[98:101], v[130:133], v[202:205], v[98:101]
	v_mfma_f32_16x16x32_bf16 v[90:93], v[138:141], v[202:205], v[90:93]
	v_mfma_f32_16x16x32_bf16 v[82:85], v[130:133], v[228:231], v[82:85]
	v_mfma_f32_16x16x32_bf16 v[74:77], v[138:141], v[228:231], v[74:77]
	v_mfma_f32_16x16x32_bf16 v[126:129], v[134:137], v[190:193], v[126:129]
	v_mfma_f32_16x16x32_bf16 v[122:125], v[142:145], v[190:193], v[122:125]
	v_mfma_f32_16x16x32_bf16 v[114:117], v[134:137], v[198:201], v[114:117]
	v_mfma_f32_16x16x32_bf16 v[106:109], v[142:145], v[198:201], v[106:109]
	v_mfma_f32_16x16x32_bf16 v[98:101], v[134:137], v[224:227], v[98:101]
	v_mfma_f32_16x16x32_bf16 v[90:93], v[142:145], v[224:227], v[90:93]
	v_mfma_f32_16x16x32_bf16 v[82:85], v[134:137], v[232:235], v[82:85]
	v_mfma_f32_16x16x32_bf16 v[74:77], v[142:145], v[232:235], v[74:77]
	v_mfma_f32_16x16x32_bf16 v[118:121], v[156:159], v[186:189], v[118:121]
	v_mfma_f32_16x16x32_bf16 v[110:113], v[174:177], v[186:189], v[110:113]
	v_mfma_f32_16x16x32_bf16 v[102:105], v[156:159], v[194:197], v[102:105]
	v_mfma_f32_16x16x32_bf16 v[94:97], v[174:177], v[194:197], v[94:97]
	v_mfma_f32_16x16x32_bf16 v[86:89], v[156:159], v[202:205], v[86:89]
	v_mfma_f32_16x16x32_bf16 v[78:81], v[174:177], v[202:205], v[78:81]
	v_mfma_f32_16x16x32_bf16 v[70:73], v[156:159], v[228:231], v[70:73]
	v_mfma_f32_16x16x32_bf16 v[66:69], v[174:177], v[228:231], v[66:69]
	v_mfma_f32_16x16x32_bf16 v[118:121], v[170:173], v[190:193], v[118:121]
	v_mfma_f32_16x16x32_bf16 v[110:113], v[182:185], v[190:193], v[110:113]
	v_mfma_f32_16x16x32_bf16 v[102:105], v[170:173], v[198:201], v[102:105]
	v_mfma_f32_16x16x32_bf16 v[94:97], v[182:185], v[198:201], v[94:97]
	v_mfma_f32_16x16x32_bf16 v[86:89], v[170:173], v[224:227], v[86:89]
	v_mfma_f32_16x16x32_bf16 v[78:81], v[182:185], v[224:227], v[78:81]
	v_mfma_f32_16x16x32_bf16 v[70:73], v[170:173], v[232:235], v[70:73]
	v_mfma_f32_16x16x32_bf16 v[66:69], v[182:185], v[232:235], v[66:69]
	s_setprio 0
	s_barrier
	s_add_i32 s6, s39, s12
	v_lshl_add_u64 v[206:207], v[206:207], 0, s[56:57]
	s_mov_b32 m0, s6
	ds_read_b128 v[186:189], v181 offset:49152
	ds_read_b128 v[190:193], v181 offset:50176
	ds_read_b128 v[194:197], v181 offset:51200
	ds_read_b128 v[198:201], v181 offset:52224
	ds_read_b128 v[202:205], v181 offset:53248
	ds_read_b128 v[224:227], v181 offset:54272
	ds_read_b128 v[228:231], v181 offset:55296
	ds_read_b128 v[232:235], v181 offset:56320
	global_load_lds_dwordx4 v[206:207], off
	s_add_i32 m0, s6, 0x2000
	s_add_u32 s0, s0, 0x40080
	v_lshl_add_u64 v[206:207], v[236:237], 0, s[56:57]
	s_addc_u32 s1, s1, 0
	s_add_i32 s6, s45, s12
	global_load_lds_dwordx4 v[206:207], off
	v_lshl_add_u64 v[206:207], s[0:1], 0, v[0:1]
	s_mov_b32 m0, s6
	s_nop 0
	global_load_lds_dwordx4 v[206:207], off
	v_lshl_add_u64 v[206:207], s[0:1], 0, v[146:147]
	s_add_i32 m0, s6, 0x2000
	s_nop 0
	global_load_lds_dwordx4 v[206:207], off
	v_lshl_add_u64 v[206:207], v[238:239], 0, s[56:57]
	s_mov_b32 m0, s18
	s_nop 0
	global_load_lds_dwordx4 v[206:207], off
	v_lshl_add_u64 v[206:207], v[240:241], 0, s[56:57]
	s_mov_b32 m0, s19
	s_nop 0
	global_load_lds_dwordx4 v[206:207], off
	s_waitcnt vmcnt(8)
	s_waitcnt lgkmcnt(0)
	s_barrier
	s_setprio 1
	s_waitcnt lgkmcnt(0)
	v_mfma_f32_16x16x32_bf16 v[62:65], v[130:133], v[186:189], v[62:65]
	v_mfma_f32_16x16x32_bf16 v[58:61], v[138:141], v[186:189], v[58:61]
	v_mfma_f32_16x16x32_bf16 v[50:53], v[130:133], v[194:197], v[50:53]
	v_mfma_f32_16x16x32_bf16 v[42:45], v[138:141], v[194:197], v[42:45]
	v_mfma_f32_16x16x32_bf16 v[34:37], v[130:133], v[202:205], v[34:37]
	v_mfma_f32_16x16x32_bf16 v[26:29], v[138:141], v[202:205], v[26:29]
	v_mfma_f32_16x16x32_bf16 v[18:21], v[130:133], v[228:231], v[18:21]
	v_mfma_f32_16x16x32_bf16 v[10:13], v[138:141], v[228:231], v[10:13]
	v_mfma_f32_16x16x32_bf16 v[62:65], v[134:137], v[190:193], v[62:65]
	v_mfma_f32_16x16x32_bf16 v[58:61], v[142:145], v[190:193], v[58:61]
	v_mfma_f32_16x16x32_bf16 v[50:53], v[134:137], v[198:201], v[50:53]
	v_mfma_f32_16x16x32_bf16 v[42:45], v[142:145], v[198:201], v[42:45]
	v_mfma_f32_16x16x32_bf16 v[34:37], v[134:137], v[224:227], v[34:37]
	v_mfma_f32_16x16x32_bf16 v[26:29], v[142:145], v[224:227], v[26:29]
	v_mfma_f32_16x16x32_bf16 v[18:21], v[134:137], v[232:235], v[18:21]
	v_mfma_f32_16x16x32_bf16 v[10:13], v[142:145], v[232:235], v[10:13]
	v_mfma_f32_16x16x32_bf16 v[54:57], v[156:159], v[186:189], v[54:57]
	v_mfma_f32_16x16x32_bf16 v[46:49], v[174:177], v[186:189], v[46:49]
	v_mfma_f32_16x16x32_bf16 v[38:41], v[156:159], v[194:197], v[38:41]
	v_mfma_f32_16x16x32_bf16 v[30:33], v[174:177], v[194:197], v[30:33]
	v_mfma_f32_16x16x32_bf16 v[22:25], v[156:159], v[202:205], v[22:25]
	v_mfma_f32_16x16x32_bf16 v[14:17], v[174:177], v[202:205], v[14:17]
	v_mfma_f32_16x16x32_bf16 v[6:9], v[156:159], v[228:231], v[6:9]
	v_mfma_f32_16x16x32_bf16 v[2:5], v[174:177], v[228:231], v[2:5]
	v_mfma_f32_16x16x32_bf16 v[54:57], v[170:173], v[190:193], v[54:57]
	v_mfma_f32_16x16x32_bf16 v[46:49], v[182:185], v[190:193], v[46:49]
	v_mfma_f32_16x16x32_bf16 v[38:41], v[170:173], v[198:201], v[38:41]
	v_mfma_f32_16x16x32_bf16 v[30:33], v[182:185], v[198:201], v[30:33]
	v_mfma_f32_16x16x32_bf16 v[22:25], v[170:173], v[224:227], v[22:25]
	v_mfma_f32_16x16x32_bf16 v[14:17], v[182:185], v[224:227], v[14:17]
	v_mfma_f32_16x16x32_bf16 v[6:9], v[170:173], v[232:235], v[6:9]
	v_mfma_f32_16x16x32_bf16 v[2:5], v[182:185], v[232:235], v[2:5]
	s_setprio 0
	s_barrier
	s_add_i32 s35, s35, 2
	s_add_u32 s42, s42, 0x100
	s_addc_u32 s43, s43, 0
	s_add_u32 s29, s29, 0x100
	s_addc_u32 s34, s34, 0
	s_cmp_gt_u32 s35, 13

.Lws__778_0:
	s_waitcnt lgkmcnt(0)
	s_barrier
	s_setprio 1
	s_waitcnt lgkmcnt(0)
	v_mfma_f32_16x16x32_bf16 v[126:129], v[130:133], v[186:189], v[126:129]
	v_mfma_f32_16x16x32_bf16 v[122:125], v[138:141], v[186:189], v[122:125]
	v_mfma_f32_16x16x32_bf16 v[114:117], v[130:133], v[194:197], v[114:117]
	v_mfma_f32_16x16x32_bf16 v[106:109], v[138:141], v[194:197], v[106:109]
	v_mfma_f32_16x16x32_bf16 v[98:101], v[130:133], v[202:205], v[98:101]
	v_mfma_f32_16x16x32_bf16 v[90:93], v[138:141], v[202:205], v[90:93]
	v_mfma_f32_16x16x32_bf16 v[82:85], v[130:133], v[228:231], v[82:85]
	v_mfma_f32_16x16x32_bf16 v[74:77], v[138:141], v[228:231], v[74:77]
	v_mfma_f32_16x16x32_bf16 v[126:129], v[134:137], v[190:193], v[126:129]
	v_mfma_f32_16x16x32_bf16 v[122:125], v[142:145], v[190:193], v[122:125]
	v_mfma_f32_16x16x32_bf16 v[114:117], v[134:137], v[198:201], v[114:117]
	v_mfma_f32_16x16x32_bf16 v[106:109], v[142:145], v[198:201], v[106:109]
	v_mfma_f32_16x16x32_bf16 v[98:101], v[134:137], v[224:227], v[98:101]
	v_mfma_f32_16x16x32_bf16 v[90:93], v[142:145], v[224:227], v[90:93]
	v_mfma_f32_16x16x32_bf16 v[82:85], v[134:137], v[232:235], v[82:85]
	v_mfma_f32_16x16x32_bf16 v[74:77], v[142:145], v[232:235], v[74:77]
	v_mfma_f32_16x16x32_bf16 v[118:121], v[156:159], v[186:189], v[118:121]
	v_mfma_f32_16x16x32_bf16 v[110:113], v[174:177], v[186:189], v[110:113]
	v_mfma_f32_16x16x32_bf16 v[102:105], v[156:159], v[194:197], v[102:105]
	v_mfma_f32_16x16x32_bf16 v[94:97], v[174:177], v[194:197], v[94:97]
	v_mfma_f32_16x16x32_bf16 v[86:89], v[156:159], v[202:205], v[86:89]
	v_mfma_f32_16x16x32_bf16 v[78:81], v[174:177], v[202:205], v[78:81]
	v_mfma_f32_16x16x32_bf16 v[70:73], v[156:159], v[228:231], v[70:73]
	v_mfma_f32_16x16x32_bf16 v[66:69], v[174:177], v[228:231], v[66:69]
	v_mfma_f32_16x16x32_bf16 v[118:121], v[170:173], v[190:193], v[118:121]
	v_mfma_f32_16x16x32_bf16 v[110:113], v[182:185], v[190:193], v[110:113]
	v_mfma_f32_16x16x32_bf16 v[102:105], v[170:173], v[198:201], v[102:105]
	v_mfma_f32_16x16x32_bf16 v[94:97], v[182:185], v[198:201], v[94:97]
	v_mfma_f32_16x16x32_bf16 v[86:89], v[170:173], v[224:227], v[86:89]
	v_mfma_f32_16x16x32_bf16 v[78:81], v[182:185], v[224:227], v[78:81]
	v_mfma_f32_16x16x32_bf16 v[70:73], v[170:173], v[232:235], v[70:73]
	v_mfma_f32_16x16x32_bf16 v[66:69], v[182:185], v[232:235], v[66:69]
	s_setprio 0
	s_barrier
	s_add_i32 s39, s39, s12
	v_lshl_add_u64 v[206:207], s[0:1], 0, v[0:1]
	s_mov_b32 m0, s39
	ds_read_b128 v[186:189], v181 offset:16384
	ds_read_b128 v[190:193], v181 offset:17408
	ds_read_b128 v[194:197], v181 offset:18432
	ds_read_b128 v[198:201], v181 offset:19456
	ds_read_b128 v[202:205], v181 offset:20480
	ds_read_b128 v[224:227], v181 offset:21504
	ds_read_b128 v[228:231], v181 offset:22528
	ds_read_b128 v[232:235], v181 offset:23552
	global_load_lds_dwordx4 v[206:207], off
	s_add_i32 m0, s39, 0x2000
	s_add_u32 s46, s0, 0x40000
	v_lshl_add_u64 v[236:237], s[0:1], 0, v[146:147]
	s_addc_u32 s47, s1, 0
	s_add_i32 s39, s45, s12
	global_load_lds_dwordx4 v[236:237], off
	v_lshl_add_u64 v[238:239], s[46:47], 0, v[0:1]
	s_mov_b32 m0, s39
	v_lshl_add_u64 v[240:241], s[6:7], 0, v[148:149]
	global_load_lds_dwordx4 v[238:239], off
	v_lshl_add_u64 v[238:239], s[46:47], 0, v[146:147]
	s_add_i32 m0, s39, 0x2000
	s_nop 0
	global_load_lds_dwordx4 v[238:239], off
	v_lshl_add_u64 v[238:239], s[6:7], 0, v[150:151]
	s_mov_b32 m0, s14
	s_nop 0
	global_load_lds_dwordx4 v[238:239], off
	s_mov_b32 m0, s15
	s_nop 0
	global_load_lds_dwordx4 v[240:241], off
	s_cmp_lg_u32 s35, -2
	s_cbranch_scc1 .Lwt__778_1
	s_cmp_lt_u32 s21, 2
	s_cbranch_scc0 .Lws__778_1

.Lws__778_1:
	s_waitcnt lgkmcnt(0)
	s_barrier
	s_setprio 1
	s_waitcnt lgkmcnt(0)
	v_mfma_f32_16x16x32_bf16 v[62:65], v[130:133], v[186:189], v[62:65]
	v_mfma_f32_16x16x32_bf16 v[58:61], v[138:141], v[186:189], v[58:61]
	v_mfma_f32_16x16x32_bf16 v[50:53], v[130:133], v[194:197], v[50:53]
	v_mfma_f32_16x16x32_bf16 v[42:45], v[138:141], v[194:197], v[42:45]
	v_mfma_f32_16x16x32_bf16 v[34:37], v[130:133], v[202:205], v[34:37]
	v_mfma_f32_16x16x32_bf16 v[26:29], v[138:141], v[202:205], v[26:29]
	v_mfma_f32_16x16x32_bf16 v[18:21], v[130:133], v[228:231], v[18:21]
	v_mfma_f32_16x16x32_bf16 v[10:13], v[138:141], v[228:231], v[10:13]
	v_mfma_f32_16x16x32_bf16 v[62:65], v[134:137], v[190:193], v[62:65]
	v_mfma_f32_16x16x32_bf16 v[58:61], v[142:145], v[190:193], v[58:61]
	v_mfma_f32_16x16x32_bf16 v[50:53], v[134:137], v[198:201], v[50:53]
	v_mfma_f32_16x16x32_bf16 v[42:45], v[142:145], v[198:201], v[42:45]
	v_mfma_f32_16x16x32_bf16 v[34:37], v[134:137], v[224:227], v[34:37]
	v_mfma_f32_16x16x32_bf16 v[26:29], v[142:145], v[224:227], v[26:29]
	v_mfma_f32_16x16x32_bf16 v[18:21], v[134:137], v[232:235], v[18:21]
	v_mfma_f32_16x16x32_bf16 v[10:13], v[142:145], v[232:235], v[10:13]
	v_mfma_f32_16x16x32_bf16 v[54:57], v[156:159], v[186:189], v[54:57]
	v_mfma_f32_16x16x32_bf16 v[46:49], v[174:177], v[186:189], v[46:49]
	v_mfma_f32_16x16x32_bf16 v[38:41], v[156:159], v[194:197], v[38:41]
	v_mfma_f32_16x16x32_bf16 v[30:33], v[174:177], v[194:197], v[30:33]
	v_mfma_f32_16x16x32_bf16 v[22:25], v[156:159], v[202:205], v[22:25]
	v_mfma_f32_16x16x32_bf16 v[14:17], v[174:177], v[202:205], v[14:17]
	v_mfma_f32_16x16x32_bf16 v[6:9], v[156:159], v[228:231], v[6:9]
	v_mfma_f32_16x16x32_bf16 v[2:5], v[174:177], v[228:231], v[2:5]
	v_mfma_f32_16x16x32_bf16 v[54:57], v[170:173], v[190:193], v[54:57]
	v_mfma_f32_16x16x32_bf16 v[46:49], v[182:185], v[190:193], v[46:49]
	v_mfma_f32_16x16x32_bf16 v[38:41], v[170:173], v[198:201], v[38:41]
	v_mfma_f32_16x16x32_bf16 v[30:33], v[182:185], v[198:201], v[30:33]
	v_mfma_f32_16x16x32_bf16 v[22:25], v[170:173], v[224:227], v[22:25]
	v_mfma_f32_16x16x32_bf16 v[14:17], v[182:185], v[224:227], v[14:17]
	v_mfma_f32_16x16x32_bf16 v[6:9], v[170:173], v[232:235], v[6:9]
	v_mfma_f32_16x16x32_bf16 v[2:5], v[182:185], v[232:235], v[2:5]
	s_setprio 0
	s_barrier
	s_add_i32 s39, 0, 0x18000
	s_add_i32 s45, 0, 0x1c000
	v_add_u32_e32 v142, s39, v179
	v_add_u32_e32 v182, s45, v179
	ds_read_b128 v[130:133], v142
	ds_read_b128 v[134:137], v142 offset:1024
	ds_read_b128 v[138:141], v142 offset:2048
	ds_read_b128 v[142:145], v142 offset:3072
	ds_read_b128 v[156:159], v182
	ds_read_b128 v[170:173], v182 offset:1024
	ds_read_b128 v[174:177], v182 offset:2048
	ds_read_b128 v[182:185], v182 offset:3072
	s_add_u32 s6, s6, 0x40000
	s_addc_u32 s7, s7, 0
	s_mov_b32 m0, s16
	v_lshl_add_u64 v[242:243], s[6:7], 0, v[150:151]
	ds_read_b128 v[186:189], v181 offset:32768
	ds_read_b128 v[190:193], v181 offset:33792
	ds_read_b128 v[194:197], v181 offset:34816
	ds_read_b128 v[198:201], v181 offset:35840
	ds_read_b128 v[202:205], v181 offset:36864
	ds_read_b128 v[224:227], v181 offset:37888
	ds_read_b128 v[228:231], v181 offset:38912
	ds_read_b128 v[232:235], v181 offset:39936
	global_load_lds_dwordx4 v[242:243], off
	v_lshl_add_u64 v[242:243], s[6:7], 0, v[148:149]
	s_mov_b32 m0, s17
	s_nop 0
	global_load_lds_dwordx4 v[242:243], off
	s_waitcnt vmcnt(8)
	s_waitcnt lgkmcnt(0)
	s_barrier
	s_setprio 1
	s_waitcnt lgkmcnt(0)
	v_mfma_f32_16x16x32_bf16 v[126:129], v[130:133], v[186:189], v[126:129]
	v_mfma_f32_16x16x32_bf16 v[122:125], v[138:141], v[186:189], v[122:125]
	v_mfma_f32_16x16x32_bf16 v[114:117], v[130:133], v[194:197], v[114:117]
	v_mfma_f32_16x16x32_bf16 v[106:109], v[138:141], v[194:197], v[106:109]
	v_mfma_f32_16x16x32_bf16 v[98:101], v[130:133], v[202:205], v[98:101]
	v_mfma_f32_16x16x32_bf16 v[90:93], v[138:141], v[202:205], v[90:93]
	v_mfma_f32_16x16x32_bf16 v[82:85], v[130:133], v[228:231], v[82:85]
	v_mfma_f32_16x16x32_bf16 v[74:77], v[138:141], v[228:231], v[74:77]
	v_mfma_f32_16x16x32_bf16 v[126:129], v[134:137], v[190:193], v[126:129]
	v_mfma_f32_16x16x32_bf16 v[122:125], v[142:145], v[190:193], v[122:125]
	v_mfma_f32_16x16x32_bf16 v[114:117], v[134:137], v[198:201], v[114:117]
	v_mfma_f32_16x16x32_bf16 v[106:109], v[142:145], v[198:201], v[106:109]
	v_mfma_f32_16x16x32_bf16 v[98:101], v[134:137], v[224:227], v[98:101]
	v_mfma_f32_16x16x32_bf16 v[90:93], v[142:145], v[224:227], v[90:93]
	v_mfma_f32_16x16x32_bf16 v[82:85], v[134:137], v[232:235], v[82:85]
	v_mfma_f32_16x16x32_bf16 v[74:77], v[142:145], v[232:235], v[74:77]
	v_mfma_f32_16x16x32_bf16 v[118:121], v[156:159], v[186:189], v[118:121]
	v_mfma_f32_16x16x32_bf16 v[110:113], v[174:177], v[186:189], v[110:113]
	v_mfma_f32_16x16x32_bf16 v[102:105], v[156:159], v[194:197], v[102:105]
	v_mfma_f32_16x16x32_bf16 v[94:97], v[174:177], v[194:197], v[94:97]
	v_mfma_f32_16x16x32_bf16 v[86:89], v[156:159], v[202:205], v[86:89]
	v_mfma_f32_16x16x32_bf16 v[78:81], v[174:177], v[202:205], v[78:81]
	v_mfma_f32_16x16x32_bf16 v[70:73], v[156:159], v[228:231], v[70:73]
	v_mfma_f32_16x16x32_bf16 v[66:69], v[174:177], v[228:231], v[66:69]
	v_mfma_f32_16x16x32_bf16 v[118:121], v[170:173], v[190:193], v[118:121]
	v_mfma_f32_16x16x32_bf16 v[110:113], v[182:185], v[190:193], v[110:113]
	v_mfma_f32_16x16x32_bf16 v[102:105], v[170:173], v[198:201], v[102:105]
	v_mfma_f32_16x16x32_bf16 v[94:97], v[182:185], v[198:201], v[94:97]
	v_mfma_f32_16x16x32_bf16 v[86:89], v[170:173], v[224:227], v[86:89]
	v_mfma_f32_16x16x32_bf16 v[78:81], v[182:185], v[224:227], v[78:81]
	v_mfma_f32_16x16x32_bf16 v[70:73], v[170:173], v[232:235], v[70:73]
	v_mfma_f32_16x16x32_bf16 v[66:69], v[182:185], v[232:235], v[66:69]
	s_setprio 0
	s_barrier
	s_add_i32 s6, s39, s12
	v_lshl_add_u64 v[206:207], v[206:207], 0, s[56:57]
	s_mov_b32 m0, s6
	ds_read_b128 v[186:189], v181 offset:49152
	ds_read_b128 v[190:193], v181 offset:50176
	ds_read_b128 v[194:197], v181 offset:51200
	ds_read_b128 v[198:201], v181 offset:52224
	ds_read_b128 v[202:205], v181 offset:53248
	ds_read_b128 v[224:227], v181 offset:54272
	ds_read_b128 v[228:231], v181 offset:55296
	ds_read_b128 v[232:235], v181 offset:56320
	global_load_lds_dwordx4 v[206:207], off
	s_add_i32 m0, s6, 0x2000
	s_add_u32 s0, s0, 0x40080
	v_lshl_add_u64 v[206:207], v[236:237], 0, s[56:57]
	s_addc_u32 s1, s1, 0
	s_add_i32 s6, s45, s12
	global_load_lds_dwordx4 v[206:207], off
	v_lshl_add_u64 v[206:207], s[0:1], 0, v[0:1]
	s_mov_b32 m0, s6
	s_nop 0
	global_load_lds_dwordx4 v[206:207], off
	v_lshl_add_u64 v[206:207], s[0:1], 0, v[146:147]
	s_add_i32 m0, s6, 0x2000
	s_nop 0
	global_load_lds_dwordx4 v[206:207], off
	v_lshl_add_u64 v[206:207], v[238:239], 0, s[56:57]
	s_mov_b32 m0, s18
	s_nop 0
	global_load_lds_dwordx4 v[206:207], off
	v_lshl_add_u64 v[206:207], v[240:241], 0, s[56:57]
	s_mov_b32 m0, s19
	s_nop 0
	global_load_lds_dwordx4 v[206:207], off
	s_waitcnt vmcnt(8)
	s_waitcnt lgkmcnt(0)
	s_barrier
	s_setprio 1
	s_waitcnt lgkmcnt(0)
	v_mfma_f32_16x16x32_bf16 v[62:65], v[130:133], v[186:189], v[62:65]
	v_mfma_f32_16x16x32_bf16 v[58:61], v[138:141], v[186:189], v[58:61]
	v_mfma_f32_16x16x32_bf16 v[50:53], v[130:133], v[194:197], v[50:53]
	v_mfma_f32_16x16x32_bf16 v[42:45], v[138:141], v[194:197], v[42:45]
	v_mfma_f32_16x16x32_bf16 v[34:37], v[130:133], v[202:205], v[34:37]
	v_mfma_f32_16x16x32_bf16 v[26:29], v[138:141], v[202:205], v[26:29]
	v_mfma_f32_16x16x32_bf16 v[18:21], v[130:133], v[228:231], v[18:21]
	v_mfma_f32_16x16x32_bf16 v[10:13], v[138:141], v[228:231], v[10:13]
	v_mfma_f32_16x16x32_bf16 v[62:65], v[134:137], v[190:193], v[62:65]
	v_mfma_f32_16x16x32_bf16 v[58:61], v[142:145], v[190:193], v[58:61]
	v_mfma_f32_16x16x32_bf16 v[50:53], v[134:137], v[198:201], v[50:53]
	v_mfma_f32_16x16x32_bf16 v[42:45], v[142:145], v[198:201], v[42:45]
	v_mfma_f32_16x16x32_bf16 v[34:37], v[134:137], v[224:227], v[34:37]
	v_mfma_f32_16x16x32_bf16 v[26:29], v[142:145], v[224:227], v[26:29]
	v_mfma_f32_16x16x32_bf16 v[18:21], v[134:137], v[232:235], v[18:21]
	v_mfma_f32_16x16x32_bf16 v[10:13], v[142:145], v[232:235], v[10:13]
	v_mfma_f32_16x16x32_bf16 v[54:57], v[156:159], v[186:189], v[54:57]
	v_mfma_f32_16x16x32_bf16 v[46:49], v[174:177], v[186:189], v[46:49]
	v_mfma_f32_16x16x32_bf16 v[38:41], v[156:159], v[194:197], v[38:41]
	v_mfma_f32_16x16x32_bf16 v[30:33], v[174:177], v[194:197], v[30:33]
	v_mfma_f32_16x16x32_bf16 v[22:25], v[156:159], v[202:205], v[22:25]
	v_mfma_f32_16x16x32_bf16 v[14:17], v[174:177], v[202:205], v[14:17]
	v_mfma_f32_16x16x32_bf16 v[6:9], v[156:159], v[228:231], v[6:9]
	v_mfma_f32_16x16x32_bf16 v[2:5], v[174:177], v[228:231], v[2:5]
	v_mfma_f32_16x16x32_bf16 v[54:57], v[170:173], v[190:193], v[54:57]
	v_mfma_f32_16x16x32_bf16 v[46:49], v[182:185], v[190:193], v[46:49]
	v_mfma_f32_16x16x32_bf16 v[38:41], v[170:173], v[198:201], v[38:41]
	v_mfma_f32_16x16x32_bf16 v[30:33], v[182:185], v[198:201], v[30:33]
	v_mfma_f32_16x16x32_bf16 v[22:25], v[170:173], v[224:227], v[22:25]
	v_mfma_f32_16x16x32_bf16 v[14:17], v[182:185], v[224:227], v[14:17]
	v_mfma_f32_16x16x32_bf16 v[6:9], v[170:173], v[232:235], v[6:9]
	v_mfma_f32_16x16x32_bf16 v[2:5], v[182:185], v[232:235], v[2:5]
	s_setprio 0
	s_barrier
	s_add_i32 s35, s35, 2
	s_add_u32 s42, s42, 0x100
	s_addc_u32 s43, s43, 0
	s_add_u32 s29, s29, 0x100
	s_addc_u32 s34, s34, 0
	s_cmp_gt_u32 s35, 13
	s_cbranch_scc0 .LBB0_778
	s_and_b64 vcc, exec, s[36:37]
	s_cbranch_vccz .LBB0_781
	s_barrier
